# code placement: each GEMM load segment's closing wait/barrier and the MFMA block that follows it aligned to a 64-byte boundary (padding placed before the waits), all nine K-loops; on top of v25
# baseline (speedup 1.0000x reference)
; #define PG8_STAGE(bufoff, gbase, voff) do { _Pragma("unroll") for (int _i = 0; _i < 2; ++_i) \
;         __builtin_amdgcn_global_load_lds((const unsigned*)((const char*)(gbase) + (voff)[_i]), (PG8_LAS unsigned*)(lds + (bufoff) + ldsw + _i * 8192), 16, 0, 0); } while (0)
; #define PG8_LDA(dst, b, h) do { _Pragma("unroll") for (int m = 0; m < 4; ++m) _Pragma("unroll") for (int k = 0; k < 2; ++k) dst[m][k] = *(const PG8_LAS bf16x8*)(lds + PG8_SA(b, h) + aoff + m * 2048 + k * 1024); } while (0)
; #define PG8_LDB(dst, b, h) do { _Pragma("unroll") for (int n = 0; n < 2; ++n) _Pragma("unroll") for (int k = 0; k < 2; ++k) dst[n][k] = *(const PG8_LAS bf16x8*)(lds + PG8_SB(b, h) + boff + n * 2048 + k * 1024); } while (0)
; #define PG8_MMA(ai, bj, At, Bt) do { __builtin_amdgcn_s_setprio(1); _Pragma("unroll") for (int m = 0; m < 4; ++m) _Pragma("unroll") for (int n = 0; n < 2; ++n) _Pragma("unroll") for (int k = 0; k < 2; ++k) \
;         acc[ai][bj][m][n] = __builtin_amdgcn_mfma_f32_16x16x32_bf16(Bt[n][k], At[m][k], acc[ai][bj][m][n], 0, 0, 0); __builtin_amdgcn_s_setprio(0); } while (0)
; #define PG8_WAIT_V(n) asm volatile("s_waitcnt vmcnt(" #n ")" ::: "memory")
; #define PG8_BAR __builtin_amdgcn_s_barrier()
; template <class Epi, class Sched, bool ALIGN_EPI = false, bool SP2 = false>
; __device__ __forceinline__ void gemm_phase(PG8_LAS unsigned char* lds, const Gemm g, const Sched& S, const Epi& E) {
;     ...
;         for (int t = 0; t < nt; t += 2) {
;             const bool last = (t == nt - 2);
;             const char* a1 = cA + (size_t)(t + 1) * kstep;
;             const char* a2 = last ? nA : cA + (size_t)(t + 2) * kstep; const char* b2 = last ? nB : cB + (size_t)(t + 2) * kstep;
;             const char* a3 = a2 + kstep; const char* b3 = b2 + kstep;
;             if (last && has_next) S.a_ready(nxt);
;             if constexpr (SP2) {
;             PG8_LDB(B0, 0, 0); PG8_LDB(B1, 0, 1); PG8_SCHED; PG8_LDA(At, 0, 0); PG8_STAGE(PG8_SA(1, 1), a1 + hstep, voffA);
;             PG8_WAIT_V(8); PG8_WAIT_L(0); PG8_BAR; PG8_MMA(0, 0, At, B0); PG8_MMA(0, 1, At, B1); PG8_BAR; PG8_SCHED;
;             PG8_LDA(At, 0, 1); PG8_STAGE(PG8_SB(0, 0), b2, voffB); PG8_STAGE(PG8_SB(0, 1), b2 + hstep, voffB); PG8_STAGE(PG8_SA(0, 0), a2, voffA);
;             PG8_WAIT_V(8); PG8_WAIT_L(0); PG8_BAR; PG8_MMA(1, 0, At, B0); PG8_MMA(1, 1, At, B1); PG8_BAR; PG8_SCHED;
.LBB0_66:
	s_add_u32 s61, s90, 0xfffc0080
	s_addc_u32 s72, s91, -1
	s_add_i32 s73, 0, 0x10000
	s_cmp_eq_u32 s80, 12
	s_cselect_b32 s95, s47, s72
	s_cselect_b32 s94, vcc_lo, s61
	v_add_u32_e32 v147, s73, v139
	s_cselect_b32 s93, s45, s7
	s_cselect_b32 s92, vcc_hi, s4
	s_add_i32 s61, 0, 0x14000
	ds_read_b128 v[170:173], v147
	ds_read_b128 v[174:177], v147 offset:1024
	ds_read_b128 v[178:181], v147 offset:2048
	ds_read_b128 v[182:185], v147 offset:3072
	v_add_u32_e32 v147, s61, v139
	ds_read_b128 v[196:199], v147
	ds_read_b128 v[200:203], v147 offset:1024
	ds_read_b128 v[204:207], v147 offset:2048
	ds_read_b128 v[208:211], v147 offset:3072
	v_lshl_add_u64 v[160:161], s[90:91], 0, v[150:151]
	s_add_i32 m0, s8, 0xc000
	ds_read_b128 v[212:215], v143
	ds_read_b128 v[216:219], v143 offset:1024
	ds_read_b128 v[220:223], v143 offset:2048
	ds_read_b128 v[224:227], v143 offset:3072
	ds_read_b128 v[228:231], v143 offset:4096
	ds_read_b128 v[232:235], v143 offset:5120
	ds_read_b128 v[236:239], v143 offset:6144
	ds_read_b128 v[240:243], v143 offset:7168
	global_load_lds_dwordx4 v[160:161], off
	v_lshl_add_u64 v[160:161], s[90:91], 0, v[148:149]
	s_add_i32 m0, s8, 0xe000
	s_nop 0
	global_load_lds_dwordx4 v[160:161], off
	.p2align	6
	s_waitcnt vmcnt(8)
	s_waitcnt lgkmcnt(0)
	s_barrier
	v_mfma_f32_16x16x32_bf16 v[126:129], v[170:173], v[212:215], v[126:129]
	v_mfma_f32_16x16x32_bf16 v[122:125], v[178:181], v[212:215], v[122:125]
	v_mfma_f32_16x16x32_bf16 v[110:113], v[170:173], v[220:223], v[110:113]
	v_mfma_f32_16x16x32_bf16 v[106:109], v[178:181], v[220:223], v[106:109]
	v_mfma_f32_16x16x32_bf16 v[94:97], v[170:173], v[228:231], v[94:97]
	v_mfma_f32_16x16x32_bf16 v[90:93], v[178:181], v[228:231], v[90:93]
	v_mfma_f32_16x16x32_bf16 v[78:81], v[170:173], v[236:239], v[78:81]
	v_mfma_f32_16x16x32_bf16 v[74:77], v[178:181], v[236:239], v[74:77]
	v_mfma_f32_16x16x32_bf16 v[126:129], v[174:177], v[216:219], v[126:129]
	v_mfma_f32_16x16x32_bf16 v[122:125], v[182:185], v[216:219], v[122:125]
	v_mfma_f32_16x16x32_bf16 v[110:113], v[174:177], v[224:227], v[110:113]
	v_mfma_f32_16x16x32_bf16 v[106:109], v[182:185], v[224:227], v[106:109]
	v_mfma_f32_16x16x32_bf16 v[94:97], v[174:177], v[232:235], v[94:97]
	v_mfma_f32_16x16x32_bf16 v[90:93], v[182:185], v[232:235], v[90:93]
	v_mfma_f32_16x16x32_bf16 v[78:81], v[174:177], v[240:243], v[78:81]
	v_mfma_f32_16x16x32_bf16 v[74:77], v[182:185], v[240:243], v[74:77]
	v_mfma_f32_16x16x32_bf16 v[118:121], v[196:199], v[212:215], v[118:121]
	v_mfma_f32_16x16x32_bf16 v[114:117], v[204:207], v[212:215], v[114:117]
	v_mfma_f32_16x16x32_bf16 v[102:105], v[196:199], v[220:223], v[102:105]
	v_mfma_f32_16x16x32_bf16 v[98:101], v[204:207], v[220:223], v[98:101]
	v_mfma_f32_16x16x32_bf16 v[86:89], v[196:199], v[228:231], v[86:89]
	v_mfma_f32_16x16x32_bf16 v[82:85], v[204:207], v[228:231], v[82:85]
	v_mfma_f32_16x16x32_bf16 v[70:73], v[196:199], v[236:239], v[70:73]
	v_mfma_f32_16x16x32_bf16 v[66:69], v[204:207], v[236:239], v[66:69]
	v_mfma_f32_16x16x32_bf16 v[118:121], v[200:203], v[216:219], v[118:121]
	v_mfma_f32_16x16x32_bf16 v[114:117], v[208:211], v[216:219], v[114:117]
	v_mfma_f32_16x16x32_bf16 v[102:105], v[200:203], v[224:227], v[102:105]
	v_mfma_f32_16x16x32_bf16 v[98:101], v[208:211], v[224:227], v[98:101]
	v_mfma_f32_16x16x32_bf16 v[86:89], v[200:203], v[232:235], v[86:89]
	v_mfma_f32_16x16x32_bf16 v[82:85], v[208:211], v[232:235], v[82:85]
	v_mfma_f32_16x16x32_bf16 v[70:73], v[200:203], v[240:243], v[70:73]
	v_mfma_f32_16x16x32_bf16 v[66:69], v[208:211], v[240:243], v[66:69]
	s_barrier
	s_add_i32 s72, s73, s5
	v_lshl_add_u64 v[160:161], s[92:93], 0, v[132:133]
	s_mov_b32 m0, s72
	ds_read_b128 v[212:215], v143 offset:16384
	ds_read_b128 v[216:219], v143 offset:17408
	ds_read_b128 v[220:223], v143 offset:18432
	ds_read_b128 v[224:227], v143 offset:19456
	ds_read_b128 v[228:231], v143 offset:20480
	ds_read_b128 v[232:235], v143 offset:21504
	ds_read_b128 v[236:239], v143 offset:22528
	ds_read_b128 v[240:243], v143 offset:23552
	global_load_lds_dwordx4 v[160:161], off
	s_add_i32 m0, s72, 0x2000
	s_add_u32 s76, s92, 0x40000
	v_lshl_add_u64 v[244:245], s[92:93], 0, v[136:137]
	s_addc_u32 s77, s93, 0
	s_add_i32 s61, s61, s5
	global_load_lds_dwordx4 v[244:245], off
	v_lshl_add_u64 v[246:247], s[76:77], 0, v[132:133]
	s_mov_b32 m0, s61
	v_lshl_add_u64 v[248:249], s[94:95], 0, v[134:135]
	global_load_lds_dwordx4 v[246:247], off
	v_lshl_add_u64 v[246:247], s[76:77], 0, v[136:137]
	s_add_i32 m0, s61, 0x2000
	s_nop 0
	global_load_lds_dwordx4 v[246:247], off
	v_lshl_add_u64 v[246:247], s[94:95], 0, v[130:131]
	s_mov_b32 m0, s8
	s_nop 0
	global_load_lds_dwordx4 v[246:247], off
	s_mov_b32 m0, s9
	s_nop 0
	global_load_lds_dwordx4 v[248:249], off
	.p2align	6
	s_waitcnt vmcnt(8)
	s_waitcnt lgkmcnt(0)
	s_barrier
; #define PG8_STAGE(bufoff, gbase, voff) do { _Pragma("unroll") for (int _i = 0; _i < 2; ++_i) \
;         __builtin_amdgcn_global_load_lds((const unsigned*)((const char*)(gbase) + (voff)[_i]), (PG8_LAS unsigned*)(lds + (bufoff) + ldsw + _i * 8192), 16, 0, 0); } while (0)
; #define PG8_LDA(dst, b, h) do { _Pragma("unroll") for (int m = 0; m < 4; ++m) _Pragma("unroll") for (int k = 0; k < 2; ++k) dst[m][k] = *(const PG8_LAS bf16x8*)(lds + PG8_SA(b, h) + aoff + m * 2048 + k * 1024); } while (0)
; #define PG8_LDB(dst, b, h) do { _Pragma("unroll") for (int n = 0; n < 2; ++n) _Pragma("unroll") for (int k = 0; k < 2; ++k) dst[n][k] = *(const PG8_LAS bf16x8*)(lds + PG8_SB(b, h) + boff + n * 2048 + k * 1024); } while (0)
; #define PG8_MMA(ai, bj, At, Bt) do { __builtin_amdgcn_s_setprio(1); _Pragma("unroll") for (int m = 0; m < 4; ++m) _Pragma("unroll") for (int n = 0; n < 2; ++n) _Pragma("unroll") for (int k = 0; k < 2; ++k) \
;         acc[ai][bj][m][n] = __builtin_amdgcn_mfma_f32_16x16x32_bf16(Bt[n][k], At[m][k], acc[ai][bj][m][n], 0, 0, 0); __builtin_amdgcn_s_setprio(0); } while (0)
; #define PG8_WAIT_V(n) asm volatile("s_waitcnt vmcnt(" #n ")" ::: "memory")
; #define PG8_WAIT_L(n) asm volatile("s_waitcnt lgkmcnt(" #n ")" ::: "memory")
; #define PG8_BAR __builtin_amdgcn_s_barrier()
; #define PG8_SCHED __builtin_amdgcn_sched_barrier(0)
; template <class Epi, class Sched, bool ALIGN_EPI = false, bool SP2 = false>
; __device__ __forceinline__ void gemm_phase(PG8_LAS unsigned char* lds, const Gemm g, const Sched& S, const Epi& E) {
;     ...
;             PG8_WAIT_V(8); PG8_WAIT_L(0); PG8_BAR; PG8_MMA(1, 0, At, B0); PG8_MMA(1, 1, At, B1); PG8_BAR; PG8_SCHED;
;             PG8_LDB(B0, 1, 0); PG8_LDB(B1, 1, 1); PG8_SCHED; PG8_LDA(At, 1, 0); PG8_STAGE(PG8_SA(0, 1), a2 + hstep, voffA);
;             PG8_WAIT_V(8); PG8_WAIT_L(0); PG8_BAR; PG8_MMA(0, 0, At, B0); PG8_MMA(0, 1, At, B1); PG8_BAR; PG8_SCHED;
	v_mfma_f32_16x16x32_bf16 v[62:65], v[170:173], v[212:215], v[62:65]
	v_mfma_f32_16x16x32_bf16 v[58:61], v[178:181], v[212:215], v[58:61]
	v_mfma_f32_16x16x32_bf16 v[50:53], v[170:173], v[220:223], v[50:53]
	v_mfma_f32_16x16x32_bf16 v[42:45], v[178:181], v[220:223], v[42:45]
	v_mfma_f32_16x16x32_bf16 v[34:37], v[170:173], v[228:231], v[34:37]
	v_mfma_f32_16x16x32_bf16 v[24:27], v[178:181], v[228:231], v[24:27]
	v_mfma_f32_16x16x32_bf16 v[16:19], v[170:173], v[236:239], v[16:19]
	v_mfma_f32_16x16x32_bf16 v[8:11], v[178:181], v[236:239], v[8:11]
	v_mfma_f32_16x16x32_bf16 v[62:65], v[174:177], v[216:219], v[62:65]
	v_mfma_f32_16x16x32_bf16 v[58:61], v[182:185], v[216:219], v[58:61]
	v_mfma_f32_16x16x32_bf16 v[50:53], v[174:177], v[224:227], v[50:53]
	v_mfma_f32_16x16x32_bf16 v[42:45], v[182:185], v[224:227], v[42:45]
	v_mfma_f32_16x16x32_bf16 v[34:37], v[174:177], v[232:235], v[34:37]
	v_mfma_f32_16x16x32_bf16 v[24:27], v[182:185], v[232:235], v[24:27]
	v_mfma_f32_16x16x32_bf16 v[16:19], v[174:177], v[240:243], v[16:19]
	v_mfma_f32_16x16x32_bf16 v[8:11], v[182:185], v[240:243], v[8:11]
	v_mfma_f32_16x16x32_bf16 v[54:57], v[196:199], v[212:215], v[54:57]
	v_mfma_f32_16x16x32_bf16 v[46:49], v[204:207], v[212:215], v[46:49]
	v_mfma_f32_16x16x32_bf16 v[38:41], v[196:199], v[220:223], v[38:41]
	v_mfma_f32_16x16x32_bf16 v[28:31], v[204:207], v[220:223], v[28:31]
	v_mfma_f32_16x16x32_bf16 v[20:23], v[196:199], v[228:231], v[20:23]
	v_mfma_f32_16x16x32_bf16 v[12:15], v[204:207], v[228:231], v[12:15]
	v_mfma_f32_16x16x32_bf16 v[4:7], v[196:199], v[236:239], v[4:7]
	v_mfma_f32_16x16x32_bf16 v[0:3], v[204:207], v[236:239], v[0:3]
	v_mfma_f32_16x16x32_bf16 v[54:57], v[200:203], v[216:219], v[54:57]
	v_mfma_f32_16x16x32_bf16 v[46:49], v[208:211], v[216:219], v[46:49]
	v_mfma_f32_16x16x32_bf16 v[38:41], v[200:203], v[224:227], v[38:41]
	v_mfma_f32_16x16x32_bf16 v[28:31], v[208:211], v[224:227], v[28:31]
	v_mfma_f32_16x16x32_bf16 v[20:23], v[200:203], v[232:235], v[20:23]
	v_mfma_f32_16x16x32_bf16 v[12:15], v[208:211], v[232:235], v[12:15]
	v_mfma_f32_16x16x32_bf16 v[4:7], v[200:203], v[240:243], v[4:7]
	v_mfma_f32_16x16x32_bf16 v[0:3], v[208:211], v[240:243], v[0:3]
	s_barrier
	s_add_i32 s61, 0, 0x18000
	v_add_u32_e32 v147, s61, v139
	s_add_i32 s72, 0, 0x1c000
	ds_read_b128 v[170:173], v147
	ds_read_b128 v[174:177], v147 offset:1024
	ds_read_b128 v[178:181], v147 offset:2048
	ds_read_b128 v[182:185], v147 offset:3072
	v_add_u32_e32 v147, s72, v139
	ds_read_b128 v[196:199], v147
	ds_read_b128 v[200:203], v147 offset:1024
	ds_read_b128 v[204:207], v147 offset:2048
	ds_read_b128 v[208:211], v147 offset:3072
	s_add_u32 s76, s94, 0x40000
	s_addc_u32 s77, s95, 0
	s_mov_b32 m0, s89
	v_lshl_add_u64 v[250:251], s[76:77], 0, v[130:131]
	ds_read_b128 v[212:215], v143 offset:32768
	ds_read_b128 v[216:219], v143 offset:33792
	ds_read_b128 v[220:223], v143 offset:34816
	ds_read_b128 v[224:227], v143 offset:35840
	ds_read_b128 v[228:231], v143 offset:36864
	ds_read_b128 v[232:235], v143 offset:37888
	ds_read_b128 v[236:239], v143 offset:38912
	ds_read_b128 v[240:243], v143 offset:39936
	global_load_lds_dwordx4 v[250:251], off
	v_lshl_add_u64 v[250:251], s[76:77], 0, v[134:135]
	s_mov_b32 m0, s96
	s_nop 0
	global_load_lds_dwordx4 v[250:251], off
	.p2align	6
	s_waitcnt vmcnt(8)
	s_waitcnt lgkmcnt(0)
	s_barrier
	v_mfma_f32_16x16x32_bf16 v[126:129], v[170:173], v[212:215], v[126:129]
	v_mfma_f32_16x16x32_bf16 v[122:125], v[178:181], v[212:215], v[122:125]
	v_mfma_f32_16x16x32_bf16 v[110:113], v[170:173], v[220:223], v[110:113]
	v_mfma_f32_16x16x32_bf16 v[106:109], v[178:181], v[220:223], v[106:109]
	v_mfma_f32_16x16x32_bf16 v[94:97], v[170:173], v[228:231], v[94:97]
	v_mfma_f32_16x16x32_bf16 v[90:93], v[178:181], v[228:231], v[90:93]
	v_mfma_f32_16x16x32_bf16 v[78:81], v[170:173], v[236:239], v[78:81]
	v_mfma_f32_16x16x32_bf16 v[74:77], v[178:181], v[236:239], v[74:77]
	v_mfma_f32_16x16x32_bf16 v[126:129], v[174:177], v[216:219], v[126:129]
	v_mfma_f32_16x16x32_bf16 v[122:125], v[182:185], v[216:219], v[122:125]
	v_mfma_f32_16x16x32_bf16 v[110:113], v[174:177], v[224:227], v[110:113]
	v_mfma_f32_16x16x32_bf16 v[106:109], v[182:185], v[224:227], v[106:109]
	v_mfma_f32_16x16x32_bf16 v[94:97], v[174:177], v[232:235], v[94:97]
	v_mfma_f32_16x16x32_bf16 v[90:93], v[182:185], v[232:235], v[90:93]
	v_mfma_f32_16x16x32_bf16 v[78:81], v[174:177], v[240:243], v[78:81]
	v_mfma_f32_16x16x32_bf16 v[74:77], v[182:185], v[240:243], v[74:77]
	v_mfma_f32_16x16x32_bf16 v[118:121], v[196:199], v[212:215], v[118:121]
	v_mfma_f32_16x16x32_bf16 v[114:117], v[204:207], v[212:215], v[114:117]
	v_mfma_f32_16x16x32_bf16 v[102:105], v[196:199], v[220:223], v[102:105]
	v_mfma_f32_16x16x32_bf16 v[98:101], v[204:207], v[220:223], v[98:101]
	v_mfma_f32_16x16x32_bf16 v[86:89], v[196:199], v[228:231], v[86:89]
	v_mfma_f32_16x16x32_bf16 v[82:85], v[204:207], v[228:231], v[82:85]
	v_mfma_f32_16x16x32_bf16 v[70:73], v[196:199], v[236:239], v[70:73]
	v_mfma_f32_16x16x32_bf16 v[66:69], v[204:207], v[236:239], v[66:69]
	v_mfma_f32_16x16x32_bf16 v[118:121], v[200:203], v[216:219], v[118:121]
	v_mfma_f32_16x16x32_bf16 v[114:117], v[208:211], v[216:219], v[114:117]
	v_mfma_f32_16x16x32_bf16 v[102:105], v[200:203], v[224:227], v[102:105]
	v_mfma_f32_16x16x32_bf16 v[98:101], v[208:211], v[224:227], v[98:101]
	v_mfma_f32_16x16x32_bf16 v[86:89], v[200:203], v[232:235], v[86:89]
	v_mfma_f32_16x16x32_bf16 v[82:85], v[208:211], v[232:235], v[82:85]
	v_mfma_f32_16x16x32_bf16 v[70:73], v[200:203], v[240:243], v[70:73]
	v_mfma_f32_16x16x32_bf16 v[66:69], v[208:211], v[240:243], v[66:69]
	s_barrier
; #define PG8_STAGE(bufoff, gbase, voff) do { _Pragma("unroll") for (int _i = 0; _i < 2; ++_i) \
;         __builtin_amdgcn_global_load_lds((const unsigned*)((const char*)(gbase) + (voff)[_i]), (PG8_LAS unsigned*)(lds + (bufoff) + ldsw + _i * 8192), 16, 0, 0); } while (0)
; #define PG8_LDA(dst, b, h) do { _Pragma("unroll") for (int m = 0; m < 4; ++m) _Pragma("unroll") for (int k = 0; k < 2; ++k) dst[m][k] = *(const PG8_LAS bf16x8*)(lds + PG8_SA(b, h) + aoff + m * 2048 + k * 1024); } while (0)
; #define PG8_MMA(ai, bj, At, Bt) do { __builtin_amdgcn_s_setprio(1); _Pragma("unroll") for (int m = 0; m < 4; ++m) _Pragma("unroll") for (int n = 0; n < 2; ++n) _Pragma("unroll") for (int k = 0; k < 2; ++k) \
;         acc[ai][bj][m][n] = __builtin_amdgcn_mfma_f32_16x16x32_bf16(Bt[n][k], At[m][k], acc[ai][bj][m][n], 0, 0, 0); __builtin_amdgcn_s_setprio(0); } while (0)
; #define PG8_WAIT_V(n) asm volatile("s_waitcnt vmcnt(" #n ")" ::: "memory")
; #define PG8_WAIT_L(n) asm volatile("s_waitcnt lgkmcnt(" #n ")" ::: "memory")
; #define PG8_BAR __builtin_amdgcn_s_barrier()
; #define PG8_SCHED __builtin_amdgcn_sched_barrier(0)
; template <class Epi, class Sched, bool ALIGN_EPI = false, bool SP2 = false>
; __device__ __forceinline__ void gemm_phase(PG8_LAS unsigned char* lds, const Gemm g, const Sched& S, const Epi& E) {
;     ...
;             PG8_WAIT_V(8); PG8_WAIT_L(0); PG8_BAR; PG8_MMA(0, 0, At, B0); PG8_MMA(0, 1, At, B1); PG8_BAR; PG8_SCHED;
;             PG8_LDA(At, 1, 1); PG8_STAGE(PG8_SB(1, 0), b3, voffB); PG8_STAGE(PG8_SB(1, 1), b3 + hstep, voffB); PG8_STAGE(PG8_SA(1, 0), a3, voffA);
;             PG8_WAIT_V(8); PG8_WAIT_L(0); PG8_BAR; PG8_MMA(1, 0, At, B0); PG8_MMA(1, 1, At, B1); PG8_BAR; PG8_SCHED;
	s_add_i32 s61, s61, s5
	v_lshl_add_u64 v[160:161], v[160:161], 0, s[34:35]
	s_mov_b32 m0, s61
	ds_read_b128 v[212:215], v143 offset:49152
	ds_read_b128 v[216:219], v143 offset:50176
	ds_read_b128 v[220:223], v143 offset:51200
	ds_read_b128 v[224:227], v143 offset:52224
	ds_read_b128 v[228:231], v143 offset:53248
	ds_read_b128 v[232:235], v143 offset:54272
	ds_read_b128 v[236:239], v143 offset:55296
	ds_read_b128 v[240:243], v143 offset:56320
	global_load_lds_dwordx4 v[160:161], off
	s_add_i32 m0, s61, 0x2000
	s_add_u32 s76, s92, 0x40080
	v_lshl_add_u64 v[160:161], v[244:245], 0, s[34:35]
	s_addc_u32 s77, s93, 0
	s_add_i32 s61, s72, s5
	global_load_lds_dwordx4 v[160:161], off
	v_lshl_add_u64 v[160:161], s[76:77], 0, v[132:133]
	s_mov_b32 m0, s61
	s_nop 0
	global_load_lds_dwordx4 v[160:161], off
	v_lshl_add_u64 v[160:161], s[76:77], 0, v[136:137]
	s_add_i32 m0, s61, 0x2000
	s_nop 0
	global_load_lds_dwordx4 v[160:161], off
	v_lshl_add_u64 v[160:161], v[246:247], 0, s[34:35]
	s_mov_b32 m0, s0
	s_nop 0
	global_load_lds_dwordx4 v[160:161], off
	v_lshl_add_u64 v[160:161], v[248:249], 0, s[34:35]
	s_mov_b32 m0, s97
	s_nop 0
	global_load_lds_dwordx4 v[160:161], off
	.p2align	6
	s_waitcnt vmcnt(8)
	s_waitcnt lgkmcnt(0)
	s_barrier
	v_mfma_f32_16x16x32_bf16 v[62:65], v[170:173], v[212:215], v[62:65]
	v_mfma_f32_16x16x32_bf16 v[58:61], v[178:181], v[212:215], v[58:61]
	v_mfma_f32_16x16x32_bf16 v[50:53], v[170:173], v[220:223], v[50:53]
	v_mfma_f32_16x16x32_bf16 v[42:45], v[178:181], v[220:223], v[42:45]
	v_mfma_f32_16x16x32_bf16 v[34:37], v[170:173], v[228:231], v[34:37]
	v_mfma_f32_16x16x32_bf16 v[24:27], v[178:181], v[228:231], v[24:27]
	v_mfma_f32_16x16x32_bf16 v[16:19], v[170:173], v[236:239], v[16:19]
	v_mfma_f32_16x16x32_bf16 v[8:11], v[178:181], v[236:239], v[8:11]
	v_mfma_f32_16x16x32_bf16 v[62:65], v[174:177], v[216:219], v[62:65]
	v_mfma_f32_16x16x32_bf16 v[58:61], v[182:185], v[216:219], v[58:61]
	v_mfma_f32_16x16x32_bf16 v[50:53], v[174:177], v[224:227], v[50:53]
	v_mfma_f32_16x16x32_bf16 v[42:45], v[182:185], v[224:227], v[42:45]
	v_mfma_f32_16x16x32_bf16 v[34:37], v[174:177], v[232:235], v[34:37]
	v_mfma_f32_16x16x32_bf16 v[24:27], v[182:185], v[232:235], v[24:27]
	v_mfma_f32_16x16x32_bf16 v[16:19], v[174:177], v[240:243], v[16:19]
	v_mfma_f32_16x16x32_bf16 v[8:11], v[182:185], v[240:243], v[8:11]
	v_mfma_f32_16x16x32_bf16 v[54:57], v[196:199], v[212:215], v[54:57]
	v_mfma_f32_16x16x32_bf16 v[46:49], v[204:207], v[212:215], v[46:49]
	v_mfma_f32_16x16x32_bf16 v[38:41], v[196:199], v[220:223], v[38:41]
	v_mfma_f32_16x16x32_bf16 v[28:31], v[204:207], v[220:223], v[28:31]
	v_mfma_f32_16x16x32_bf16 v[20:23], v[196:199], v[228:231], v[20:23]
	v_mfma_f32_16x16x32_bf16 v[12:15], v[204:207], v[228:231], v[12:15]
	v_mfma_f32_16x16x32_bf16 v[4:7], v[196:199], v[236:239], v[4:7]
	v_mfma_f32_16x16x32_bf16 v[0:3], v[204:207], v[236:239], v[0:3]
	v_mfma_f32_16x16x32_bf16 v[54:57], v[200:203], v[216:219], v[54:57]
	v_mfma_f32_16x16x32_bf16 v[46:49], v[208:211], v[216:219], v[46:49]
	v_mfma_f32_16x16x32_bf16 v[38:41], v[200:203], v[224:227], v[38:41]
	v_mfma_f32_16x16x32_bf16 v[28:31], v[208:211], v[224:227], v[28:31]
	v_mfma_f32_16x16x32_bf16 v[20:23], v[200:203], v[232:235], v[20:23]
	v_mfma_f32_16x16x32_bf16 v[12:15], v[208:211], v[232:235], v[12:15]
	v_mfma_f32_16x16x32_bf16 v[4:7], v[200:203], v[240:243], v[4:7]
	v_mfma_f32_16x16x32_bf16 v[0:3], v[208:211], v[240:243], v[0:3]
	s_barrier
	s_add_i32 s80, s80, 2
	s_add_u32 s4, s4, 0x100
	s_addc_u32 s7, s7, 0
	s_add_u32 s90, s90, 0x100
	s_addc_u32 s91, s91, 0
	s_cmp_gt_u32 s80, 13
	s_cbranch_scc0 .LBB0_66
	s_and_b64 vcc, exec, s[38:39]
	s_cbranch_vccz .LBB0_69
	s_barrier

; #define PG8_STAGE(bufoff, gbase, voff) do { _Pragma("unroll") for (int _i = 0; _i < 2; ++_i) \
;         __builtin_amdgcn_global_load_lds((const unsigned*)((const char*)(gbase) + (voff)[_i]), (PG8_LAS unsigned*)(lds + (bufoff) + ldsw + _i * 8192), 16, 0, 0); } while (0)
; #define PG8_LDA(dst, b, h) do { _Pragma("unroll") for (int m = 0; m < 4; ++m) _Pragma("unroll") for (int k = 0; k < 2; ++k) dst[m][k] = *(const PG8_LAS bf16x8*)(lds + PG8_SA(b, h) + aoff + m * 2048 + k * 1024); } while (0)
; #define PG8_LDB(dst, b, h) do { _Pragma("unroll") for (int n = 0; n < 2; ++n) _Pragma("unroll") for (int k = 0; k < 2; ++k) dst[n][k] = *(const PG8_LAS bf16x8*)(lds + PG8_SB(b, h) + boff + n * 2048 + k * 1024); } while (0)
; #define PG8_MMA(ai, bj, At, Bt) do { __builtin_amdgcn_s_setprio(1); _Pragma("unroll") for (int m = 0; m < 4; ++m) _Pragma("unroll") for (int n = 0; n < 2; ++n) _Pragma("unroll") for (int k = 0; k < 2; ++k) \
;         acc[ai][bj][m][n] = __builtin_amdgcn_mfma_f32_16x16x32_bf16(Bt[n][k], At[m][k], acc[ai][bj][m][n], 0, 0, 0); __builtin_amdgcn_s_setprio(0); } while (0)
; #define PG8_WAIT_V(n) asm volatile("s_waitcnt vmcnt(" #n ")" ::: "memory")
; #define PG8_BAR __builtin_amdgcn_s_barrier()
; template <class Epi, class Sched, bool ALIGN_EPI = false, bool SP2 = false>
; __device__ __forceinline__ void gemm_phase(PG8_LAS unsigned char* lds, const Gemm g, const Sched& S, const Epi& E) {
;     ...
;         for (int t = 0; t < nt; t += 2) {
;             const bool last = (t == nt - 2);
;             const char* a1 = cA + (size_t)(t + 1) * kstep;
;             const char* a2 = last ? nA : cA + (size_t)(t + 2) * kstep; const char* b2 = last ? nB : cB + (size_t)(t + 2) * kstep;
;             const char* a3 = a2 + kstep; const char* b3 = b2 + kstep;
;             if (last && has_next) S.a_ready(nxt);
;             if constexpr (SP2) {
;             PG8_LDB(B0, 0, 0); PG8_LDB(B1, 0, 1); PG8_SCHED; PG8_LDA(At, 0, 0); PG8_STAGE(PG8_SA(1, 1), a1 + hstep, voffA);
;             PG8_WAIT_V(8); PG8_WAIT_L(0); PG8_BAR; PG8_MMA(0, 0, At, B0); PG8_MMA(0, 1, At, B1); PG8_BAR; PG8_SCHED;
;             PG8_LDA(At, 0, 1); PG8_STAGE(PG8_SB(0, 0), b2, voffB); PG8_STAGE(PG8_SB(0, 1), b2 + hstep, voffB); PG8_STAGE(PG8_SA(0, 0), a2, voffA);
;             PG8_WAIT_V(8); PG8_WAIT_L(0); PG8_BAR; PG8_MMA(1, 0, At, B0); PG8_MMA(1, 1, At, B1); PG8_BAR; PG8_SCHED;
.LBB0_91:
	s_add_u32 s48, s46, 0xfffc0080
	s_addc_u32 s49, s47, -1
	s_add_i32 s61, 0, 0x10000
	s_cmp_eq_u32 s80, 12
	s_cselect_b32 s51, s89, s49
	s_cselect_b32 s50, vcc_lo, s48
	s_cselect_b32 s49, s87, s7
	s_cselect_b32 s48, vcc_hi, s5
	s_add_i32 s72, 0, 0x14000
	v_add_u32_e32 v110, s61, v170
	v_add_u32_e32 v173, s72, v170
	ds_read_b128 v[98:101], v110
	ds_read_b128 v[102:105], v110 offset:1024
	ds_read_b128 v[106:109], v110 offset:2048
	ds_read_b128 v[110:113], v110 offset:3072
	ds_read_b128 v[158:161], v173
	ds_read_b128 v[174:177], v173 offset:1024
	ds_read_b128 v[178:181], v173 offset:2048
	ds_read_b128 v[182:185], v173 offset:3072
	v_lshl_add_u64 v[228:229], s[46:47], 0, v[156:157]
	s_add_i32 m0, s9, 0xc000
	ds_read_b128 v[196:199], v172
	ds_read_b128 v[200:203], v172 offset:1024
	ds_read_b128 v[204:207], v172 offset:2048
	ds_read_b128 v[208:211], v172 offset:3072
	ds_read_b128 v[212:215], v172 offset:4096
	ds_read_b128 v[216:219], v172 offset:5120
	ds_read_b128 v[220:223], v172 offset:6144
	ds_read_b128 v[224:227], v172 offset:7168
	global_load_lds_dwordx4 v[228:229], off
	v_lshl_add_u64 v[228:229], s[46:47], 0, v[154:155]
	s_add_i32 m0, s9, 0xe000
	s_nop 0
	global_load_lds_dwordx4 v[228:229], off
	.p2align	6
	s_waitcnt vmcnt(8)
	s_waitcnt lgkmcnt(0)
	s_barrier
	v_mfma_f32_16x16x32_bf16 v[142:145], v[98:101], v[196:199], v[142:145]
	v_mfma_f32_16x16x32_bf16 v[138:141], v[106:109], v[196:199], v[138:141]
	v_mfma_f32_16x16x32_bf16 v[126:129], v[98:101], v[204:207], v[126:129]
	v_mfma_f32_16x16x32_bf16 v[122:125], v[106:109], v[204:207], v[122:125]
	v_mfma_f32_16x16x32_bf16 v[94:97], v[98:101], v[212:215], v[94:97]
	v_mfma_f32_16x16x32_bf16 v[90:93], v[106:109], v[212:215], v[90:93]
	v_mfma_f32_16x16x32_bf16 v[78:81], v[98:101], v[220:223], v[78:81]
	v_mfma_f32_16x16x32_bf16 v[74:77], v[106:109], v[220:223], v[74:77]
	v_mfma_f32_16x16x32_bf16 v[142:145], v[102:105], v[200:203], v[142:145]
	v_mfma_f32_16x16x32_bf16 v[138:141], v[110:113], v[200:203], v[138:141]
	v_mfma_f32_16x16x32_bf16 v[126:129], v[102:105], v[208:211], v[126:129]
	v_mfma_f32_16x16x32_bf16 v[122:125], v[110:113], v[208:211], v[122:125]
	v_mfma_f32_16x16x32_bf16 v[94:97], v[102:105], v[216:219], v[94:97]
	v_mfma_f32_16x16x32_bf16 v[90:93], v[110:113], v[216:219], v[90:93]
	v_mfma_f32_16x16x32_bf16 v[78:81], v[102:105], v[224:227], v[78:81]
	v_mfma_f32_16x16x32_bf16 v[74:77], v[110:113], v[224:227], v[74:77]
	v_mfma_f32_16x16x32_bf16 v[134:137], v[158:161], v[196:199], v[134:137]
	v_mfma_f32_16x16x32_bf16 v[130:133], v[178:181], v[196:199], v[130:133]
	v_mfma_f32_16x16x32_bf16 v[118:121], v[158:161], v[204:207], v[118:121]
	v_mfma_f32_16x16x32_bf16 v[114:117], v[178:181], v[204:207], v[114:117]
	v_mfma_f32_16x16x32_bf16 v[86:89], v[158:161], v[212:215], v[86:89]
	v_mfma_f32_16x16x32_bf16 v[82:85], v[178:181], v[212:215], v[82:85]
	v_mfma_f32_16x16x32_bf16 v[70:73], v[158:161], v[220:223], v[70:73]
	v_mfma_f32_16x16x32_bf16 v[66:69], v[178:181], v[220:223], v[66:69]
	v_mfma_f32_16x16x32_bf16 v[134:137], v[174:177], v[200:203], v[134:137]
	v_mfma_f32_16x16x32_bf16 v[130:133], v[182:185], v[200:203], v[130:133]
	v_mfma_f32_16x16x32_bf16 v[118:121], v[174:177], v[208:211], v[118:121]
	v_mfma_f32_16x16x32_bf16 v[114:117], v[182:185], v[208:211], v[114:117]
	v_mfma_f32_16x16x32_bf16 v[86:89], v[174:177], v[216:219], v[86:89]
	v_mfma_f32_16x16x32_bf16 v[82:85], v[182:185], v[216:219], v[82:85]
	v_mfma_f32_16x16x32_bf16 v[70:73], v[174:177], v[224:227], v[70:73]
	v_mfma_f32_16x16x32_bf16 v[66:69], v[182:185], v[224:227], v[66:69]
	s_barrier
	s_add_i32 s61, s61, s8
	v_lshl_add_u64 v[228:229], s[48:49], 0, v[148:149]
	s_mov_b32 m0, s61
	ds_read_b128 v[196:199], v172 offset:16384
	ds_read_b128 v[200:203], v172 offset:17408
	ds_read_b128 v[204:207], v172 offset:18432
	ds_read_b128 v[208:211], v172 offset:19456
	ds_read_b128 v[212:215], v172 offset:20480
	ds_read_b128 v[216:219], v172 offset:21504
	ds_read_b128 v[220:223], v172 offset:22528
	ds_read_b128 v[224:227], v172 offset:23552
	global_load_lds_dwordx4 v[228:229], off
	s_add_i32 m0, s61, 0x2000
	s_add_u32 s76, s48, 0x40000
	v_lshl_add_u64 v[230:231], s[48:49], 0, v[152:153]
	s_addc_u32 s77, s49, 0
	s_add_i32 s61, s72, s8
	global_load_lds_dwordx4 v[230:231], off
	v_lshl_add_u64 v[232:233], s[76:77], 0, v[148:149]
	s_mov_b32 m0, s61
	v_lshl_add_u64 v[234:235], s[50:51], 0, v[150:151]
	global_load_lds_dwordx4 v[232:233], off
	v_lshl_add_u64 v[232:233], s[76:77], 0, v[152:153]
	s_add_i32 m0, s61, 0x2000
	s_nop 0
	global_load_lds_dwordx4 v[232:233], off
	v_lshl_add_u64 v[232:233], s[50:51], 0, v[146:147]
	s_mov_b32 m0, s9
	s_nop 0
	global_load_lds_dwordx4 v[232:233], off
	s_mov_b32 m0, s96
	s_nop 0
	global_load_lds_dwordx4 v[234:235], off
	.p2align	6
	s_waitcnt vmcnt(8)
	s_waitcnt lgkmcnt(0)
	s_barrier
; #define PG8_STAGE(bufoff, gbase, voff) do { _Pragma("unroll") for (int _i = 0; _i < 2; ++_i) \
;         __builtin_amdgcn_global_load_lds((const unsigned*)((const char*)(gbase) + (voff)[_i]), (PG8_LAS unsigned*)(lds + (bufoff) + ldsw + _i * 8192), 16, 0, 0); } while (0)
; #define PG8_LDA(dst, b, h) do { _Pragma("unroll") for (int m = 0; m < 4; ++m) _Pragma("unroll") for (int k = 0; k < 2; ++k) dst[m][k] = *(const PG8_LAS bf16x8*)(lds + PG8_SA(b, h) + aoff + m * 2048 + k * 1024); } while (0)
; #define PG8_LDB(dst, b, h) do { _Pragma("unroll") for (int n = 0; n < 2; ++n) _Pragma("unroll") for (int k = 0; k < 2; ++k) dst[n][k] = *(const PG8_LAS bf16x8*)(lds + PG8_SB(b, h) + boff + n * 2048 + k * 1024); } while (0)
; #define PG8_MMA(ai, bj, At, Bt) do { __builtin_amdgcn_s_setprio(1); _Pragma("unroll") for (int m = 0; m < 4; ++m) _Pragma("unroll") for (int n = 0; n < 2; ++n) _Pragma("unroll") for (int k = 0; k < 2; ++k) \
;         acc[ai][bj][m][n] = __builtin_amdgcn_mfma_f32_16x16x32_bf16(Bt[n][k], At[m][k], acc[ai][bj][m][n], 0, 0, 0); __builtin_amdgcn_s_setprio(0); } while (0)
; #define PG8_WAIT_V(n) asm volatile("s_waitcnt vmcnt(" #n ")" ::: "memory")
; #define PG8_WAIT_L(n) asm volatile("s_waitcnt lgkmcnt(" #n ")" ::: "memory")
; #define PG8_BAR __builtin_amdgcn_s_barrier()
; #define PG8_SCHED __builtin_amdgcn_sched_barrier(0)
; template <class Epi, class Sched, bool ALIGN_EPI = false, bool SP2 = false>
; __device__ __forceinline__ void gemm_phase(PG8_LAS unsigned char* lds, const Gemm g, const Sched& S, const Epi& E) {
;     ...
;             PG8_WAIT_V(8); PG8_WAIT_L(0); PG8_BAR; PG8_MMA(1, 0, At, B0); PG8_MMA(1, 1, At, B1); PG8_BAR; PG8_SCHED;
;             PG8_LDB(B0, 1, 0); PG8_LDB(B1, 1, 1); PG8_SCHED; PG8_LDA(At, 1, 0); PG8_STAGE(PG8_SA(0, 1), a2 + hstep, voffA);
;             PG8_WAIT_V(8); PG8_WAIT_L(0); PG8_BAR; PG8_MMA(0, 0, At, B0); PG8_MMA(0, 1, At, B1); PG8_BAR; PG8_SCHED;
	v_mfma_f32_16x16x32_bf16 v[62:65], v[98:101], v[196:199], v[62:65]
	v_mfma_f32_16x16x32_bf16 v[58:61], v[106:109], v[196:199], v[58:61]
	v_mfma_f32_16x16x32_bf16 v[50:53], v[98:101], v[204:207], v[50:53]
	v_mfma_f32_16x16x32_bf16 v[42:45], v[106:109], v[204:207], v[42:45]
	v_mfma_f32_16x16x32_bf16 v[34:37], v[98:101], v[212:215], v[34:37]
	v_mfma_f32_16x16x32_bf16 v[24:27], v[106:109], v[212:215], v[24:27]
	v_mfma_f32_16x16x32_bf16 v[12:15], v[98:101], v[220:223], v[12:15]
	v_mfma_f32_16x16x32_bf16 v[8:11], v[106:109], v[220:223], v[8:11]
	v_mfma_f32_16x16x32_bf16 v[62:65], v[102:105], v[200:203], v[62:65]
	v_mfma_f32_16x16x32_bf16 v[58:61], v[110:113], v[200:203], v[58:61]
	v_mfma_f32_16x16x32_bf16 v[50:53], v[102:105], v[208:211], v[50:53]
	v_mfma_f32_16x16x32_bf16 v[42:45], v[110:113], v[208:211], v[42:45]
	v_mfma_f32_16x16x32_bf16 v[34:37], v[102:105], v[216:219], v[34:37]
	v_mfma_f32_16x16x32_bf16 v[24:27], v[110:113], v[216:219], v[24:27]
	v_mfma_f32_16x16x32_bf16 v[12:15], v[102:105], v[224:227], v[12:15]
	v_mfma_f32_16x16x32_bf16 v[8:11], v[110:113], v[224:227], v[8:11]
	v_mfma_f32_16x16x32_bf16 v[54:57], v[158:161], v[196:199], v[54:57]
	v_mfma_f32_16x16x32_bf16 v[46:49], v[178:181], v[196:199], v[46:49]
	v_mfma_f32_16x16x32_bf16 v[38:41], v[158:161], v[204:207], v[38:41]
	v_mfma_f32_16x16x32_bf16 v[28:31], v[178:181], v[204:207], v[28:31]
	v_mfma_f32_16x16x32_bf16 v[20:23], v[158:161], v[212:215], v[20:23]
	v_mfma_f32_16x16x32_bf16 v[16:19], v[178:181], v[212:215], v[16:19]
	v_mfma_f32_16x16x32_bf16 v[4:7], v[158:161], v[220:223], v[4:7]
	v_mfma_f32_16x16x32_bf16 v[0:3], v[178:181], v[220:223], v[0:3]
	v_mfma_f32_16x16x32_bf16 v[54:57], v[174:177], v[200:203], v[54:57]
	v_mfma_f32_16x16x32_bf16 v[46:49], v[182:185], v[200:203], v[46:49]
	v_mfma_f32_16x16x32_bf16 v[38:41], v[174:177], v[208:211], v[38:41]
	v_mfma_f32_16x16x32_bf16 v[28:31], v[182:185], v[208:211], v[28:31]
	v_mfma_f32_16x16x32_bf16 v[20:23], v[174:177], v[216:219], v[20:23]
	v_mfma_f32_16x16x32_bf16 v[16:19], v[182:185], v[216:219], v[16:19]
	v_mfma_f32_16x16x32_bf16 v[4:7], v[174:177], v[224:227], v[4:7]
	v_mfma_f32_16x16x32_bf16 v[0:3], v[182:185], v[224:227], v[0:3]
	s_barrier
	s_add_i32 s61, 0, 0x18000
	s_add_i32 s72, 0, 0x1c000
	v_add_u32_e32 v110, s61, v170
	v_add_u32_e32 v173, s72, v170
	ds_read_b128 v[98:101], v110
	ds_read_b128 v[102:105], v110 offset:1024
	ds_read_b128 v[106:109], v110 offset:2048
	ds_read_b128 v[110:113], v110 offset:3072
	ds_read_b128 v[158:161], v173
	ds_read_b128 v[174:177], v173 offset:1024
	ds_read_b128 v[178:181], v173 offset:2048
	ds_read_b128 v[182:185], v173 offset:3072
	s_add_u32 s50, s50, 0x40000
	s_addc_u32 s51, s51, 0
	s_mov_b32 m0, s97
	v_lshl_add_u64 v[236:237], s[50:51], 0, v[146:147]
	ds_read_b128 v[196:199], v172 offset:32768
	ds_read_b128 v[200:203], v172 offset:33792
	ds_read_b128 v[204:207], v172 offset:34816
	ds_read_b128 v[208:211], v172 offset:35840
	ds_read_b128 v[212:215], v172 offset:36864
	ds_read_b128 v[216:219], v172 offset:37888
	ds_read_b128 v[220:223], v172 offset:38912
	ds_read_b128 v[224:227], v172 offset:39936
	global_load_lds_dwordx4 v[236:237], off
	v_lshl_add_u64 v[236:237], s[50:51], 0, v[150:151]
	s_mov_b32 m0, s2
	s_nop 0
	global_load_lds_dwordx4 v[236:237], off
	.p2align	6
	s_waitcnt vmcnt(8)
	s_waitcnt lgkmcnt(0)
	s_barrier
	v_mfma_f32_16x16x32_bf16 v[142:145], v[98:101], v[196:199], v[142:145]
	v_mfma_f32_16x16x32_bf16 v[138:141], v[106:109], v[196:199], v[138:141]
	v_mfma_f32_16x16x32_bf16 v[126:129], v[98:101], v[204:207], v[126:129]
	v_mfma_f32_16x16x32_bf16 v[122:125], v[106:109], v[204:207], v[122:125]
	v_mfma_f32_16x16x32_bf16 v[94:97], v[98:101], v[212:215], v[94:97]
	v_mfma_f32_16x16x32_bf16 v[90:93], v[106:109], v[212:215], v[90:93]
	v_mfma_f32_16x16x32_bf16 v[78:81], v[98:101], v[220:223], v[78:81]
	v_mfma_f32_16x16x32_bf16 v[74:77], v[106:109], v[220:223], v[74:77]
	v_mfma_f32_16x16x32_bf16 v[142:145], v[102:105], v[200:203], v[142:145]
	v_mfma_f32_16x16x32_bf16 v[138:141], v[110:113], v[200:203], v[138:141]
	v_mfma_f32_16x16x32_bf16 v[126:129], v[102:105], v[208:211], v[126:129]
	v_mfma_f32_16x16x32_bf16 v[122:125], v[110:113], v[208:211], v[122:125]
	v_mfma_f32_16x16x32_bf16 v[94:97], v[102:105], v[216:219], v[94:97]
	v_mfma_f32_16x16x32_bf16 v[90:93], v[110:113], v[216:219], v[90:93]
	v_mfma_f32_16x16x32_bf16 v[78:81], v[102:105], v[224:227], v[78:81]
	v_mfma_f32_16x16x32_bf16 v[74:77], v[110:113], v[224:227], v[74:77]
	v_mfma_f32_16x16x32_bf16 v[134:137], v[158:161], v[196:199], v[134:137]
	v_mfma_f32_16x16x32_bf16 v[130:133], v[178:181], v[196:199], v[130:133]
	v_mfma_f32_16x16x32_bf16 v[118:121], v[158:161], v[204:207], v[118:121]
	v_mfma_f32_16x16x32_bf16 v[114:117], v[178:181], v[204:207], v[114:117]
	v_mfma_f32_16x16x32_bf16 v[86:89], v[158:161], v[212:215], v[86:89]
	v_mfma_f32_16x16x32_bf16 v[82:85], v[178:181], v[212:215], v[82:85]
	v_mfma_f32_16x16x32_bf16 v[70:73], v[158:161], v[220:223], v[70:73]
	v_mfma_f32_16x16x32_bf16 v[66:69], v[178:181], v[220:223], v[66:69]
	v_mfma_f32_16x16x32_bf16 v[134:137], v[174:177], v[200:203], v[134:137]
	v_mfma_f32_16x16x32_bf16 v[130:133], v[182:185], v[200:203], v[130:133]
	v_mfma_f32_16x16x32_bf16 v[118:121], v[174:177], v[208:211], v[118:121]
	v_mfma_f32_16x16x32_bf16 v[114:117], v[182:185], v[208:211], v[114:117]
	v_mfma_f32_16x16x32_bf16 v[86:89], v[174:177], v[216:219], v[86:89]
	v_mfma_f32_16x16x32_bf16 v[82:85], v[182:185], v[216:219], v[82:85]
	v_mfma_f32_16x16x32_bf16 v[70:73], v[174:177], v[224:227], v[70:73]
	v_mfma_f32_16x16x32_bf16 v[66:69], v[182:185], v[224:227], v[66:69]
	s_barrier
; #define PG8_STAGE(bufoff, gbase, voff) do { _Pragma("unroll") for (int _i = 0; _i < 2; ++_i) \
;         __builtin_amdgcn_global_load_lds((const unsigned*)((const char*)(gbase) + (voff)[_i]), (PG8_LAS unsigned*)(lds + (bufoff) + ldsw + _i * 8192), 16, 0, 0); } while (0)
; #define PG8_LDA(dst, b, h) do { _Pragma("unroll") for (int m = 0; m < 4; ++m) _Pragma("unroll") for (int k = 0; k < 2; ++k) dst[m][k] = *(const PG8_LAS bf16x8*)(lds + PG8_SA(b, h) + aoff + m * 2048 + k * 1024); } while (0)
; #define PG8_MMA(ai, bj, At, Bt) do { __builtin_amdgcn_s_setprio(1); _Pragma("unroll") for (int m = 0; m < 4; ++m) _Pragma("unroll") for (int n = 0; n < 2; ++n) _Pragma("unroll") for (int k = 0; k < 2; ++k) \
;         acc[ai][bj][m][n] = __builtin_amdgcn_mfma_f32_16x16x32_bf16(Bt[n][k], At[m][k], acc[ai][bj][m][n], 0, 0, 0); __builtin_amdgcn_s_setprio(0); } while (0)
; #define PG8_WAIT_V(n) asm volatile("s_waitcnt vmcnt(" #n ")" ::: "memory")
; #define PG8_WAIT_L(n) asm volatile("s_waitcnt lgkmcnt(" #n ")" ::: "memory")
; #define PG8_BAR __builtin_amdgcn_s_barrier()
; #define PG8_SCHED __builtin_amdgcn_sched_barrier(0)
; template <class Epi, class Sched, bool ALIGN_EPI = false, bool SP2 = false>
; __device__ __forceinline__ void gemm_phase(PG8_LAS unsigned char* lds, const Gemm g, const Sched& S, const Epi& E) {
;     ...
;             PG8_WAIT_V(8); PG8_WAIT_L(0); PG8_BAR; PG8_MMA(0, 0, At, B0); PG8_MMA(0, 1, At, B1); PG8_BAR; PG8_SCHED;
;             PG8_LDA(At, 1, 1); PG8_STAGE(PG8_SB(1, 0), b3, voffB); PG8_STAGE(PG8_SB(1, 1), b3 + hstep, voffB); PG8_STAGE(PG8_SA(1, 0), a3, voffA);
;             PG8_WAIT_V(8); PG8_WAIT_L(0); PG8_BAR; PG8_MMA(1, 0, At, B0); PG8_MMA(1, 1, At, B1); PG8_BAR; PG8_SCHED;
	s_add_i32 s50, s61, s8
	v_lshl_add_u64 v[228:229], v[228:229], 0, s[34:35]
	s_mov_b32 m0, s50
	ds_read_b128 v[196:199], v172 offset:49152
	ds_read_b128 v[200:203], v172 offset:50176
	ds_read_b128 v[204:207], v172 offset:51200
	ds_read_b128 v[208:211], v172 offset:52224
	ds_read_b128 v[212:215], v172 offset:53248
	ds_read_b128 v[216:219], v172 offset:54272
	ds_read_b128 v[220:223], v172 offset:55296
	ds_read_b128 v[224:227], v172 offset:56320
	global_load_lds_dwordx4 v[228:229], off
	s_add_i32 m0, s50, 0x2000
	s_add_u32 s48, s48, 0x40080
	v_lshl_add_u64 v[228:229], v[230:231], 0, s[34:35]
	s_addc_u32 s49, s49, 0
	s_add_i32 s50, s72, s8
	global_load_lds_dwordx4 v[228:229], off
	v_lshl_add_u64 v[228:229], s[48:49], 0, v[148:149]
	s_mov_b32 m0, s50
	s_nop 0
	global_load_lds_dwordx4 v[228:229], off
	v_lshl_add_u64 v[228:229], s[48:49], 0, v[152:153]
	s_add_i32 m0, s50, 0x2000
	s_nop 0
	global_load_lds_dwordx4 v[228:229], off
	v_lshl_add_u64 v[228:229], v[232:233], 0, s[34:35]
	s_mov_b32 m0, s0
	s_nop 0
	global_load_lds_dwordx4 v[228:229], off
	v_lshl_add_u64 v[228:229], v[234:235], 0, s[34:35]
	s_mov_b32 m0, s3
	s_nop 0
	global_load_lds_dwordx4 v[228:229], off
	.p2align	6
	s_waitcnt vmcnt(8)
	s_waitcnt lgkmcnt(0)
	s_barrier
	v_mfma_f32_16x16x32_bf16 v[62:65], v[98:101], v[196:199], v[62:65]
	v_mfma_f32_16x16x32_bf16 v[58:61], v[106:109], v[196:199], v[58:61]
	v_mfma_f32_16x16x32_bf16 v[50:53], v[98:101], v[204:207], v[50:53]
	v_mfma_f32_16x16x32_bf16 v[42:45], v[106:109], v[204:207], v[42:45]
	v_mfma_f32_16x16x32_bf16 v[34:37], v[98:101], v[212:215], v[34:37]
	v_mfma_f32_16x16x32_bf16 v[24:27], v[106:109], v[212:215], v[24:27]
	v_mfma_f32_16x16x32_bf16 v[12:15], v[98:101], v[220:223], v[12:15]
	v_mfma_f32_16x16x32_bf16 v[8:11], v[106:109], v[220:223], v[8:11]
	v_mfma_f32_16x16x32_bf16 v[62:65], v[102:105], v[200:203], v[62:65]
	v_mfma_f32_16x16x32_bf16 v[58:61], v[110:113], v[200:203], v[58:61]
	v_mfma_f32_16x16x32_bf16 v[50:53], v[102:105], v[208:211], v[50:53]
	v_mfma_f32_16x16x32_bf16 v[42:45], v[110:113], v[208:211], v[42:45]
	v_mfma_f32_16x16x32_bf16 v[34:37], v[102:105], v[216:219], v[34:37]
	v_mfma_f32_16x16x32_bf16 v[24:27], v[110:113], v[216:219], v[24:27]
	v_mfma_f32_16x16x32_bf16 v[12:15], v[102:105], v[224:227], v[12:15]
	v_mfma_f32_16x16x32_bf16 v[8:11], v[110:113], v[224:227], v[8:11]
	v_mfma_f32_16x16x32_bf16 v[54:57], v[158:161], v[196:199], v[54:57]
	v_mfma_f32_16x16x32_bf16 v[46:49], v[178:181], v[196:199], v[46:49]
	v_mfma_f32_16x16x32_bf16 v[38:41], v[158:161], v[204:207], v[38:41]
	v_mfma_f32_16x16x32_bf16 v[28:31], v[178:181], v[204:207], v[28:31]
	v_mfma_f32_16x16x32_bf16 v[20:23], v[158:161], v[212:215], v[20:23]
	v_mfma_f32_16x16x32_bf16 v[16:19], v[178:181], v[212:215], v[16:19]
	v_mfma_f32_16x16x32_bf16 v[4:7], v[158:161], v[220:223], v[4:7]
	v_mfma_f32_16x16x32_bf16 v[0:3], v[178:181], v[220:223], v[0:3]
	v_mfma_f32_16x16x32_bf16 v[54:57], v[174:177], v[200:203], v[54:57]
	v_mfma_f32_16x16x32_bf16 v[46:49], v[182:185], v[200:203], v[46:49]
	v_mfma_f32_16x16x32_bf16 v[38:41], v[174:177], v[208:211], v[38:41]
	v_mfma_f32_16x16x32_bf16 v[28:31], v[182:185], v[208:211], v[28:31]
	v_mfma_f32_16x16x32_bf16 v[20:23], v[174:177], v[216:219], v[20:23]
	v_mfma_f32_16x16x32_bf16 v[16:19], v[182:185], v[216:219], v[16:19]
	v_mfma_f32_16x16x32_bf16 v[4:7], v[174:177], v[224:227], v[4:7]
	v_mfma_f32_16x16x32_bf16 v[0:3], v[182:185], v[224:227], v[0:3]
	s_barrier
	s_add_i32 s80, s80, 2
	s_add_u32 s5, s5, 0x100
	s_addc_u32 s7, s7, 0
	s_add_u32 s46, s46, 0x100
	s_addc_u32 s47, s47, 0
	s_cmp_gt_u32 s80, 13
	s_cbranch_scc0 .LBB0_91
	s_and_b64 vcc, exec, s[38:39]
	s_cbranch_vccz .LBB0_94
	s_barrier

; #define PG8_STAGE(bufoff, gbase, voff) do { _Pragma("unroll") for (int _i = 0; _i < 2; ++_i) \
;         __builtin_amdgcn_global_load_lds((const unsigned*)((const char*)(gbase) + (voff)[_i]), (PG8_LAS unsigned*)(lds + (bufoff) + ldsw + _i * 8192), 16, 0, 0); } while (0)
; #define PG8_LDA(dst, b, h) do { _Pragma("unroll") for (int m = 0; m < 4; ++m) _Pragma("unroll") for (int k = 0; k < 2; ++k) dst[m][k] = *(const PG8_LAS bf16x8*)(lds + PG8_SA(b, h) + aoff + m * 2048 + k * 1024); } while (0)
; #define PG8_LDB(dst, b, h) do { _Pragma("unroll") for (int n = 0; n < 2; ++n) _Pragma("unroll") for (int k = 0; k < 2; ++k) dst[n][k] = *(const PG8_LAS bf16x8*)(lds + PG8_SB(b, h) + boff + n * 2048 + k * 1024); } while (0)
; #define PG8_MMA(ai, bj, At, Bt) do { __builtin_amdgcn_s_setprio(1); _Pragma("unroll") for (int m = 0; m < 4; ++m) _Pragma("unroll") for (int n = 0; n < 2; ++n) _Pragma("unroll") for (int k = 0; k < 2; ++k) \
;         acc[ai][bj][m][n] = __builtin_amdgcn_mfma_f32_16x16x32_bf16(Bt[n][k], At[m][k], acc[ai][bj][m][n], 0, 0, 0); __builtin_amdgcn_s_setprio(0); } while (0)
; #define PG8_WAIT_V(n) asm volatile("s_waitcnt vmcnt(" #n ")" ::: "memory")
; #define PG8_BAR __builtin_amdgcn_s_barrier()
; template <class Epi, class Sched, bool ALIGN_EPI = false, bool SP2 = false>
; __device__ __forceinline__ void gemm_phase(PG8_LAS unsigned char* lds, const Gemm g, const Sched& S, const Epi& E) {
;     ...
;         for (int t = 0; t < nt; t += 2) {
;             const bool last = (t == nt - 2);
;             const char* a1 = cA + (size_t)(t + 1) * kstep;
;             const char* a2 = last ? nA : cA + (size_t)(t + 2) * kstep; const char* b2 = last ? nB : cB + (size_t)(t + 2) * kstep;
;             const char* a3 = a2 + kstep; const char* b3 = b2 + kstep;
;             if (last && has_next) S.a_ready(nxt);
;             if constexpr (SP2) {
;             PG8_LDB(B0, 0, 0); PG8_LDB(B1, 0, 1); PG8_SCHED; PG8_LDA(At, 0, 0); PG8_STAGE(PG8_SA(1, 1), a1 + hstep, voffA);
;             PG8_WAIT_V(8); PG8_WAIT_L(0); PG8_BAR; PG8_MMA(0, 0, At, B0); PG8_MMA(0, 1, At, B1); PG8_BAR; PG8_SCHED;
;             PG8_LDA(At, 0, 1); PG8_STAGE(PG8_SB(0, 0), b2, voffB); PG8_STAGE(PG8_SB(0, 1), b2 + hstep, voffB); PG8_STAGE(PG8_SA(0, 0), a2, voffA);
;             PG8_WAIT_V(8); PG8_WAIT_L(0); PG8_BAR; PG8_MMA(1, 0, At, B0); PG8_MMA(1, 1, At, B1); PG8_BAR; PG8_SCHED;
.LBB0_118:
	s_add_u32 s48, s46, 0xfffc0080
	s_addc_u32 s49, s47, -1
	s_add_i32 s61, 0, 0x10000
	s_cmp_eq_u32 vcc_lo, 12
	s_cselect_b32 s51, s5, s49
	s_cselect_b32 s50, s7, s48
	v_add_u32_e32 v150, s61, v145
	s_cselect_b32 s49, s8, s91
	s_cselect_b32 s48, s45, s89
	s_add_i32 s72, 0, 0x14000
	ds_read_b128 v[174:177], v150
	ds_read_b128 v[178:181], v150 offset:1024
	ds_read_b128 v[182:185], v150 offset:2048
	ds_read_b128 v[196:199], v150 offset:3072
	v_add_u32_e32 v150, s72, v145
	ds_read_b128 v[200:203], v150
	ds_read_b128 v[204:207], v150 offset:1024
	ds_read_b128 v[208:211], v150 offset:2048
	ds_read_b128 v[212:215], v150 offset:3072
	v_lshl_add_u64 v[150:151], s[46:47], 0, v[142:143]
	s_add_i32 m0, s39, 0xc000
	ds_read_b128 v[216:219], v149
	ds_read_b128 v[220:223], v149 offset:1024
	ds_read_b128 v[224:227], v149 offset:2048
	ds_read_b128 v[228:231], v149 offset:3072
	ds_read_b128 v[232:235], v149 offset:4096
	ds_read_b128 v[236:239], v149 offset:5120
	ds_read_b128 v[240:243], v149 offset:6144
	ds_read_b128 v[244:247], v149 offset:7168
	global_load_lds_dwordx4 v[150:151], off
	v_lshl_add_u64 v[150:151], s[46:47], 0, v[140:141]
	s_add_i32 m0, s39, 0xe000
	s_nop 0
	global_load_lds_dwordx4 v[150:151], off
	.p2align	6
	s_waitcnt vmcnt(8)
	s_waitcnt lgkmcnt(0)
	s_barrier
	v_mfma_f32_16x16x32_bf16 v[126:129], v[174:177], v[216:219], v[126:129]
	v_mfma_f32_16x16x32_bf16 v[122:125], v[182:185], v[216:219], v[122:125]
	v_mfma_f32_16x16x32_bf16 v[110:113], v[174:177], v[224:227], v[110:113]
	v_mfma_f32_16x16x32_bf16 v[106:109], v[182:185], v[224:227], v[106:109]
	v_mfma_f32_16x16x32_bf16 v[94:97], v[174:177], v[232:235], v[94:97]
	v_mfma_f32_16x16x32_bf16 v[90:93], v[182:185], v[232:235], v[90:93]
	v_mfma_f32_16x16x32_bf16 v[78:81], v[174:177], v[240:243], v[78:81]
	v_mfma_f32_16x16x32_bf16 v[74:77], v[182:185], v[240:243], v[74:77]
	v_mfma_f32_16x16x32_bf16 v[126:129], v[178:181], v[220:223], v[126:129]
	v_mfma_f32_16x16x32_bf16 v[122:125], v[196:199], v[220:223], v[122:125]
	v_mfma_f32_16x16x32_bf16 v[110:113], v[178:181], v[228:231], v[110:113]
	v_mfma_f32_16x16x32_bf16 v[106:109], v[196:199], v[228:231], v[106:109]
	v_mfma_f32_16x16x32_bf16 v[94:97], v[178:181], v[236:239], v[94:97]
	v_mfma_f32_16x16x32_bf16 v[90:93], v[196:199], v[236:239], v[90:93]
	v_mfma_f32_16x16x32_bf16 v[78:81], v[178:181], v[244:247], v[78:81]
	v_mfma_f32_16x16x32_bf16 v[74:77], v[196:199], v[244:247], v[74:77]
	v_mfma_f32_16x16x32_bf16 v[118:121], v[200:203], v[216:219], v[118:121]
	v_mfma_f32_16x16x32_bf16 v[114:117], v[208:211], v[216:219], v[114:117]
	v_mfma_f32_16x16x32_bf16 v[102:105], v[200:203], v[224:227], v[102:105]
	v_mfma_f32_16x16x32_bf16 v[98:101], v[208:211], v[224:227], v[98:101]
	v_mfma_f32_16x16x32_bf16 v[86:89], v[200:203], v[232:235], v[86:89]
	v_mfma_f32_16x16x32_bf16 v[82:85], v[208:211], v[232:235], v[82:85]
	v_mfma_f32_16x16x32_bf16 v[70:73], v[200:203], v[240:243], v[70:73]
	v_mfma_f32_16x16x32_bf16 v[66:69], v[208:211], v[240:243], v[66:69]
	v_mfma_f32_16x16x32_bf16 v[118:121], v[204:207], v[220:223], v[118:121]
	v_mfma_f32_16x16x32_bf16 v[114:117], v[212:215], v[220:223], v[114:117]
	v_mfma_f32_16x16x32_bf16 v[102:105], v[204:207], v[228:231], v[102:105]
	v_mfma_f32_16x16x32_bf16 v[98:101], v[212:215], v[228:231], v[98:101]
	v_mfma_f32_16x16x32_bf16 v[86:89], v[204:207], v[236:239], v[86:89]
	v_mfma_f32_16x16x32_bf16 v[82:85], v[212:215], v[236:239], v[82:85]
	v_mfma_f32_16x16x32_bf16 v[70:73], v[204:207], v[244:247], v[70:73]
	v_mfma_f32_16x16x32_bf16 v[66:69], v[212:215], v[244:247], v[66:69]
	s_barrier
	s_add_i32 s61, s61, s38
	v_lshl_add_u64 v[150:151], s[48:49], 0, v[132:133]
	s_mov_b32 m0, s61
	ds_read_b128 v[216:219], v149 offset:16384
	ds_read_b128 v[220:223], v149 offset:17408
	ds_read_b128 v[224:227], v149 offset:18432
	ds_read_b128 v[228:231], v149 offset:19456
	ds_read_b128 v[232:235], v149 offset:20480
	ds_read_b128 v[236:239], v149 offset:21504
	ds_read_b128 v[240:243], v149 offset:22528
	ds_read_b128 v[244:247], v149 offset:23552
	global_load_lds_dwordx4 v[150:151], off
	s_add_i32 m0, s61, 0x2000
	s_add_u32 s80, s48, 0x40000
	v_lshl_add_u64 v[160:161], s[48:49], 0, v[136:137]
	s_addc_u32 s81, s49, 0
	s_add_i32 s61, s72, s38
	global_load_lds_dwordx4 v[160:161], off
	v_lshl_add_u64 v[170:171], s[80:81], 0, v[132:133]
	s_mov_b32 m0, s61
	v_lshl_add_u64 v[248:249], s[50:51], 0, v[134:135]
	global_load_lds_dwordx4 v[170:171], off
	v_lshl_add_u64 v[170:171], s[80:81], 0, v[136:137]
	s_add_i32 m0, s61, 0x2000
	s_nop 0
	global_load_lds_dwordx4 v[170:171], off
	v_lshl_add_u64 v[170:171], s[50:51], 0, v[130:131]
	s_mov_b32 m0, s39
	s_nop 0
	global_load_lds_dwordx4 v[170:171], off
	s_mov_b32 m0, s2
	s_nop 0
	global_load_lds_dwordx4 v[248:249], off
	.p2align	6
	s_waitcnt vmcnt(8)
	s_waitcnt lgkmcnt(0)
	s_barrier
; #define PG8_STAGE(bufoff, gbase, voff) do { _Pragma("unroll") for (int _i = 0; _i < 2; ++_i) \
;         __builtin_amdgcn_global_load_lds((const unsigned*)((const char*)(gbase) + (voff)[_i]), (PG8_LAS unsigned*)(lds + (bufoff) + ldsw + _i * 8192), 16, 0, 0); } while (0)
; #define PG8_LDA(dst, b, h) do { _Pragma("unroll") for (int m = 0; m < 4; ++m) _Pragma("unroll") for (int k = 0; k < 2; ++k) dst[m][k] = *(const PG8_LAS bf16x8*)(lds + PG8_SA(b, h) + aoff + m * 2048 + k * 1024); } while (0)
; #define PG8_LDB(dst, b, h) do { _Pragma("unroll") for (int n = 0; n < 2; ++n) _Pragma("unroll") for (int k = 0; k < 2; ++k) dst[n][k] = *(const PG8_LAS bf16x8*)(lds + PG8_SB(b, h) + boff + n * 2048 + k * 1024); } while (0)
; #define PG8_MMA(ai, bj, At, Bt) do { __builtin_amdgcn_s_setprio(1); _Pragma("unroll") for (int m = 0; m < 4; ++m) _Pragma("unroll") for (int n = 0; n < 2; ++n) _Pragma("unroll") for (int k = 0; k < 2; ++k) \
;         acc[ai][bj][m][n] = __builtin_amdgcn_mfma_f32_16x16x32_bf16(Bt[n][k], At[m][k], acc[ai][bj][m][n], 0, 0, 0); __builtin_amdgcn_s_setprio(0); } while (0)
; #define PG8_WAIT_V(n) asm volatile("s_waitcnt vmcnt(" #n ")" ::: "memory")
; #define PG8_WAIT_L(n) asm volatile("s_waitcnt lgkmcnt(" #n ")" ::: "memory")
; #define PG8_BAR __builtin_amdgcn_s_barrier()
; #define PG8_SCHED __builtin_amdgcn_sched_barrier(0)
; template <class Epi, class Sched, bool ALIGN_EPI = false, bool SP2 = false>
; __device__ __forceinline__ void gemm_phase(PG8_LAS unsigned char* lds, const Gemm g, const Sched& S, const Epi& E) {
;     ...
;             PG8_WAIT_V(8); PG8_WAIT_L(0); PG8_BAR; PG8_MMA(1, 0, At, B0); PG8_MMA(1, 1, At, B1); PG8_BAR; PG8_SCHED;
;             PG8_LDB(B0, 1, 0); PG8_LDB(B1, 1, 1); PG8_SCHED; PG8_LDA(At, 1, 0); PG8_STAGE(PG8_SA(0, 1), a2 + hstep, voffA);
;             PG8_WAIT_V(8); PG8_WAIT_L(0); PG8_BAR; PG8_MMA(0, 0, At, B0); PG8_MMA(0, 1, At, B1); PG8_BAR; PG8_SCHED;
	v_mfma_f32_16x16x32_bf16 v[62:65], v[174:177], v[216:219], v[62:65]
	v_mfma_f32_16x16x32_bf16 v[58:61], v[182:185], v[216:219], v[58:61]
	v_mfma_f32_16x16x32_bf16 v[46:49], v[174:177], v[224:227], v[46:49]
	v_mfma_f32_16x16x32_bf16 v[42:45], v[182:185], v[224:227], v[42:45]
	v_mfma_f32_16x16x32_bf16 v[28:31], v[174:177], v[232:235], v[28:31]
	v_mfma_f32_16x16x32_bf16 v[24:27], v[182:185], v[232:235], v[24:27]
	v_mfma_f32_16x16x32_bf16 v[12:15], v[174:177], v[240:243], v[12:15]
	v_mfma_f32_16x16x32_bf16 v[8:11], v[182:185], v[240:243], v[8:11]
	v_mfma_f32_16x16x32_bf16 v[62:65], v[178:181], v[220:223], v[62:65]
	v_mfma_f32_16x16x32_bf16 v[58:61], v[196:199], v[220:223], v[58:61]
	v_mfma_f32_16x16x32_bf16 v[46:49], v[178:181], v[228:231], v[46:49]
	v_mfma_f32_16x16x32_bf16 v[42:45], v[196:199], v[228:231], v[42:45]
	v_mfma_f32_16x16x32_bf16 v[28:31], v[178:181], v[236:239], v[28:31]
	v_mfma_f32_16x16x32_bf16 v[24:27], v[196:199], v[236:239], v[24:27]
	v_mfma_f32_16x16x32_bf16 v[12:15], v[178:181], v[244:247], v[12:15]
	v_mfma_f32_16x16x32_bf16 v[8:11], v[196:199], v[244:247], v[8:11]
	v_mfma_f32_16x16x32_bf16 v[54:57], v[200:203], v[216:219], v[54:57]
	v_mfma_f32_16x16x32_bf16 v[50:53], v[208:211], v[216:219], v[50:53]
	v_mfma_f32_16x16x32_bf16 v[38:41], v[200:203], v[224:227], v[38:41]
	v_mfma_f32_16x16x32_bf16 v[34:37], v[208:211], v[224:227], v[34:37]
	v_mfma_f32_16x16x32_bf16 v[20:23], v[200:203], v[232:235], v[20:23]
	v_mfma_f32_16x16x32_bf16 v[16:19], v[208:211], v[232:235], v[16:19]
	v_mfma_f32_16x16x32_bf16 v[4:7], v[200:203], v[240:243], v[4:7]
	v_mfma_f32_16x16x32_bf16 v[0:3], v[208:211], v[240:243], v[0:3]
	v_mfma_f32_16x16x32_bf16 v[54:57], v[204:207], v[220:223], v[54:57]
	v_mfma_f32_16x16x32_bf16 v[50:53], v[212:215], v[220:223], v[50:53]
	v_mfma_f32_16x16x32_bf16 v[38:41], v[204:207], v[228:231], v[38:41]
	v_mfma_f32_16x16x32_bf16 v[34:37], v[212:215], v[228:231], v[34:37]
	v_mfma_f32_16x16x32_bf16 v[20:23], v[204:207], v[236:239], v[20:23]
	v_mfma_f32_16x16x32_bf16 v[16:19], v[212:215], v[236:239], v[16:19]
	v_mfma_f32_16x16x32_bf16 v[4:7], v[204:207], v[244:247], v[4:7]
	v_mfma_f32_16x16x32_bf16 v[0:3], v[212:215], v[244:247], v[0:3]
	s_barrier
	s_add_i32 s61, 0, 0x18000
	v_add_u32_e32 v153, s61, v145
	s_add_i32 s72, 0, 0x1c000
	ds_read_b128 v[174:177], v153
	ds_read_b128 v[178:181], v153 offset:1024
	ds_read_b128 v[182:185], v153 offset:2048
	ds_read_b128 v[196:199], v153 offset:3072
	v_add_u32_e32 v153, s72, v145
	ds_read_b128 v[200:203], v153
	ds_read_b128 v[204:207], v153 offset:1024
	ds_read_b128 v[208:211], v153 offset:2048
	ds_read_b128 v[212:215], v153 offset:3072
	s_add_u32 s50, s50, 0x40000
	s_addc_u32 s51, s51, 0
	s_mov_b32 m0, s3
	v_lshl_add_u64 v[250:251], s[50:51], 0, v[130:131]
	ds_read_b128 v[216:219], v149 offset:32768
	ds_read_b128 v[220:223], v149 offset:33792
	ds_read_b128 v[224:227], v149 offset:34816
	ds_read_b128 v[228:231], v149 offset:35840
	ds_read_b128 v[232:235], v149 offset:36864
	ds_read_b128 v[236:239], v149 offset:37888
	ds_read_b128 v[240:243], v149 offset:38912
	ds_read_b128 v[244:247], v149 offset:39936
	global_load_lds_dwordx4 v[250:251], off
	v_lshl_add_u64 v[250:251], s[50:51], 0, v[134:135]
	s_mov_b32 m0, s87
	s_nop 0
	global_load_lds_dwordx4 v[250:251], off
	.p2align	6
	s_waitcnt vmcnt(8)
	s_waitcnt lgkmcnt(0)
	s_barrier
	v_mfma_f32_16x16x32_bf16 v[126:129], v[174:177], v[216:219], v[126:129]
	v_mfma_f32_16x16x32_bf16 v[122:125], v[182:185], v[216:219], v[122:125]
	v_mfma_f32_16x16x32_bf16 v[110:113], v[174:177], v[224:227], v[110:113]
	v_mfma_f32_16x16x32_bf16 v[106:109], v[182:185], v[224:227], v[106:109]
	v_mfma_f32_16x16x32_bf16 v[94:97], v[174:177], v[232:235], v[94:97]
	v_mfma_f32_16x16x32_bf16 v[90:93], v[182:185], v[232:235], v[90:93]
	v_mfma_f32_16x16x32_bf16 v[78:81], v[174:177], v[240:243], v[78:81]
	v_mfma_f32_16x16x32_bf16 v[74:77], v[182:185], v[240:243], v[74:77]
	v_mfma_f32_16x16x32_bf16 v[126:129], v[178:181], v[220:223], v[126:129]
	v_mfma_f32_16x16x32_bf16 v[122:125], v[196:199], v[220:223], v[122:125]
	v_mfma_f32_16x16x32_bf16 v[110:113], v[178:181], v[228:231], v[110:113]
	v_mfma_f32_16x16x32_bf16 v[106:109], v[196:199], v[228:231], v[106:109]
	v_mfma_f32_16x16x32_bf16 v[94:97], v[178:181], v[236:239], v[94:97]
	v_mfma_f32_16x16x32_bf16 v[90:93], v[196:199], v[236:239], v[90:93]
	v_mfma_f32_16x16x32_bf16 v[78:81], v[178:181], v[244:247], v[78:81]
	v_mfma_f32_16x16x32_bf16 v[74:77], v[196:199], v[244:247], v[74:77]
	v_mfma_f32_16x16x32_bf16 v[118:121], v[200:203], v[216:219], v[118:121]
	v_mfma_f32_16x16x32_bf16 v[114:117], v[208:211], v[216:219], v[114:117]
	v_mfma_f32_16x16x32_bf16 v[102:105], v[200:203], v[224:227], v[102:105]
	v_mfma_f32_16x16x32_bf16 v[98:101], v[208:211], v[224:227], v[98:101]
	v_mfma_f32_16x16x32_bf16 v[86:89], v[200:203], v[232:235], v[86:89]
	v_mfma_f32_16x16x32_bf16 v[82:85], v[208:211], v[232:235], v[82:85]
	v_mfma_f32_16x16x32_bf16 v[70:73], v[200:203], v[240:243], v[70:73]
	v_mfma_f32_16x16x32_bf16 v[66:69], v[208:211], v[240:243], v[66:69]
	v_mfma_f32_16x16x32_bf16 v[118:121], v[204:207], v[220:223], v[118:121]
	v_mfma_f32_16x16x32_bf16 v[114:117], v[212:215], v[220:223], v[114:117]
	v_mfma_f32_16x16x32_bf16 v[102:105], v[204:207], v[228:231], v[102:105]
	v_mfma_f32_16x16x32_bf16 v[98:101], v[212:215], v[228:231], v[98:101]
	v_mfma_f32_16x16x32_bf16 v[86:89], v[204:207], v[236:239], v[86:89]
	v_mfma_f32_16x16x32_bf16 v[82:85], v[212:215], v[236:239], v[82:85]
	v_mfma_f32_16x16x32_bf16 v[70:73], v[204:207], v[244:247], v[70:73]
	v_mfma_f32_16x16x32_bf16 v[66:69], v[212:215], v[244:247], v[66:69]
	s_barrier
; #define PG8_STAGE(bufoff, gbase, voff) do { _Pragma("unroll") for (int _i = 0; _i < 2; ++_i) \
;         __builtin_amdgcn_global_load_lds((const unsigned*)((const char*)(gbase) + (voff)[_i]), (PG8_LAS unsigned*)(lds + (bufoff) + ldsw + _i * 8192), 16, 0, 0); } while (0)
; #define PG8_LDA(dst, b, h) do { _Pragma("unroll") for (int m = 0; m < 4; ++m) _Pragma("unroll") for (int k = 0; k < 2; ++k) dst[m][k] = *(const PG8_LAS bf16x8*)(lds + PG8_SA(b, h) + aoff + m * 2048 + k * 1024); } while (0)
; #define PG8_MMA(ai, bj, At, Bt) do { __builtin_amdgcn_s_setprio(1); _Pragma("unroll") for (int m = 0; m < 4; ++m) _Pragma("unroll") for (int n = 0; n < 2; ++n) _Pragma("unroll") for (int k = 0; k < 2; ++k) \
;         acc[ai][bj][m][n] = __builtin_amdgcn_mfma_f32_16x16x32_bf16(Bt[n][k], At[m][k], acc[ai][bj][m][n], 0, 0, 0); __builtin_amdgcn_s_setprio(0); } while (0)
; #define PG8_WAIT_V(n) asm volatile("s_waitcnt vmcnt(" #n ")" ::: "memory")
; #define PG8_WAIT_L(n) asm volatile("s_waitcnt lgkmcnt(" #n ")" ::: "memory")
; #define PG8_BAR __builtin_amdgcn_s_barrier()
; #define PG8_SCHED __builtin_amdgcn_sched_barrier(0)
; template <class Epi, class Sched, bool ALIGN_EPI = false, bool SP2 = false>
; __device__ __forceinline__ void gemm_phase(PG8_LAS unsigned char* lds, const Gemm g, const Sched& S, const Epi& E) {
;     ...
;             PG8_LDA(At, 1, 1); PG8_STAGE(PG8_SB(1, 0), b3, voffB); PG8_STAGE(PG8_SB(1, 1), b3 + hstep, voffB); PG8_STAGE(PG8_SA(1, 0), a3, voffA);
;             PG8_WAIT_V(8); PG8_WAIT_L(0); PG8_BAR; PG8_MMA(1, 0, At, B0); PG8_MMA(1, 1, At, B1); PG8_BAR; PG8_SCHED;
;     ...
;         if constexpr (ALIGN_EPI) { if (wr == 0) PG8_BAR; }
	s_add_i32 s50, s61, s38
	v_lshl_add_u64 v[150:151], v[150:151], 0, s[34:35]
	s_mov_b32 m0, s50
	ds_read_b128 v[216:219], v149 offset:49152
	ds_read_b128 v[220:223], v149 offset:50176
	ds_read_b128 v[224:227], v149 offset:51200
	ds_read_b128 v[228:231], v149 offset:52224
	ds_read_b128 v[232:235], v149 offset:53248
	ds_read_b128 v[236:239], v149 offset:54272
	ds_read_b128 v[240:243], v149 offset:55296
	ds_read_b128 v[244:247], v149 offset:56320
	global_load_lds_dwordx4 v[150:151], off
	s_add_i32 m0, s50, 0x2000
	s_add_u32 s48, s48, 0x40080
	v_lshl_add_u64 v[150:151], v[160:161], 0, s[34:35]
	s_addc_u32 s49, s49, 0
	s_add_i32 s50, s72, s38
	global_load_lds_dwordx4 v[150:151], off
	v_lshl_add_u64 v[150:151], s[48:49], 0, v[132:133]
	s_mov_b32 m0, s50
	s_nop 0
	global_load_lds_dwordx4 v[150:151], off
	v_lshl_add_u64 v[150:151], s[48:49], 0, v[136:137]
	s_add_i32 m0, s50, 0x2000
	s_nop 0
	global_load_lds_dwordx4 v[150:151], off
	v_lshl_add_u64 v[150:151], v[170:171], 0, s[34:35]
	s_mov_b32 m0, s0
	s_nop 0
	global_load_lds_dwordx4 v[150:151], off
	v_lshl_add_u64 v[150:151], v[248:249], 0, s[34:35]
	s_mov_b32 m0, s86
	s_nop 0
	global_load_lds_dwordx4 v[150:151], off
	.p2align	6
	s_waitcnt vmcnt(8)
	s_waitcnt lgkmcnt(0)
	s_barrier
	v_mfma_f32_16x16x32_bf16 v[62:65], v[174:177], v[216:219], v[62:65]
	v_mfma_f32_16x16x32_bf16 v[58:61], v[182:185], v[216:219], v[58:61]
	v_mfma_f32_16x16x32_bf16 v[46:49], v[174:177], v[224:227], v[46:49]
	v_mfma_f32_16x16x32_bf16 v[42:45], v[182:185], v[224:227], v[42:45]
	v_mfma_f32_16x16x32_bf16 v[28:31], v[174:177], v[232:235], v[28:31]
	v_mfma_f32_16x16x32_bf16 v[24:27], v[182:185], v[232:235], v[24:27]
	v_mfma_f32_16x16x32_bf16 v[12:15], v[174:177], v[240:243], v[12:15]
	v_mfma_f32_16x16x32_bf16 v[8:11], v[182:185], v[240:243], v[8:11]
	v_mfma_f32_16x16x32_bf16 v[62:65], v[178:181], v[220:223], v[62:65]
	v_mfma_f32_16x16x32_bf16 v[58:61], v[196:199], v[220:223], v[58:61]
	v_mfma_f32_16x16x32_bf16 v[46:49], v[178:181], v[228:231], v[46:49]
	v_mfma_f32_16x16x32_bf16 v[42:45], v[196:199], v[228:231], v[42:45]
	v_mfma_f32_16x16x32_bf16 v[28:31], v[178:181], v[236:239], v[28:31]
	v_mfma_f32_16x16x32_bf16 v[24:27], v[196:199], v[236:239], v[24:27]
	v_mfma_f32_16x16x32_bf16 v[12:15], v[178:181], v[244:247], v[12:15]
	v_mfma_f32_16x16x32_bf16 v[8:11], v[196:199], v[244:247], v[8:11]
	v_mfma_f32_16x16x32_bf16 v[54:57], v[200:203], v[216:219], v[54:57]
	v_mfma_f32_16x16x32_bf16 v[50:53], v[208:211], v[216:219], v[50:53]
	v_mfma_f32_16x16x32_bf16 v[38:41], v[200:203], v[224:227], v[38:41]
	v_mfma_f32_16x16x32_bf16 v[34:37], v[208:211], v[224:227], v[34:37]
	v_mfma_f32_16x16x32_bf16 v[20:23], v[200:203], v[232:235], v[20:23]
	v_mfma_f32_16x16x32_bf16 v[16:19], v[208:211], v[232:235], v[16:19]
	v_mfma_f32_16x16x32_bf16 v[4:7], v[200:203], v[240:243], v[4:7]
	v_mfma_f32_16x16x32_bf16 v[0:3], v[208:211], v[240:243], v[0:3]
	v_mfma_f32_16x16x32_bf16 v[54:57], v[204:207], v[220:223], v[54:57]
	v_mfma_f32_16x16x32_bf16 v[50:53], v[212:215], v[220:223], v[50:53]
	v_mfma_f32_16x16x32_bf16 v[38:41], v[204:207], v[228:231], v[38:41]
	v_mfma_f32_16x16x32_bf16 v[34:37], v[212:215], v[228:231], v[34:37]
	v_mfma_f32_16x16x32_bf16 v[20:23], v[204:207], v[236:239], v[20:23]
	v_mfma_f32_16x16x32_bf16 v[16:19], v[212:215], v[236:239], v[16:19]
	v_mfma_f32_16x16x32_bf16 v[4:7], v[204:207], v[244:247], v[4:7]
	v_mfma_f32_16x16x32_bf16 v[0:3], v[212:215], v[244:247], v[0:3]
	s_barrier
	s_add_i32 vcc_lo, vcc_lo, 2
	s_add_u32 s89, s89, 0x100
	s_addc_u32 s91, s91, 0
	s_add_u32 s46, s46, 0x100
	s_addc_u32 s47, s47, 0
	s_cmp_gt_u32 vcc_lo, 13
	s_cbranch_scc0 .LBB0_118
	v_readlane_b32 s46, v254, 51
	v_readlane_b32 s47, v254, 52
	s_and_b64 vcc, exec, s[46:47]
	s_cbranch_vccz .LBB0_121
	s_barrier

; #define PG8_STAGE(bufoff, gbase, voff) do { _Pragma("unroll") for (int _i = 0; _i < 2; ++_i) \
;         __builtin_amdgcn_global_load_lds((const unsigned*)((const char*)(gbase) + (voff)[_i]), (PG8_LAS unsigned*)(lds + (bufoff) + ldsw + _i * 8192), 16, 0, 0); } while (0)
; #define PG8_LDA(dst, b, h) do { _Pragma("unroll") for (int m = 0; m < 4; ++m) _Pragma("unroll") for (int k = 0; k < 2; ++k) dst[m][k] = *(const PG8_LAS bf16x8*)(lds + PG8_SA(b, h) + aoff + m * 2048 + k * 1024); } while (0)
; #define PG8_LDB(dst, b, h) do { _Pragma("unroll") for (int n = 0; n < 2; ++n) _Pragma("unroll") for (int k = 0; k < 2; ++k) dst[n][k] = *(const PG8_LAS bf16x8*)(lds + PG8_SB(b, h) + boff + n * 2048 + k * 1024); } while (0)
; #define PG8_MMA(ai, bj, At, Bt) do { __builtin_amdgcn_s_setprio(1); _Pragma("unroll") for (int m = 0; m < 4; ++m) _Pragma("unroll") for (int n = 0; n < 2; ++n) _Pragma("unroll") for (int k = 0; k < 2; ++k) \
;         acc[ai][bj][m][n] = __builtin_amdgcn_mfma_f32_16x16x32_bf16(Bt[n][k], At[m][k], acc[ai][bj][m][n], 0, 0, 0); __builtin_amdgcn_s_setprio(0); } while (0)
; #define PG8_WAIT_V(n) asm volatile("s_waitcnt vmcnt(" #n ")" ::: "memory")
; #define PG8_WAIT_L(n) asm volatile("s_waitcnt lgkmcnt(" #n ")" ::: "memory")
; #define PG8_BAR __builtin_amdgcn_s_barrier()
; #define PG8_SCHED __builtin_amdgcn_sched_barrier(0)
; template <class Epi, class Sched, bool ALIGN_EPI = false, bool SP2 = false>
; __device__ __forceinline__ void gemm_phase(PG8_LAS unsigned char* lds, const Gemm g, const Sched& S, const Epi& E) {
;     ...
;             const bool last = (t == nt - 2);
;             const char* a1 = cA + (size_t)(t + 1) * kstep;
;             const char* a2 = last ? nA : cA + (size_t)(t + 2) * kstep; const char* b2 = last ? nB : cB + (size_t)(t + 2) * kstep;
;             const char* a3 = a2 + kstep; const char* b3 = b2 + kstep;
;             if (last && has_next) S.a_ready(nxt);
;             if constexpr (SP2) {
;             PG8_LDB(B0, 0, 0); PG8_LDB(B1, 0, 1); PG8_SCHED; PG8_LDA(At, 0, 0); PG8_STAGE(PG8_SA(1, 1), a1 + hstep, voffA);
;             PG8_WAIT_V(8); PG8_WAIT_L(0); PG8_BAR; PG8_MMA(0, 0, At, B0); PG8_MMA(0, 1, At, B1); PG8_BAR; PG8_SCHED;
;             PG8_LDA(At, 0, 1); PG8_STAGE(PG8_SB(0, 0), b2, voffB); PG8_STAGE(PG8_SB(0, 1), b2 + hstep, voffB); PG8_STAGE(PG8_SA(0, 0), a2, voffA);
.LBB0_145:
	s_add_u32 s48, s46, 0xfffc0080
	s_addc_u32 s49, s47, -1
	s_add_i32 s61, 0, 0x10000
	s_cmp_eq_u32 s80, 12
	s_cselect_b32 s51, s3, s49
	s_cselect_b32 s50, s45, s48
	s_cselect_b32 s49, s89, s7
	s_cselect_b32 s48, vcc_lo, vcc_hi
	s_add_i32 s72, 0, 0x14000
	v_add_u32_e32 v70, s61, v176
	v_add_u32_e32 v174, s72, v176
	ds_read_b128 v[50:53], v70
	ds_read_b128 v[54:57], v70 offset:1024
	ds_read_b128 v[66:69], v70 offset:2048
	ds_read_b128 v[70:73], v70 offset:3072
	ds_read_b128 v[158:161], v174
	ds_read_b128 v[170:173], v174 offset:1024
	ds_read_b128 v[180:183], v174 offset:2048
	ds_read_b128 v[196:199], v174 offset:3072
	v_lshl_add_u64 v[174:175], s[46:47], 0, v[156:157]
	s_add_i32 m0, s5, 0xc000
	ds_read_b128 v[200:203], v178
	ds_read_b128 v[204:207], v178 offset:1024
	ds_read_b128 v[208:211], v178 offset:2048
	ds_read_b128 v[212:215], v178 offset:3072
	ds_read_b128 v[216:219], v178 offset:4096
	ds_read_b128 v[220:223], v178 offset:5120
	ds_read_b128 v[224:227], v178 offset:6144
	ds_read_b128 v[228:231], v178 offset:7168
	global_load_lds_dwordx4 v[174:175], off
	v_lshl_add_u64 v[174:175], s[46:47], 0, v[154:155]
	s_add_i32 m0, s5, 0xe000
	s_nop 0
	global_load_lds_dwordx4 v[174:175], off
	.p2align	6
	s_waitcnt vmcnt(8)
	s_waitcnt lgkmcnt(0)
	s_barrier
	v_mfma_f32_16x16x32_bf16 v[142:145], v[50:53], v[200:203], v[142:145]
	v_mfma_f32_16x16x32_bf16 v[138:141], v[66:69], v[200:203], v[138:141]
	v_mfma_f32_16x16x32_bf16 v[126:129], v[50:53], v[208:211], v[126:129]
	v_mfma_f32_16x16x32_bf16 v[122:125], v[66:69], v[208:211], v[122:125]
	v_mfma_f32_16x16x32_bf16 v[110:113], v[50:53], v[216:219], v[110:113]
	v_mfma_f32_16x16x32_bf16 v[106:109], v[66:69], v[216:219], v[106:109]
	v_mfma_f32_16x16x32_bf16 v[94:97], v[50:53], v[224:227], v[94:97]
	v_mfma_f32_16x16x32_bf16 v[90:93], v[66:69], v[224:227], v[90:93]
	v_mfma_f32_16x16x32_bf16 v[142:145], v[54:57], v[204:207], v[142:145]
	v_mfma_f32_16x16x32_bf16 v[138:141], v[70:73], v[204:207], v[138:141]
	v_mfma_f32_16x16x32_bf16 v[126:129], v[54:57], v[212:215], v[126:129]
	v_mfma_f32_16x16x32_bf16 v[122:125], v[70:73], v[212:215], v[122:125]
	v_mfma_f32_16x16x32_bf16 v[110:113], v[54:57], v[220:223], v[110:113]
	v_mfma_f32_16x16x32_bf16 v[106:109], v[70:73], v[220:223], v[106:109]
	v_mfma_f32_16x16x32_bf16 v[94:97], v[54:57], v[228:231], v[94:97]
	v_mfma_f32_16x16x32_bf16 v[90:93], v[70:73], v[228:231], v[90:93]
	v_mfma_f32_16x16x32_bf16 v[134:137], v[158:161], v[200:203], v[134:137]
	v_mfma_f32_16x16x32_bf16 v[130:133], v[180:183], v[200:203], v[130:133]
	v_mfma_f32_16x16x32_bf16 v[118:121], v[158:161], v[208:211], v[118:121]
	v_mfma_f32_16x16x32_bf16 v[114:117], v[180:183], v[208:211], v[114:117]
	v_mfma_f32_16x16x32_bf16 v[102:105], v[158:161], v[216:219], v[102:105]
	v_mfma_f32_16x16x32_bf16 v[98:101], v[180:183], v[216:219], v[98:101]
	v_mfma_f32_16x16x32_bf16 v[86:89], v[158:161], v[224:227], v[86:89]
	v_mfma_f32_16x16x32_bf16 v[82:85], v[180:183], v[224:227], v[82:85]
	v_mfma_f32_16x16x32_bf16 v[134:137], v[170:173], v[204:207], v[134:137]
	v_mfma_f32_16x16x32_bf16 v[130:133], v[196:199], v[204:207], v[130:133]
	v_mfma_f32_16x16x32_bf16 v[118:121], v[170:173], v[212:215], v[118:121]
	v_mfma_f32_16x16x32_bf16 v[114:117], v[196:199], v[212:215], v[114:117]
	v_mfma_f32_16x16x32_bf16 v[102:105], v[170:173], v[220:223], v[102:105]
	v_mfma_f32_16x16x32_bf16 v[98:101], v[196:199], v[220:223], v[98:101]
	v_mfma_f32_16x16x32_bf16 v[86:89], v[170:173], v[228:231], v[86:89]
	v_mfma_f32_16x16x32_bf16 v[82:85], v[196:199], v[228:231], v[82:85]
	s_barrier
	s_add_i32 s61, s61, s4
	v_lshl_add_u64 v[174:175], s[48:49], 0, v[148:149]
	s_mov_b32 m0, s61
	ds_read_b128 v[200:203], v178 offset:16384
	ds_read_b128 v[204:207], v178 offset:17408
	ds_read_b128 v[208:211], v178 offset:18432
	ds_read_b128 v[212:215], v178 offset:19456
	ds_read_b128 v[216:219], v178 offset:20480
	ds_read_b128 v[220:223], v178 offset:21504
	ds_read_b128 v[224:227], v178 offset:22528
	ds_read_b128 v[228:231], v178 offset:23552
	global_load_lds_dwordx4 v[174:175], off
	s_add_i32 m0, s61, 0x2000
	s_add_u32 s76, s48, 0x40000
	v_lshl_add_u64 v[184:185], s[48:49], 0, v[152:153]
	s_addc_u32 s77, s49, 0
	s_add_i32 s61, s72, s4
	global_load_lds_dwordx4 v[184:185], off
	v_lshl_add_u64 v[232:233], s[76:77], 0, v[148:149]
	s_mov_b32 m0, s61
	v_lshl_add_u64 v[234:235], s[50:51], 0, v[150:151]
	global_load_lds_dwordx4 v[232:233], off
	v_lshl_add_u64 v[232:233], s[76:77], 0, v[152:153]
	s_add_i32 m0, s61, 0x2000
	s_nop 0
	global_load_lds_dwordx4 v[232:233], off
	v_lshl_add_u64 v[232:233], s[50:51], 0, v[146:147]
	s_mov_b32 m0, s5
	s_nop 0
	global_load_lds_dwordx4 v[232:233], off
	s_mov_b32 m0, s91
	s_nop 0
	global_load_lds_dwordx4 v[234:235], off
	.p2align	6
	s_waitcnt vmcnt(8)
	s_waitcnt lgkmcnt(0)
	s_barrier
; #define PG8_STAGE(bufoff, gbase, voff) do { _Pragma("unroll") for (int _i = 0; _i < 2; ++_i) \
;         __builtin_amdgcn_global_load_lds((const unsigned*)((const char*)(gbase) + (voff)[_i]), (PG8_LAS unsigned*)(lds + (bufoff) + ldsw + _i * 8192), 16, 0, 0); } while (0)
; #define PG8_LDA(dst, b, h) do { _Pragma("unroll") for (int m = 0; m < 4; ++m) _Pragma("unroll") for (int k = 0; k < 2; ++k) dst[m][k] = *(const PG8_LAS bf16x8*)(lds + PG8_SA(b, h) + aoff + m * 2048 + k * 1024); } while (0)
; #define PG8_LDB(dst, b, h) do { _Pragma("unroll") for (int n = 0; n < 2; ++n) _Pragma("unroll") for (int k = 0; k < 2; ++k) dst[n][k] = *(const PG8_LAS bf16x8*)(lds + PG8_SB(b, h) + boff + n * 2048 + k * 1024); } while (0)
; #define PG8_MMA(ai, bj, At, Bt) do { __builtin_amdgcn_s_setprio(1); _Pragma("unroll") for (int m = 0; m < 4; ++m) _Pragma("unroll") for (int n = 0; n < 2; ++n) _Pragma("unroll") for (int k = 0; k < 2; ++k) \
;         acc[ai][bj][m][n] = __builtin_amdgcn_mfma_f32_16x16x32_bf16(Bt[n][k], At[m][k], acc[ai][bj][m][n], 0, 0, 0); __builtin_amdgcn_s_setprio(0); } while (0)
; #define PG8_WAIT_V(n) asm volatile("s_waitcnt vmcnt(" #n ")" ::: "memory")
; #define PG8_WAIT_L(n) asm volatile("s_waitcnt lgkmcnt(" #n ")" ::: "memory")
; #define PG8_BAR __builtin_amdgcn_s_barrier()
; #define PG8_SCHED __builtin_amdgcn_sched_barrier(0)
; template <class Epi, class Sched, bool ALIGN_EPI = false, bool SP2 = false>
; __device__ __forceinline__ void gemm_phase(PG8_LAS unsigned char* lds, const Gemm g, const Sched& S, const Epi& E) {
;     ...
;             PG8_WAIT_V(8); PG8_WAIT_L(0); PG8_BAR; PG8_MMA(1, 0, At, B0); PG8_MMA(1, 1, At, B1); PG8_BAR; PG8_SCHED;
;             PG8_LDB(B0, 1, 0); PG8_LDB(B1, 1, 1); PG8_SCHED; PG8_LDA(At, 1, 0); PG8_STAGE(PG8_SA(0, 1), a2 + hstep, voffA);
;             PG8_WAIT_V(8); PG8_WAIT_L(0); PG8_BAR; PG8_MMA(0, 0, At, B0); PG8_MMA(0, 1, At, B1); PG8_BAR; PG8_SCHED;
	v_mfma_f32_16x16x32_bf16 v[78:81], v[50:53], v[200:203], v[78:81]
	v_mfma_f32_16x16x32_bf16 v[74:77], v[66:69], v[200:203], v[74:77]
	v_mfma_f32_16x16x32_bf16 v[46:49], v[50:53], v[208:211], v[46:49]
	v_mfma_f32_16x16x32_bf16 v[42:45], v[66:69], v[208:211], v[42:45]
	v_mfma_f32_16x16x32_bf16 v[28:31], v[50:53], v[216:219], v[28:31]
	v_mfma_f32_16x16x32_bf16 v[24:27], v[66:69], v[216:219], v[24:27]
	v_mfma_f32_16x16x32_bf16 v[12:15], v[50:53], v[224:227], v[12:15]
	v_mfma_f32_16x16x32_bf16 v[8:11], v[66:69], v[224:227], v[8:11]
	v_mfma_f32_16x16x32_bf16 v[78:81], v[54:57], v[204:207], v[78:81]
	v_mfma_f32_16x16x32_bf16 v[74:77], v[70:73], v[204:207], v[74:77]
	v_mfma_f32_16x16x32_bf16 v[46:49], v[54:57], v[212:215], v[46:49]
	v_mfma_f32_16x16x32_bf16 v[42:45], v[70:73], v[212:215], v[42:45]
	v_mfma_f32_16x16x32_bf16 v[28:31], v[54:57], v[220:223], v[28:31]
	v_mfma_f32_16x16x32_bf16 v[24:27], v[70:73], v[220:223], v[24:27]
	v_mfma_f32_16x16x32_bf16 v[12:15], v[54:57], v[228:231], v[12:15]
	v_mfma_f32_16x16x32_bf16 v[8:11], v[70:73], v[228:231], v[8:11]
	v_mfma_f32_16x16x32_bf16 v[38:41], v[158:161], v[208:211], v[38:41]
	v_mfma_f32_16x16x32_bf16 v[34:37], v[180:183], v[208:211], v[34:37]
	v_mfma_f32_16x16x32_bf16 v[20:23], v[158:161], v[216:219], v[20:23]
	v_mfma_f32_16x16x32_bf16 v[16:19], v[180:183], v[216:219], v[16:19]
	v_mfma_f32_16x16x32_bf16 v[4:7], v[158:161], v[224:227], v[4:7]
	v_mfma_f32_16x16x32_bf16 v[0:3], v[180:183], v[224:227], v[0:3]
	v_mfma_f32_16x16x32_bf16 v[50:53], v[158:161], v[200:203], v[62:65]
	v_mfma_f32_16x16x32_bf16 v[54:57], v[180:183], v[200:203], v[58:61]
	v_mfma_f32_16x16x32_bf16 v[38:41], v[170:173], v[212:215], v[38:41]
	v_mfma_f32_16x16x32_bf16 v[34:37], v[196:199], v[212:215], v[34:37]
	v_mfma_f32_16x16x32_bf16 v[20:23], v[170:173], v[220:223], v[20:23]
	v_mfma_f32_16x16x32_bf16 v[16:19], v[196:199], v[220:223], v[16:19]
	v_mfma_f32_16x16x32_bf16 v[4:7], v[170:173], v[228:231], v[4:7]
	v_mfma_f32_16x16x32_bf16 v[0:3], v[196:199], v[228:231], v[0:3]
	v_mfma_f32_16x16x32_bf16 v[50:53], v[170:173], v[204:207], v[50:53]
	v_mfma_f32_16x16x32_bf16 v[54:57], v[196:199], v[204:207], v[54:57]
	s_barrier
	s_add_i32 s61, 0, 0x18000
	s_add_i32 s72, 0, 0x1c000
	v_add_u32_e32 v70, s61, v176
	v_add_u32_e32 v179, s72, v176
	ds_read_b128 v[58:61], v70
	ds_read_b128 v[62:65], v70 offset:1024
	ds_read_b128 v[66:69], v70 offset:2048
	ds_read_b128 v[70:73], v70 offset:3072
	ds_read_b128 v[158:161], v179
	ds_read_b128 v[170:173], v179 offset:1024
	ds_read_b128 v[180:183], v179 offset:2048
	ds_read_b128 v[196:199], v179 offset:3072
	s_add_u32 s50, s50, 0x40000
	s_addc_u32 s51, s51, 0
	s_mov_b32 m0, s8
	v_lshl_add_u64 v[236:237], s[50:51], 0, v[146:147]
	ds_read_b128 v[200:203], v178 offset:32768
	ds_read_b128 v[204:207], v178 offset:33792
	ds_read_b128 v[208:211], v178 offset:34816
	ds_read_b128 v[212:215], v178 offset:35840
	ds_read_b128 v[216:219], v178 offset:36864
	ds_read_b128 v[220:223], v178 offset:37888
	ds_read_b128 v[224:227], v178 offset:38912
	ds_read_b128 v[228:231], v178 offset:39936
	global_load_lds_dwordx4 v[236:237], off
	v_lshl_add_u64 v[236:237], s[50:51], 0, v[150:151]
	s_mov_b32 m0, s0
	s_nop 0
	global_load_lds_dwordx4 v[236:237], off
	.p2align	6
	s_waitcnt vmcnt(8)
	s_waitcnt lgkmcnt(0)
	s_barrier
	v_mfma_f32_16x16x32_bf16 v[142:145], v[58:61], v[200:203], v[142:145]
	v_mfma_f32_16x16x32_bf16 v[138:141], v[66:69], v[200:203], v[138:141]
	v_mfma_f32_16x16x32_bf16 v[126:129], v[58:61], v[208:211], v[126:129]
	v_mfma_f32_16x16x32_bf16 v[122:125], v[66:69], v[208:211], v[122:125]
	v_mfma_f32_16x16x32_bf16 v[110:113], v[58:61], v[216:219], v[110:113]
	v_mfma_f32_16x16x32_bf16 v[106:109], v[66:69], v[216:219], v[106:109]
	v_mfma_f32_16x16x32_bf16 v[94:97], v[58:61], v[224:227], v[94:97]
	v_mfma_f32_16x16x32_bf16 v[90:93], v[66:69], v[224:227], v[90:93]
	v_mfma_f32_16x16x32_bf16 v[142:145], v[62:65], v[204:207], v[142:145]
	v_mfma_f32_16x16x32_bf16 v[138:141], v[70:73], v[204:207], v[138:141]
	v_mfma_f32_16x16x32_bf16 v[126:129], v[62:65], v[212:215], v[126:129]
	v_mfma_f32_16x16x32_bf16 v[122:125], v[70:73], v[212:215], v[122:125]
	v_mfma_f32_16x16x32_bf16 v[110:113], v[62:65], v[220:223], v[110:113]
	v_mfma_f32_16x16x32_bf16 v[106:109], v[70:73], v[220:223], v[106:109]
	v_mfma_f32_16x16x32_bf16 v[94:97], v[62:65], v[228:231], v[94:97]
	v_mfma_f32_16x16x32_bf16 v[90:93], v[70:73], v[228:231], v[90:93]
	v_mfma_f32_16x16x32_bf16 v[134:137], v[158:161], v[200:203], v[134:137]
	v_mfma_f32_16x16x32_bf16 v[130:133], v[180:183], v[200:203], v[130:133]
	v_mfma_f32_16x16x32_bf16 v[118:121], v[158:161], v[208:211], v[118:121]
	v_mfma_f32_16x16x32_bf16 v[114:117], v[180:183], v[208:211], v[114:117]
	v_mfma_f32_16x16x32_bf16 v[102:105], v[158:161], v[216:219], v[102:105]
	v_mfma_f32_16x16x32_bf16 v[98:101], v[180:183], v[216:219], v[98:101]
	v_mfma_f32_16x16x32_bf16 v[86:89], v[158:161], v[224:227], v[86:89]
	v_mfma_f32_16x16x32_bf16 v[82:85], v[180:183], v[224:227], v[82:85]
	v_mfma_f32_16x16x32_bf16 v[134:137], v[170:173], v[204:207], v[134:137]
	v_mfma_f32_16x16x32_bf16 v[130:133], v[196:199], v[204:207], v[130:133]
	v_mfma_f32_16x16x32_bf16 v[118:121], v[170:173], v[212:215], v[118:121]
	v_mfma_f32_16x16x32_bf16 v[114:117], v[196:199], v[212:215], v[114:117]
	v_mfma_f32_16x16x32_bf16 v[102:105], v[170:173], v[220:223], v[102:105]
	v_mfma_f32_16x16x32_bf16 v[98:101], v[196:199], v[220:223], v[98:101]
	v_mfma_f32_16x16x32_bf16 v[86:89], v[170:173], v[228:231], v[86:89]
	v_mfma_f32_16x16x32_bf16 v[82:85], v[196:199], v[228:231], v[82:85]
	s_barrier
; #define PG8_STAGE(bufoff, gbase, voff) do { _Pragma("unroll") for (int _i = 0; _i < 2; ++_i) \
;         __builtin_amdgcn_global_load_lds((const unsigned*)((const char*)(gbase) + (voff)[_i]), (PG8_LAS unsigned*)(lds + (bufoff) + ldsw + _i * 8192), 16, 0, 0); } while (0)
; #define PG8_LDA(dst, b, h) do { _Pragma("unroll") for (int m = 0; m < 4; ++m) _Pragma("unroll") for (int k = 0; k < 2; ++k) dst[m][k] = *(const PG8_LAS bf16x8*)(lds + PG8_SA(b, h) + aoff + m * 2048 + k * 1024); } while (0)
; #define PG8_MMA(ai, bj, At, Bt) do { __builtin_amdgcn_s_setprio(1); _Pragma("unroll") for (int m = 0; m < 4; ++m) _Pragma("unroll") for (int n = 0; n < 2; ++n) _Pragma("unroll") for (int k = 0; k < 2; ++k) \
;         acc[ai][bj][m][n] = __builtin_amdgcn_mfma_f32_16x16x32_bf16(Bt[n][k], At[m][k], acc[ai][bj][m][n], 0, 0, 0); __builtin_amdgcn_s_setprio(0); } while (0)
; #define PG8_WAIT_V(n) asm volatile("s_waitcnt vmcnt(" #n ")" ::: "memory")
; #define PG8_WAIT_L(n) asm volatile("s_waitcnt lgkmcnt(" #n ")" ::: "memory")
; #define PG8_BAR __builtin_amdgcn_s_barrier()
; #define PG8_SCHED __builtin_amdgcn_sched_barrier(0)
; template <class Epi, class Sched, bool ALIGN_EPI = false, bool SP2 = false>
; __device__ __forceinline__ void gemm_phase(PG8_LAS unsigned char* lds, const Gemm g, const Sched& S, const Epi& E) {
;     ...
;             PG8_LDA(At, 1, 1); PG8_STAGE(PG8_SB(1, 0), b3, voffB); PG8_STAGE(PG8_SB(1, 1), b3 + hstep, voffB); PG8_STAGE(PG8_SA(1, 0), a3, voffA);
;             PG8_WAIT_V(8); PG8_WAIT_L(0); PG8_BAR; PG8_MMA(1, 0, At, B0); PG8_MMA(1, 1, At, B1); PG8_BAR; PG8_SCHED;
;     ...
;         if constexpr (ALIGN_EPI) { if (wr == 0) PG8_BAR; }
	s_add_i32 s50, s61, s4
	v_lshl_add_u64 v[174:175], v[174:175], 0, s[34:35]
	s_mov_b32 m0, s50
	ds_read_b128 v[200:203], v178 offset:49152
	ds_read_b128 v[204:207], v178 offset:50176
	ds_read_b128 v[208:211], v178 offset:51200
	ds_read_b128 v[212:215], v178 offset:52224
	ds_read_b128 v[216:219], v178 offset:53248
	ds_read_b128 v[220:223], v178 offset:54272
	ds_read_b128 v[224:227], v178 offset:55296
	ds_read_b128 v[228:231], v178 offset:56320
	global_load_lds_dwordx4 v[174:175], off
	s_add_i32 m0, s50, 0x2000
	s_add_u32 s48, s48, 0x40080
	v_lshl_add_u64 v[174:175], v[184:185], 0, s[34:35]
	s_addc_u32 s49, s49, 0
	s_add_i32 s50, s72, s4
	global_load_lds_dwordx4 v[174:175], off
	v_lshl_add_u64 v[174:175], s[48:49], 0, v[148:149]
	s_mov_b32 m0, s50
	s_nop 0
	global_load_lds_dwordx4 v[174:175], off
	v_lshl_add_u64 v[174:175], s[48:49], 0, v[152:153]
	s_add_i32 m0, s50, 0x2000
	s_nop 0
	global_load_lds_dwordx4 v[174:175], off
	v_lshl_add_u64 v[174:175], v[232:233], 0, s[34:35]
	s_mov_b32 m0, s9
	s_nop 0
	global_load_lds_dwordx4 v[174:175], off
	v_lshl_add_u64 v[174:175], v[234:235], 0, s[34:35]
	s_mov_b32 m0, s86
	s_nop 0
	global_load_lds_dwordx4 v[174:175], off
	.p2align	6
	s_waitcnt vmcnt(8)
	s_waitcnt lgkmcnt(0)
	s_barrier
	v_mfma_f32_16x16x32_bf16 v[78:81], v[58:61], v[200:203], v[78:81]
	v_mfma_f32_16x16x32_bf16 v[74:77], v[66:69], v[200:203], v[74:77]
	v_mfma_f32_16x16x32_bf16 v[46:49], v[58:61], v[208:211], v[46:49]
	v_mfma_f32_16x16x32_bf16 v[42:45], v[66:69], v[208:211], v[42:45]
	v_mfma_f32_16x16x32_bf16 v[28:31], v[58:61], v[216:219], v[28:31]
	v_mfma_f32_16x16x32_bf16 v[24:27], v[66:69], v[216:219], v[24:27]
	v_mfma_f32_16x16x32_bf16 v[12:15], v[58:61], v[224:227], v[12:15]
	v_mfma_f32_16x16x32_bf16 v[8:11], v[66:69], v[224:227], v[8:11]
	v_mfma_f32_16x16x32_bf16 v[78:81], v[62:65], v[204:207], v[78:81]
	v_mfma_f32_16x16x32_bf16 v[74:77], v[70:73], v[204:207], v[74:77]
	v_mfma_f32_16x16x32_bf16 v[46:49], v[62:65], v[212:215], v[46:49]
	v_mfma_f32_16x16x32_bf16 v[42:45], v[70:73], v[212:215], v[42:45]
	v_mfma_f32_16x16x32_bf16 v[28:31], v[62:65], v[220:223], v[28:31]
	v_mfma_f32_16x16x32_bf16 v[24:27], v[70:73], v[220:223], v[24:27]
	v_mfma_f32_16x16x32_bf16 v[12:15], v[62:65], v[228:231], v[12:15]
	v_mfma_f32_16x16x32_bf16 v[8:11], v[70:73], v[228:231], v[8:11]
	v_mfma_f32_16x16x32_bf16 v[50:53], v[158:161], v[200:203], v[50:53]
	v_mfma_f32_16x16x32_bf16 v[62:65], v[170:173], v[204:207], v[50:53]
	v_mfma_f32_16x16x32_bf16 v[50:53], v[180:183], v[200:203], v[54:57]
	v_mfma_f32_16x16x32_bf16 v[38:41], v[158:161], v[208:211], v[38:41]
	v_mfma_f32_16x16x32_bf16 v[34:37], v[180:183], v[208:211], v[34:37]
	v_mfma_f32_16x16x32_bf16 v[20:23], v[158:161], v[216:219], v[20:23]
	v_mfma_f32_16x16x32_bf16 v[16:19], v[180:183], v[216:219], v[16:19]
	v_mfma_f32_16x16x32_bf16 v[4:7], v[158:161], v[224:227], v[4:7]
	v_mfma_f32_16x16x32_bf16 v[0:3], v[180:183], v[224:227], v[0:3]
	v_mfma_f32_16x16x32_bf16 v[58:61], v[196:199], v[204:207], v[50:53]
	v_mfma_f32_16x16x32_bf16 v[38:41], v[170:173], v[212:215], v[38:41]
	v_mfma_f32_16x16x32_bf16 v[34:37], v[196:199], v[212:215], v[34:37]
	v_mfma_f32_16x16x32_bf16 v[20:23], v[170:173], v[220:223], v[20:23]
	v_mfma_f32_16x16x32_bf16 v[16:19], v[196:199], v[220:223], v[16:19]
	v_mfma_f32_16x16x32_bf16 v[4:7], v[170:173], v[228:231], v[4:7]
	v_mfma_f32_16x16x32_bf16 v[0:3], v[196:199], v[228:231], v[0:3]
	s_barrier
	s_add_i32 s80, s80, 2
	s_add_u32 vcc_hi, vcc_hi, 0x100
	s_addc_u32 s7, s7, 0
	s_add_u32 s46, s46, 0x100
	s_addc_u32 s47, s47, 0
	s_cmp_gt_u32 s80, 13
	s_cbranch_scc0 .LBB0_145
	v_readlane_b32 s46, v254, 51
	v_readlane_b32 s47, v254, 52
	s_and_b64 vcc, exec, s[46:47]
	s_cbranch_vccz .LBB0_148
	s_barrier

; #define PG8_STAGE(bufoff, gbase, voff) do { _Pragma("unroll") for (int _i = 0; _i < 2; ++_i) \
;         __builtin_amdgcn_global_load_lds((const unsigned*)((const char*)(gbase) + (voff)[_i]), (PG8_LAS unsigned*)(lds + (bufoff) + ldsw + _i * 8192), 16, 0, 0); } while (0)
; #define PG8_LDA(dst, b, h) do { _Pragma("unroll") for (int m = 0; m < 4; ++m) _Pragma("unroll") for (int k = 0; k < 2; ++k) dst[m][k] = *(const PG8_LAS bf16x8*)(lds + PG8_SA(b, h) + aoff + m * 2048 + k * 1024); } while (0)
; #define PG8_LDB(dst, b, h) do { _Pragma("unroll") for (int n = 0; n < 2; ++n) _Pragma("unroll") for (int k = 0; k < 2; ++k) dst[n][k] = *(const PG8_LAS bf16x8*)(lds + PG8_SB(b, h) + boff + n * 2048 + k * 1024); } while (0)
; #define PG8_MMA(ai, bj, At, Bt) do { __builtin_amdgcn_s_setprio(1); _Pragma("unroll") for (int m = 0; m < 4; ++m) _Pragma("unroll") for (int n = 0; n < 2; ++n) _Pragma("unroll") for (int k = 0; k < 2; ++k) \
;         acc[ai][bj][m][n] = __builtin_amdgcn_mfma_f32_16x16x32_bf16(Bt[n][k], At[m][k], acc[ai][bj][m][n], 0, 0, 0); __builtin_amdgcn_s_setprio(0); } while (0)
; #define PG8_WAIT_V(n) asm volatile("s_waitcnt vmcnt(" #n ")" ::: "memory")
; #define PG8_WAIT_L(n) asm volatile("s_waitcnt lgkmcnt(" #n ")" ::: "memory")
; #define PG8_BAR __builtin_amdgcn_s_barrier()
; #define PG8_SCHED __builtin_amdgcn_sched_barrier(0)
; template <class Epi, class Sched, bool ALIGN_EPI = false, bool SP2 = false>
; __device__ __forceinline__ void gemm_phase(PG8_LAS unsigned char* lds, const Gemm g, const Sched& S, const Epi& E) {
;     ...
;             const bool last = (t == nt - 2);
;             const char* a1 = cA + (size_t)(t + 1) * kstep;
;             const char* a2 = last ? nA : cA + (size_t)(t + 2) * kstep; const char* b2 = last ? nB : cB + (size_t)(t + 2) * kstep;
;             const char* a3 = a2 + kstep; const char* b3 = b2 + kstep;
;             if (last && has_next) S.a_ready(nxt);
;             if constexpr (SP2) {
;             PG8_LDB(B0, 0, 0); PG8_LDB(B1, 0, 1); PG8_SCHED; PG8_LDA(At, 0, 0); PG8_STAGE(PG8_SA(1, 1), a1 + hstep, voffA);
;             PG8_WAIT_V(8); PG8_WAIT_L(0); PG8_BAR; PG8_MMA(0, 0, At, B0); PG8_MMA(0, 1, At, B1); PG8_BAR; PG8_SCHED;
;             PG8_LDA(At, 0, 1); PG8_STAGE(PG8_SB(0, 0), b2, voffB); PG8_STAGE(PG8_SB(0, 1), b2 + hstep, voffB); PG8_STAGE(PG8_SA(0, 0), a2, voffA);
.LBB0_369:
	s_add_i32 s92, s46, 2
	s_add_u32 s61, s44, 0x80
	s_addc_u32 s47, s45, 0
	s_add_i32 s72, 0, 0x10000
	s_cmp_eq_u32 s87, s46
	s_cselect_b32 s47, s43, s47
	s_cselect_b32 s46, s42, s61
	v_add_u32_e32 v149, s72, v146
	s_cselect_b32 s95, s77, s91
	s_cselect_b32 s94, s76, s90
	s_add_i32 s61, 0, 0x14000
	ds_read_b128 v[142:145], v149
	ds_read_b128 v[150:153], v149 offset:1024
	ds_read_b128 v[154:157], v149 offset:2048
	ds_read_b128 v[158:161], v149 offset:3072
	v_add_u32_e32 v149, s61, v146
	ds_read_b128 v[170:173], v149
	ds_read_b128 v[174:177], v149 offset:1024
	ds_read_b128 v[178:181], v149 offset:2048
	ds_read_b128 v[182:185], v149 offset:3072
	v_lshl_add_u64 v[228:229], s[44:45], 0, v[140:141]
	s_add_i32 m0, s51, 0xc000
	ds_read_b128 v[196:199], v148
	ds_read_b128 v[200:203], v148 offset:1024
	ds_read_b128 v[204:207], v148 offset:2048
	ds_read_b128 v[208:211], v148 offset:3072
	ds_read_b128 v[212:215], v148 offset:4096
	ds_read_b128 v[216:219], v148 offset:5120
	ds_read_b128 v[220:223], v148 offset:6144
	ds_read_b128 v[224:227], v148 offset:7168
	global_load_lds_dwordx4 v[228:229], off
	v_lshl_add_u64 v[228:229], s[44:45], 0, v[138:139]
	s_add_i32 m0, s51, 0xe000
	s_nop 0
	global_load_lds_dwordx4 v[228:229], off
	.p2align	6
	s_waitcnt vmcnt(8)
	s_waitcnt lgkmcnt(0)
	s_barrier
	v_mfma_f32_16x16x32_bf16 v[126:129], v[142:145], v[196:199], v[126:129]
	v_mfma_f32_16x16x32_bf16 v[122:125], v[154:157], v[196:199], v[122:125]
	v_mfma_f32_16x16x32_bf16 v[110:113], v[142:145], v[204:207], v[110:113]
	v_mfma_f32_16x16x32_bf16 v[106:109], v[154:157], v[204:207], v[106:109]
	v_mfma_f32_16x16x32_bf16 v[94:97], v[142:145], v[212:215], v[94:97]
	v_mfma_f32_16x16x32_bf16 v[90:93], v[154:157], v[212:215], v[90:93]
	v_mfma_f32_16x16x32_bf16 v[78:81], v[142:145], v[220:223], v[78:81]
	v_mfma_f32_16x16x32_bf16 v[74:77], v[154:157], v[220:223], v[74:77]
	v_mfma_f32_16x16x32_bf16 v[126:129], v[150:153], v[200:203], v[126:129]
	v_mfma_f32_16x16x32_bf16 v[122:125], v[158:161], v[200:203], v[122:125]
	v_mfma_f32_16x16x32_bf16 v[110:113], v[150:153], v[208:211], v[110:113]
	v_mfma_f32_16x16x32_bf16 v[106:109], v[158:161], v[208:211], v[106:109]
	v_mfma_f32_16x16x32_bf16 v[94:97], v[150:153], v[216:219], v[94:97]
	v_mfma_f32_16x16x32_bf16 v[90:93], v[158:161], v[216:219], v[90:93]
	v_mfma_f32_16x16x32_bf16 v[78:81], v[150:153], v[224:227], v[78:81]
	v_mfma_f32_16x16x32_bf16 v[74:77], v[158:161], v[224:227], v[74:77]
	v_mfma_f32_16x16x32_bf16 v[118:121], v[170:173], v[196:199], v[118:121]
	v_mfma_f32_16x16x32_bf16 v[114:117], v[178:181], v[196:199], v[114:117]
	v_mfma_f32_16x16x32_bf16 v[102:105], v[170:173], v[204:207], v[102:105]
	v_mfma_f32_16x16x32_bf16 v[98:101], v[178:181], v[204:207], v[98:101]
	v_mfma_f32_16x16x32_bf16 v[86:89], v[170:173], v[212:215], v[86:89]
	v_mfma_f32_16x16x32_bf16 v[82:85], v[178:181], v[212:215], v[82:85]
	v_mfma_f32_16x16x32_bf16 v[70:73], v[170:173], v[220:223], v[70:73]
	v_mfma_f32_16x16x32_bf16 v[66:69], v[178:181], v[220:223], v[66:69]
	v_mfma_f32_16x16x32_bf16 v[118:121], v[174:177], v[200:203], v[118:121]
	v_mfma_f32_16x16x32_bf16 v[114:117], v[182:185], v[200:203], v[114:117]
	v_mfma_f32_16x16x32_bf16 v[102:105], v[174:177], v[208:211], v[102:105]
	v_mfma_f32_16x16x32_bf16 v[98:101], v[182:185], v[208:211], v[98:101]
	v_mfma_f32_16x16x32_bf16 v[86:89], v[174:177], v[216:219], v[86:89]
	v_mfma_f32_16x16x32_bf16 v[82:85], v[182:185], v[216:219], v[82:85]
	v_mfma_f32_16x16x32_bf16 v[70:73], v[174:177], v[224:227], v[70:73]
	v_mfma_f32_16x16x32_bf16 v[66:69], v[182:185], v[224:227], v[66:69]
	s_barrier
	s_add_i32 s72, s72, s50
	v_lshl_add_u64 v[228:229], s[94:95], 0, v[132:133]
	s_mov_b32 m0, s72
	ds_read_b128 v[196:199], v148 offset:16384
	ds_read_b128 v[200:203], v148 offset:17408
	ds_read_b128 v[204:207], v148 offset:18432
	ds_read_b128 v[208:211], v148 offset:19456
	ds_read_b128 v[212:215], v148 offset:20480
	ds_read_b128 v[216:219], v148 offset:21504
	ds_read_b128 v[220:223], v148 offset:22528
	ds_read_b128 v[224:227], v148 offset:23552
	global_load_lds_dwordx4 v[228:229], off
	s_add_i32 m0, s72, 0x2000
	v_lshl_add_u64 v[230:231], s[94:95], 0, v[136:137]
	s_add_u32 s94, s94, s8
	s_addc_u32 s95, s95, 0
	s_add_i32 s61, s61, s50
	global_load_lds_dwordx4 v[230:231], off
	v_lshl_add_u64 v[232:233], s[94:95], 0, v[132:133]
	s_mov_b32 m0, s61
	v_lshl_add_u64 v[234:235], s[94:95], 0, v[136:137]
	global_load_lds_dwordx4 v[232:233], off
	s_add_i32 m0, s61, 0x2000
	v_lshl_add_u64 v[236:237], s[46:47], 0, v[130:131]
	global_load_lds_dwordx4 v[234:235], off
	s_mov_b32 m0, s51
	v_lshl_add_u64 v[238:239], s[46:47], 0, v[134:135]
	global_load_lds_dwordx4 v[236:237], off
	s_mov_b32 m0, s78
	s_nop 0
	global_load_lds_dwordx4 v[238:239], off
	.p2align	6
	s_waitcnt vmcnt(8)
	s_waitcnt lgkmcnt(0)
	s_barrier
; #define PG8_STAGE(bufoff, gbase, voff) do { _Pragma("unroll") for (int _i = 0; _i < 2; ++_i) \
;         __builtin_amdgcn_global_load_lds((const unsigned*)((const char*)(gbase) + (voff)[_i]), (PG8_LAS unsigned*)(lds + (bufoff) + ldsw + _i * 8192), 16, 0, 0); } while (0)
; #define PG8_LDA(dst, b, h) do { _Pragma("unroll") for (int m = 0; m < 4; ++m) _Pragma("unroll") for (int k = 0; k < 2; ++k) dst[m][k] = *(const PG8_LAS bf16x8*)(lds + PG8_SA(b, h) + aoff + m * 2048 + k * 1024); } while (0)
; #define PG8_LDB(dst, b, h) do { _Pragma("unroll") for (int n = 0; n < 2; ++n) _Pragma("unroll") for (int k = 0; k < 2; ++k) dst[n][k] = *(const PG8_LAS bf16x8*)(lds + PG8_SB(b, h) + boff + n * 2048 + k * 1024); } while (0)
; #define PG8_MMA(ai, bj, At, Bt) do { __builtin_amdgcn_s_setprio(1); _Pragma("unroll") for (int m = 0; m < 4; ++m) _Pragma("unroll") for (int n = 0; n < 2; ++n) _Pragma("unroll") for (int k = 0; k < 2; ++k) \
;         acc[ai][bj][m][n] = __builtin_amdgcn_mfma_f32_16x16x32_bf16(Bt[n][k], At[m][k], acc[ai][bj][m][n], 0, 0, 0); __builtin_amdgcn_s_setprio(0); } while (0)
; #define PG8_WAIT_V(n) asm volatile("s_waitcnt vmcnt(" #n ")" ::: "memory")
; #define PG8_WAIT_L(n) asm volatile("s_waitcnt lgkmcnt(" #n ")" ::: "memory")
; #define PG8_BAR __builtin_amdgcn_s_barrier()
; #define PG8_SCHED __builtin_amdgcn_sched_barrier(0)
; template <class Epi, class Sched, bool ALIGN_EPI = false, bool SP2 = false>
; __device__ __forceinline__ void gemm_phase(PG8_LAS unsigned char* lds, const Gemm g, const Sched& S, const Epi& E) {
;     ...
;             PG8_WAIT_V(8); PG8_WAIT_L(0); PG8_BAR; PG8_MMA(1, 0, At, B0); PG8_MMA(1, 1, At, B1); PG8_BAR; PG8_SCHED;
;             PG8_LDB(B0, 1, 0); PG8_LDB(B1, 1, 1); PG8_SCHED; PG8_LDA(At, 1, 0); PG8_STAGE(PG8_SA(0, 1), a2 + hstep, voffA);
;             PG8_WAIT_V(8); PG8_WAIT_L(0); PG8_BAR; PG8_MMA(0, 0, At, B0); PG8_MMA(0, 1, At, B1); PG8_BAR; PG8_SCHED;
	v_mfma_f32_16x16x32_bf16 v[62:65], v[142:145], v[196:199], v[62:65]
	v_mfma_f32_16x16x32_bf16 v[58:61], v[154:157], v[196:199], v[58:61]
	v_mfma_f32_16x16x32_bf16 v[46:49], v[142:145], v[204:207], v[46:49]
	v_mfma_f32_16x16x32_bf16 v[42:45], v[154:157], v[204:207], v[42:45]
	v_mfma_f32_16x16x32_bf16 v[28:31], v[142:145], v[212:215], v[28:31]
	v_mfma_f32_16x16x32_bf16 v[24:27], v[154:157], v[212:215], v[24:27]
	v_mfma_f32_16x16x32_bf16 v[12:15], v[142:145], v[220:223], v[12:15]
	v_mfma_f32_16x16x32_bf16 v[8:11], v[154:157], v[220:223], v[8:11]
	v_mfma_f32_16x16x32_bf16 v[62:65], v[150:153], v[200:203], v[62:65]
	v_mfma_f32_16x16x32_bf16 v[58:61], v[158:161], v[200:203], v[58:61]
	v_mfma_f32_16x16x32_bf16 v[46:49], v[150:153], v[208:211], v[46:49]
	v_mfma_f32_16x16x32_bf16 v[42:45], v[158:161], v[208:211], v[42:45]
	v_mfma_f32_16x16x32_bf16 v[28:31], v[150:153], v[216:219], v[28:31]
	v_mfma_f32_16x16x32_bf16 v[24:27], v[158:161], v[216:219], v[24:27]
	v_mfma_f32_16x16x32_bf16 v[12:15], v[150:153], v[224:227], v[12:15]
	v_mfma_f32_16x16x32_bf16 v[8:11], v[158:161], v[224:227], v[8:11]
	v_mfma_f32_16x16x32_bf16 v[54:57], v[170:173], v[196:199], v[54:57]
	v_mfma_f32_16x16x32_bf16 v[50:53], v[178:181], v[196:199], v[50:53]
	v_mfma_f32_16x16x32_bf16 v[38:41], v[170:173], v[204:207], v[38:41]
	v_mfma_f32_16x16x32_bf16 v[34:37], v[178:181], v[204:207], v[34:37]
	v_mfma_f32_16x16x32_bf16 v[20:23], v[170:173], v[212:215], v[20:23]
	v_mfma_f32_16x16x32_bf16 v[16:19], v[178:181], v[212:215], v[16:19]
	v_mfma_f32_16x16x32_bf16 v[4:7], v[170:173], v[220:223], v[4:7]
	v_mfma_f32_16x16x32_bf16 v[0:3], v[178:181], v[220:223], v[0:3]
	v_mfma_f32_16x16x32_bf16 v[54:57], v[174:177], v[200:203], v[54:57]
	v_mfma_f32_16x16x32_bf16 v[50:53], v[182:185], v[200:203], v[50:53]
	v_mfma_f32_16x16x32_bf16 v[38:41], v[174:177], v[208:211], v[38:41]
	v_mfma_f32_16x16x32_bf16 v[34:37], v[182:185], v[208:211], v[34:37]
	v_mfma_f32_16x16x32_bf16 v[20:23], v[174:177], v[216:219], v[20:23]
	v_mfma_f32_16x16x32_bf16 v[16:19], v[182:185], v[216:219], v[16:19]
	v_mfma_f32_16x16x32_bf16 v[4:7], v[174:177], v[224:227], v[4:7]
	v_mfma_f32_16x16x32_bf16 v[0:3], v[182:185], v[224:227], v[0:3]
	s_barrier
	s_add_i32 s61, 0, 0x18000
	v_add_u32_e32 v149, s61, v146
	s_add_i32 s72, 0, 0x1c000
	ds_read_b128 v[142:145], v149
	ds_read_b128 v[150:153], v149 offset:1024
	ds_read_b128 v[154:157], v149 offset:2048
	ds_read_b128 v[158:161], v149 offset:3072
	v_add_u32_e32 v149, s72, v146
	ds_read_b128 v[170:173], v149
	ds_read_b128 v[174:177], v149 offset:1024
	ds_read_b128 v[178:181], v149 offset:2048
	ds_read_b128 v[182:185], v149 offset:3072
	s_add_u32 s46, s46, s8
	s_addc_u32 s47, s47, 0
	s_mov_b32 m0, s79
	v_lshl_add_u64 v[240:241], s[46:47], 0, v[130:131]
	ds_read_b128 v[196:199], v148 offset:32768
	ds_read_b128 v[200:203], v148 offset:33792
	ds_read_b128 v[204:207], v148 offset:34816
	ds_read_b128 v[208:211], v148 offset:35840
	ds_read_b128 v[212:215], v148 offset:36864
	ds_read_b128 v[216:219], v148 offset:37888
	ds_read_b128 v[220:223], v148 offset:38912
	ds_read_b128 v[224:227], v148 offset:39936
	global_load_lds_dwordx4 v[240:241], off
	v_lshl_add_u64 v[240:241], s[46:47], 0, v[134:135]
	s_mov_b32 m0, s80
	s_nop 0
	global_load_lds_dwordx4 v[240:241], off
	.p2align	6
	s_waitcnt vmcnt(8)
	s_waitcnt lgkmcnt(0)
	s_barrier
	v_mfma_f32_16x16x32_bf16 v[126:129], v[142:145], v[196:199], v[126:129]
	v_mfma_f32_16x16x32_bf16 v[122:125], v[154:157], v[196:199], v[122:125]
	v_mfma_f32_16x16x32_bf16 v[110:113], v[142:145], v[204:207], v[110:113]
	v_mfma_f32_16x16x32_bf16 v[106:109], v[154:157], v[204:207], v[106:109]
	v_mfma_f32_16x16x32_bf16 v[94:97], v[142:145], v[212:215], v[94:97]
	v_mfma_f32_16x16x32_bf16 v[90:93], v[154:157], v[212:215], v[90:93]
	v_mfma_f32_16x16x32_bf16 v[78:81], v[142:145], v[220:223], v[78:81]
	v_mfma_f32_16x16x32_bf16 v[74:77], v[154:157], v[220:223], v[74:77]
	v_mfma_f32_16x16x32_bf16 v[126:129], v[150:153], v[200:203], v[126:129]
	v_mfma_f32_16x16x32_bf16 v[122:125], v[158:161], v[200:203], v[122:125]
	v_mfma_f32_16x16x32_bf16 v[110:113], v[150:153], v[208:211], v[110:113]
	v_mfma_f32_16x16x32_bf16 v[106:109], v[158:161], v[208:211], v[106:109]
	v_mfma_f32_16x16x32_bf16 v[94:97], v[150:153], v[216:219], v[94:97]
	v_mfma_f32_16x16x32_bf16 v[90:93], v[158:161], v[216:219], v[90:93]
	v_mfma_f32_16x16x32_bf16 v[78:81], v[150:153], v[224:227], v[78:81]
	v_mfma_f32_16x16x32_bf16 v[74:77], v[158:161], v[224:227], v[74:77]
	v_mfma_f32_16x16x32_bf16 v[118:121], v[170:173], v[196:199], v[118:121]
	v_mfma_f32_16x16x32_bf16 v[114:117], v[178:181], v[196:199], v[114:117]
	v_mfma_f32_16x16x32_bf16 v[102:105], v[170:173], v[204:207], v[102:105]
	v_mfma_f32_16x16x32_bf16 v[98:101], v[178:181], v[204:207], v[98:101]
	v_mfma_f32_16x16x32_bf16 v[86:89], v[170:173], v[212:215], v[86:89]
	v_mfma_f32_16x16x32_bf16 v[82:85], v[178:181], v[212:215], v[82:85]
	v_mfma_f32_16x16x32_bf16 v[70:73], v[170:173], v[220:223], v[70:73]
	v_mfma_f32_16x16x32_bf16 v[66:69], v[178:181], v[220:223], v[66:69]
	v_mfma_f32_16x16x32_bf16 v[118:121], v[174:177], v[200:203], v[118:121]
	v_mfma_f32_16x16x32_bf16 v[114:117], v[182:185], v[200:203], v[114:117]
	v_mfma_f32_16x16x32_bf16 v[102:105], v[174:177], v[208:211], v[102:105]
	v_mfma_f32_16x16x32_bf16 v[98:101], v[182:185], v[208:211], v[98:101]
	v_mfma_f32_16x16x32_bf16 v[86:89], v[174:177], v[216:219], v[86:89]
	v_mfma_f32_16x16x32_bf16 v[82:85], v[182:185], v[216:219], v[82:85]
	v_mfma_f32_16x16x32_bf16 v[70:73], v[174:177], v[224:227], v[70:73]
	v_mfma_f32_16x16x32_bf16 v[66:69], v[182:185], v[224:227], v[66:69]
	s_barrier
; #define PG8_STAGE(bufoff, gbase, voff) do { _Pragma("unroll") for (int _i = 0; _i < 2; ++_i) \
;         __builtin_amdgcn_global_load_lds((const unsigned*)((const char*)(gbase) + (voff)[_i]), (PG8_LAS unsigned*)(lds + (bufoff) + ldsw + _i * 8192), 16, 0, 0); } while (0)
; #define PG8_LDA(dst, b, h) do { _Pragma("unroll") for (int m = 0; m < 4; ++m) _Pragma("unroll") for (int k = 0; k < 2; ++k) dst[m][k] = *(const PG8_LAS bf16x8*)(lds + PG8_SA(b, h) + aoff + m * 2048 + k * 1024); } while (0)
; #define PG8_MMA(ai, bj, At, Bt) do { __builtin_amdgcn_s_setprio(1); _Pragma("unroll") for (int m = 0; m < 4; ++m) _Pragma("unroll") for (int n = 0; n < 2; ++n) _Pragma("unroll") for (int k = 0; k < 2; ++k) \
;         acc[ai][bj][m][n] = __builtin_amdgcn_mfma_f32_16x16x32_bf16(Bt[n][k], At[m][k], acc[ai][bj][m][n], 0, 0, 0); __builtin_amdgcn_s_setprio(0); } while (0)
; #define PG8_WAIT_V(n) asm volatile("s_waitcnt vmcnt(" #n ")" ::: "memory")
; #define PG8_WAIT_L(n) asm volatile("s_waitcnt lgkmcnt(" #n ")" ::: "memory")
; #define PG8_BAR __builtin_amdgcn_s_barrier()
; #define PG8_SCHED __builtin_amdgcn_sched_barrier(0)
; template <class Epi, class Sched, bool ALIGN_EPI = false, bool SP2 = false>
; __device__ __forceinline__ void gemm_phase(PG8_LAS unsigned char* lds, const Gemm g, const Sched& S, const Epi& E) {
;     ...
;             PG8_LDA(At, 1, 1); PG8_STAGE(PG8_SB(1, 0), b3, voffB); PG8_STAGE(PG8_SB(1, 1), b3 + hstep, voffB); PG8_STAGE(PG8_SA(1, 0), a3, voffA);
;             PG8_WAIT_V(8); PG8_WAIT_L(0); PG8_BAR; PG8_MMA(1, 0, At, B0); PG8_MMA(1, 1, At, B1); PG8_BAR; PG8_SCHED;
;     ...
;         if constexpr (ALIGN_EPI) { if (wr == 0) PG8_BAR; }
	s_add_i32 s46, s61, s50
	v_lshl_add_u64 v[228:229], v[228:229], 0, s[34:35]
	s_mov_b32 m0, s46
	ds_read_b128 v[196:199], v148 offset:49152
	ds_read_b128 v[200:203], v148 offset:50176
	ds_read_b128 v[204:207], v148 offset:51200
	ds_read_b128 v[208:211], v148 offset:52224
	ds_read_b128 v[212:215], v148 offset:53248
	ds_read_b128 v[216:219], v148 offset:54272
	ds_read_b128 v[220:223], v148 offset:55296
	ds_read_b128 v[224:227], v148 offset:56320
	global_load_lds_dwordx4 v[228:229], off
	v_lshl_add_u64 v[228:229], v[230:231], 0, s[34:35]
	s_add_i32 m0, s46, 0x2000
	s_add_i32 s46, s72, s50
	global_load_lds_dwordx4 v[228:229], off
	v_lshl_add_u64 v[228:229], v[232:233], 0, s[34:35]
	s_mov_b32 m0, s46
	s_nop 0
	global_load_lds_dwordx4 v[228:229], off
	v_lshl_add_u64 v[228:229], v[234:235], 0, s[34:35]
	s_add_i32 m0, s46, 0x2000
	s_nop 0
	global_load_lds_dwordx4 v[228:229], off
	v_lshl_add_u64 v[228:229], v[236:237], 0, s[34:35]
	s_mov_b32 m0, s85
	s_nop 0
	global_load_lds_dwordx4 v[228:229], off
	v_lshl_add_u64 v[228:229], v[238:239], 0, s[34:35]
	s_mov_b32 m0, s86
	s_nop 0
	global_load_lds_dwordx4 v[228:229], off
	.p2align	6
	s_waitcnt vmcnt(8)
	s_waitcnt lgkmcnt(0)
	s_barrier
	v_mfma_f32_16x16x32_bf16 v[62:65], v[142:145], v[196:199], v[62:65]
	v_mfma_f32_16x16x32_bf16 v[58:61], v[154:157], v[196:199], v[58:61]
	v_mfma_f32_16x16x32_bf16 v[46:49], v[142:145], v[204:207], v[46:49]
	v_mfma_f32_16x16x32_bf16 v[42:45], v[154:157], v[204:207], v[42:45]
	v_mfma_f32_16x16x32_bf16 v[28:31], v[142:145], v[212:215], v[28:31]
	v_mfma_f32_16x16x32_bf16 v[24:27], v[154:157], v[212:215], v[24:27]
	v_mfma_f32_16x16x32_bf16 v[12:15], v[142:145], v[220:223], v[12:15]
	v_mfma_f32_16x16x32_bf16 v[8:11], v[154:157], v[220:223], v[8:11]
	v_mfma_f32_16x16x32_bf16 v[62:65], v[150:153], v[200:203], v[62:65]
	v_mfma_f32_16x16x32_bf16 v[58:61], v[158:161], v[200:203], v[58:61]
	v_mfma_f32_16x16x32_bf16 v[46:49], v[150:153], v[208:211], v[46:49]
	v_mfma_f32_16x16x32_bf16 v[42:45], v[158:161], v[208:211], v[42:45]
	v_mfma_f32_16x16x32_bf16 v[28:31], v[150:153], v[216:219], v[28:31]
	v_mfma_f32_16x16x32_bf16 v[24:27], v[158:161], v[216:219], v[24:27]
	v_mfma_f32_16x16x32_bf16 v[12:15], v[150:153], v[224:227], v[12:15]
	v_mfma_f32_16x16x32_bf16 v[8:11], v[158:161], v[224:227], v[8:11]
	v_mfma_f32_16x16x32_bf16 v[54:57], v[170:173], v[196:199], v[54:57]
	v_mfma_f32_16x16x32_bf16 v[50:53], v[178:181], v[196:199], v[50:53]
	v_mfma_f32_16x16x32_bf16 v[38:41], v[170:173], v[204:207], v[38:41]
	v_mfma_f32_16x16x32_bf16 v[34:37], v[178:181], v[204:207], v[34:37]
	v_mfma_f32_16x16x32_bf16 v[20:23], v[170:173], v[212:215], v[20:23]
	v_mfma_f32_16x16x32_bf16 v[16:19], v[178:181], v[212:215], v[16:19]
	v_mfma_f32_16x16x32_bf16 v[4:7], v[170:173], v[220:223], v[4:7]
	v_mfma_f32_16x16x32_bf16 v[0:3], v[178:181], v[220:223], v[0:3]
	v_mfma_f32_16x16x32_bf16 v[54:57], v[174:177], v[200:203], v[54:57]
	v_mfma_f32_16x16x32_bf16 v[50:53], v[182:185], v[200:203], v[50:53]
	v_mfma_f32_16x16x32_bf16 v[38:41], v[174:177], v[208:211], v[38:41]
	v_mfma_f32_16x16x32_bf16 v[34:37], v[182:185], v[208:211], v[34:37]
	v_mfma_f32_16x16x32_bf16 v[20:23], v[174:177], v[216:219], v[20:23]
	v_mfma_f32_16x16x32_bf16 v[16:19], v[182:185], v[216:219], v[16:19]
	v_mfma_f32_16x16x32_bf16 v[4:7], v[174:177], v[224:227], v[4:7]
	v_mfma_f32_16x16x32_bf16 v[0:3], v[182:185], v[224:227], v[0:3]
	s_barrier
	s_add_u32 s90, s90, 0x100
	s_addc_u32 s91, s91, 0
	s_add_u32 s44, s44, 0x100
	s_addc_u32 s45, s45, 0
	s_cmp_ge_u32 s92, s82
	s_mov_b32 s46, s92
	s_cbranch_scc0 .LBB0_369
	s_and_b64 vcc, exec, s[40:41]
	s_cbranch_vccz .LBB0_372
	s_barrier

; #define PG8_STAGE(bufoff, gbase, voff) do { _Pragma("unroll") for (int _i = 0; _i < 2; ++_i) \
;         __builtin_amdgcn_global_load_lds((const unsigned*)((const char*)(gbase) + (voff)[_i]), (PG8_LAS unsigned*)(lds + (bufoff) + ldsw + _i * 8192), 16, 0, 0); } while (0)
; #define PG8_LDA(dst, b, h) do { _Pragma("unroll") for (int m = 0; m < 4; ++m) _Pragma("unroll") for (int k = 0; k < 2; ++k) dst[m][k] = *(const PG8_LAS bf16x8*)(lds + PG8_SA(b, h) + aoff + m * 2048 + k * 1024); } while (0)
; #define PG8_LDB(dst, b, h) do { _Pragma("unroll") for (int n = 0; n < 2; ++n) _Pragma("unroll") for (int k = 0; k < 2; ++k) dst[n][k] = *(const PG8_LAS bf16x8*)(lds + PG8_SB(b, h) + boff + n * 2048 + k * 1024); } while (0)
; #define PG8_MMA(ai, bj, At, Bt) do { __builtin_amdgcn_s_setprio(1); _Pragma("unroll") for (int m = 0; m < 4; ++m) _Pragma("unroll") for (int n = 0; n < 2; ++n) _Pragma("unroll") for (int k = 0; k < 2; ++k) \
;         acc[ai][bj][m][n] = __builtin_amdgcn_mfma_f32_16x16x32_bf16(Bt[n][k], At[m][k], acc[ai][bj][m][n], 0, 0, 0); __builtin_amdgcn_s_setprio(0); } while (0)
; #define PG8_WAIT_V(n) asm volatile("s_waitcnt vmcnt(" #n ")" ::: "memory")
; #define PG8_WAIT_L(n) asm volatile("s_waitcnt lgkmcnt(" #n ")" ::: "memory")
; #define PG8_BAR __builtin_amdgcn_s_barrier()
; #define PG8_SCHED __builtin_amdgcn_sched_barrier(0)
; template <class Epi, class Sched, bool ALIGN_EPI = false, bool SP2 = false>
; __device__ __forceinline__ void gemm_phase(PG8_LAS unsigned char* lds, const Gemm g, const Sched& S, const Epi& E) {
;     ...
;             const bool last = (t == nt - 2);
;             const char* a1 = cA + (size_t)(t + 1) * kstep;
;             const char* a2 = last ? nA : cA + (size_t)(t + 2) * kstep; const char* b2 = last ? nB : cB + (size_t)(t + 2) * kstep;
;             const char* a3 = a2 + kstep; const char* b3 = b2 + kstep;
;             if (last && has_next) S.a_ready(nxt);
;             if constexpr (SP2) {
;             PG8_LDB(B0, 0, 0); PG8_LDB(B1, 0, 1); PG8_SCHED; PG8_LDA(At, 0, 0); PG8_STAGE(PG8_SA(1, 1), a1 + hstep, voffA);
;             PG8_WAIT_V(8); PG8_WAIT_L(0); PG8_BAR; PG8_MMA(0, 0, At, B0); PG8_MMA(0, 1, At, B1); PG8_BAR; PG8_SCHED;
;             PG8_LDA(At, 0, 1); PG8_STAGE(PG8_SB(0, 0), b2, voffB); PG8_STAGE(PG8_SB(0, 1), b2 + hstep, voffB); PG8_STAGE(PG8_SA(0, 0), a2, voffA);
.LBB0_411:
	s_add_i32 vcc_lo, s46, 2
	s_add_u32 s38, s44, 0x80
	s_addc_u32 s39, s45, 0
	s_add_i32 vcc_hi, 0, 0x10000
	s_cmp_eq_u32 s92, s46
	s_cselect_b32 s47, s79, s39
	s_cselect_b32 s46, s78, s38
	v_add_u32_e32 v149, vcc_hi, v146
	s_cselect_b32 s39, s81, s49
	s_cselect_b32 s38, s80, s48
	s_add_i32 s61, 0, 0x14000
	ds_read_b128 v[142:145], v149
	ds_read_b128 v[150:153], v149 offset:1024
	ds_read_b128 v[154:157], v149 offset:2048
	ds_read_b128 v[158:161], v149 offset:3072
	v_add_u32_e32 v149, s61, v146
	ds_read_b128 v[170:173], v149
	ds_read_b128 v[174:177], v149 offset:1024
	ds_read_b128 v[178:181], v149 offset:2048
	ds_read_b128 v[182:185], v149 offset:3072
	v_lshl_add_u64 v[228:229], s[44:45], 0, v[140:141]
	s_add_i32 m0, s82, 0xc000
	ds_read_b128 v[196:199], v148
	ds_read_b128 v[200:203], v148 offset:1024
	ds_read_b128 v[204:207], v148 offset:2048
	ds_read_b128 v[208:211], v148 offset:3072
	ds_read_b128 v[212:215], v148 offset:4096
	ds_read_b128 v[216:219], v148 offset:5120
	ds_read_b128 v[220:223], v148 offset:6144
	ds_read_b128 v[224:227], v148 offset:7168
	global_load_lds_dwordx4 v[228:229], off
	v_lshl_add_u64 v[228:229], s[44:45], 0, v[138:139]
	s_add_i32 m0, s82, 0xe000
	s_nop 0
	global_load_lds_dwordx4 v[228:229], off
	.p2align	6
	s_waitcnt vmcnt(8)
	s_waitcnt lgkmcnt(0)
	s_barrier
	v_mfma_f32_16x16x32_bf16 v[126:129], v[142:145], v[196:199], v[126:129]
	v_mfma_f32_16x16x32_bf16 v[122:125], v[154:157], v[196:199], v[122:125]
	v_mfma_f32_16x16x32_bf16 v[110:113], v[142:145], v[204:207], v[110:113]
	v_mfma_f32_16x16x32_bf16 v[106:109], v[154:157], v[204:207], v[106:109]
	v_mfma_f32_16x16x32_bf16 v[94:97], v[142:145], v[212:215], v[94:97]
	v_mfma_f32_16x16x32_bf16 v[90:93], v[154:157], v[212:215], v[90:93]
	v_mfma_f32_16x16x32_bf16 v[78:81], v[142:145], v[220:223], v[78:81]
	v_mfma_f32_16x16x32_bf16 v[74:77], v[154:157], v[220:223], v[74:77]
	v_mfma_f32_16x16x32_bf16 v[126:129], v[150:153], v[200:203], v[126:129]
	v_mfma_f32_16x16x32_bf16 v[122:125], v[158:161], v[200:203], v[122:125]
	v_mfma_f32_16x16x32_bf16 v[110:113], v[150:153], v[208:211], v[110:113]
	v_mfma_f32_16x16x32_bf16 v[106:109], v[158:161], v[208:211], v[106:109]
	v_mfma_f32_16x16x32_bf16 v[94:97], v[150:153], v[216:219], v[94:97]
	v_mfma_f32_16x16x32_bf16 v[90:93], v[158:161], v[216:219], v[90:93]
	v_mfma_f32_16x16x32_bf16 v[78:81], v[150:153], v[224:227], v[78:81]
	v_mfma_f32_16x16x32_bf16 v[74:77], v[158:161], v[224:227], v[74:77]
	v_mfma_f32_16x16x32_bf16 v[118:121], v[170:173], v[196:199], v[118:121]
	v_mfma_f32_16x16x32_bf16 v[114:117], v[178:181], v[196:199], v[114:117]
	v_mfma_f32_16x16x32_bf16 v[102:105], v[170:173], v[204:207], v[102:105]
	v_mfma_f32_16x16x32_bf16 v[98:101], v[178:181], v[204:207], v[98:101]
	v_mfma_f32_16x16x32_bf16 v[86:89], v[170:173], v[212:215], v[86:89]
	v_mfma_f32_16x16x32_bf16 v[82:85], v[178:181], v[212:215], v[82:85]
	v_mfma_f32_16x16x32_bf16 v[70:73], v[170:173], v[220:223], v[70:73]
	v_mfma_f32_16x16x32_bf16 v[66:69], v[178:181], v[220:223], v[66:69]
	v_mfma_f32_16x16x32_bf16 v[118:121], v[174:177], v[200:203], v[118:121]
	v_mfma_f32_16x16x32_bf16 v[114:117], v[182:185], v[200:203], v[114:117]
	v_mfma_f32_16x16x32_bf16 v[102:105], v[174:177], v[208:211], v[102:105]
	v_mfma_f32_16x16x32_bf16 v[98:101], v[182:185], v[208:211], v[98:101]
	v_mfma_f32_16x16x32_bf16 v[86:89], v[174:177], v[216:219], v[86:89]
	v_mfma_f32_16x16x32_bf16 v[82:85], v[182:185], v[216:219], v[82:85]
	v_mfma_f32_16x16x32_bf16 v[70:73], v[174:177], v[224:227], v[70:73]
	v_mfma_f32_16x16x32_bf16 v[66:69], v[182:185], v[224:227], v[66:69]
	s_barrier
	s_add_i32 vcc_hi, vcc_hi, s51
	v_lshl_add_u64 v[228:229], s[38:39], 0, v[132:133]
	s_mov_b32 m0, vcc_hi
	ds_read_b128 v[196:199], v148 offset:16384
	ds_read_b128 v[200:203], v148 offset:17408
	ds_read_b128 v[204:207], v148 offset:18432
	ds_read_b128 v[208:211], v148 offset:19456
	ds_read_b128 v[212:215], v148 offset:20480
	ds_read_b128 v[216:219], v148 offset:21504
	ds_read_b128 v[220:223], v148 offset:22528
	ds_read_b128 v[224:227], v148 offset:23552
	global_load_lds_dwordx4 v[228:229], off
	s_add_i32 m0, vcc_hi, 0x2000
	v_lshl_add_u64 v[230:231], s[38:39], 0, v[136:137]
	s_add_u32 s38, s38, s8
	s_addc_u32 s39, s39, 0
	s_add_i32 s61, s61, s51
	global_load_lds_dwordx4 v[230:231], off
	v_lshl_add_u64 v[232:233], s[38:39], 0, v[132:133]
	s_mov_b32 m0, s61
	v_lshl_add_u64 v[234:235], s[38:39], 0, v[136:137]
	global_load_lds_dwordx4 v[232:233], off
	s_add_i32 m0, s61, 0x2000
	v_lshl_add_u64 v[236:237], s[46:47], 0, v[130:131]
	global_load_lds_dwordx4 v[234:235], off
	s_mov_b32 m0, s82
	v_lshl_add_u64 v[238:239], s[46:47], 0, v[134:135]
	global_load_lds_dwordx4 v[236:237], off
	s_mov_b32 m0, s83
	s_nop 0
	global_load_lds_dwordx4 v[238:239], off
	.p2align	6
	s_waitcnt vmcnt(8)
	s_waitcnt lgkmcnt(0)
	s_barrier
; #define PG8_STAGE(bufoff, gbase, voff) do { _Pragma("unroll") for (int _i = 0; _i < 2; ++_i) \
;         __builtin_amdgcn_global_load_lds((const unsigned*)((const char*)(gbase) + (voff)[_i]), (PG8_LAS unsigned*)(lds + (bufoff) + ldsw + _i * 8192), 16, 0, 0); } while (0)
; #define PG8_LDA(dst, b, h) do { _Pragma("unroll") for (int m = 0; m < 4; ++m) _Pragma("unroll") for (int k = 0; k < 2; ++k) dst[m][k] = *(const PG8_LAS bf16x8*)(lds + PG8_SA(b, h) + aoff + m * 2048 + k * 1024); } while (0)
; #define PG8_LDB(dst, b, h) do { _Pragma("unroll") for (int n = 0; n < 2; ++n) _Pragma("unroll") for (int k = 0; k < 2; ++k) dst[n][k] = *(const PG8_LAS bf16x8*)(lds + PG8_SB(b, h) + boff + n * 2048 + k * 1024); } while (0)
; #define PG8_MMA(ai, bj, At, Bt) do { __builtin_amdgcn_s_setprio(1); _Pragma("unroll") for (int m = 0; m < 4; ++m) _Pragma("unroll") for (int n = 0; n < 2; ++n) _Pragma("unroll") for (int k = 0; k < 2; ++k) \
;         acc[ai][bj][m][n] = __builtin_amdgcn_mfma_f32_16x16x32_bf16(Bt[n][k], At[m][k], acc[ai][bj][m][n], 0, 0, 0); __builtin_amdgcn_s_setprio(0); } while (0)
; #define PG8_WAIT_V(n) asm volatile("s_waitcnt vmcnt(" #n ")" ::: "memory")
; #define PG8_WAIT_L(n) asm volatile("s_waitcnt lgkmcnt(" #n ")" ::: "memory")
; #define PG8_BAR __builtin_amdgcn_s_barrier()
; #define PG8_SCHED __builtin_amdgcn_sched_barrier(0)
; template <class Epi, class Sched, bool ALIGN_EPI = false, bool SP2 = false>
; __device__ __forceinline__ void gemm_phase(PG8_LAS unsigned char* lds, const Gemm g, const Sched& S, const Epi& E) {
;     ...
;             PG8_WAIT_V(8); PG8_WAIT_L(0); PG8_BAR; PG8_MMA(1, 0, At, B0); PG8_MMA(1, 1, At, B1); PG8_BAR; PG8_SCHED;
;             PG8_LDB(B0, 1, 0); PG8_LDB(B1, 1, 1); PG8_SCHED; PG8_LDA(At, 1, 0); PG8_STAGE(PG8_SA(0, 1), a2 + hstep, voffA);
;             PG8_WAIT_V(8); PG8_WAIT_L(0); PG8_BAR; PG8_MMA(0, 0, At, B0); PG8_MMA(0, 1, At, B1); PG8_BAR; PG8_SCHED;
	v_mfma_f32_16x16x32_bf16 v[62:65], v[142:145], v[196:199], v[62:65]
	v_mfma_f32_16x16x32_bf16 v[58:61], v[154:157], v[196:199], v[58:61]
	v_mfma_f32_16x16x32_bf16 v[46:49], v[142:145], v[204:207], v[46:49]
	v_mfma_f32_16x16x32_bf16 v[42:45], v[154:157], v[204:207], v[42:45]
	v_mfma_f32_16x16x32_bf16 v[28:31], v[142:145], v[212:215], v[28:31]
	v_mfma_f32_16x16x32_bf16 v[24:27], v[154:157], v[212:215], v[24:27]
	v_mfma_f32_16x16x32_bf16 v[12:15], v[142:145], v[220:223], v[12:15]
	v_mfma_f32_16x16x32_bf16 v[8:11], v[154:157], v[220:223], v[8:11]
	v_mfma_f32_16x16x32_bf16 v[62:65], v[150:153], v[200:203], v[62:65]
	v_mfma_f32_16x16x32_bf16 v[58:61], v[158:161], v[200:203], v[58:61]
	v_mfma_f32_16x16x32_bf16 v[46:49], v[150:153], v[208:211], v[46:49]
	v_mfma_f32_16x16x32_bf16 v[42:45], v[158:161], v[208:211], v[42:45]
	v_mfma_f32_16x16x32_bf16 v[28:31], v[150:153], v[216:219], v[28:31]
	v_mfma_f32_16x16x32_bf16 v[24:27], v[158:161], v[216:219], v[24:27]
	v_mfma_f32_16x16x32_bf16 v[12:15], v[150:153], v[224:227], v[12:15]
	v_mfma_f32_16x16x32_bf16 v[8:11], v[158:161], v[224:227], v[8:11]
	v_mfma_f32_16x16x32_bf16 v[54:57], v[170:173], v[196:199], v[54:57]
	v_mfma_f32_16x16x32_bf16 v[50:53], v[178:181], v[196:199], v[50:53]
	v_mfma_f32_16x16x32_bf16 v[38:41], v[170:173], v[204:207], v[38:41]
	v_mfma_f32_16x16x32_bf16 v[34:37], v[178:181], v[204:207], v[34:37]
	v_mfma_f32_16x16x32_bf16 v[20:23], v[170:173], v[212:215], v[20:23]
	v_mfma_f32_16x16x32_bf16 v[16:19], v[178:181], v[212:215], v[16:19]
	v_mfma_f32_16x16x32_bf16 v[4:7], v[170:173], v[220:223], v[4:7]
	v_mfma_f32_16x16x32_bf16 v[0:3], v[178:181], v[220:223], v[0:3]
	v_mfma_f32_16x16x32_bf16 v[54:57], v[174:177], v[200:203], v[54:57]
	v_mfma_f32_16x16x32_bf16 v[50:53], v[182:185], v[200:203], v[50:53]
	v_mfma_f32_16x16x32_bf16 v[38:41], v[174:177], v[208:211], v[38:41]
	v_mfma_f32_16x16x32_bf16 v[34:37], v[182:185], v[208:211], v[34:37]
	v_mfma_f32_16x16x32_bf16 v[20:23], v[174:177], v[216:219], v[20:23]
	v_mfma_f32_16x16x32_bf16 v[16:19], v[182:185], v[216:219], v[16:19]
	v_mfma_f32_16x16x32_bf16 v[4:7], v[174:177], v[224:227], v[4:7]
	v_mfma_f32_16x16x32_bf16 v[0:3], v[182:185], v[224:227], v[0:3]
	s_barrier
	s_add_i32 s61, 0, 0x18000
	v_add_u32_e32 v149, s61, v146
	s_add_i32 vcc_hi, 0, 0x1c000
	ds_read_b128 v[142:145], v149
	ds_read_b128 v[150:153], v149 offset:1024
	ds_read_b128 v[154:157], v149 offset:2048
	ds_read_b128 v[158:161], v149 offset:3072
	v_add_u32_e32 v149, vcc_hi, v146
	ds_read_b128 v[170:173], v149
	ds_read_b128 v[174:177], v149 offset:1024
	ds_read_b128 v[178:181], v149 offset:2048
	ds_read_b128 v[182:185], v149 offset:3072
	s_add_u32 s38, s46, s8
	s_addc_u32 s39, s47, 0
	s_mov_b32 m0, s87
	v_lshl_add_u64 v[240:241], s[38:39], 0, v[130:131]
	ds_read_b128 v[196:199], v148 offset:32768
	ds_read_b128 v[200:203], v148 offset:33792
	ds_read_b128 v[204:207], v148 offset:34816
	ds_read_b128 v[208:211], v148 offset:35840
	ds_read_b128 v[212:215], v148 offset:36864
	ds_read_b128 v[216:219], v148 offset:37888
	ds_read_b128 v[220:223], v148 offset:38912
	ds_read_b128 v[224:227], v148 offset:39936
	global_load_lds_dwordx4 v[240:241], off
	v_lshl_add_u64 v[240:241], s[38:39], 0, v[134:135]
	s_mov_b32 m0, s88
	s_nop 0
	global_load_lds_dwordx4 v[240:241], off
	.p2align	6
	s_waitcnt vmcnt(8)
	s_waitcnt lgkmcnt(0)
	s_barrier
	v_mfma_f32_16x16x32_bf16 v[126:129], v[142:145], v[196:199], v[126:129]
	v_mfma_f32_16x16x32_bf16 v[122:125], v[154:157], v[196:199], v[122:125]
	v_mfma_f32_16x16x32_bf16 v[110:113], v[142:145], v[204:207], v[110:113]
	v_mfma_f32_16x16x32_bf16 v[106:109], v[154:157], v[204:207], v[106:109]
	v_mfma_f32_16x16x32_bf16 v[94:97], v[142:145], v[212:215], v[94:97]
	v_mfma_f32_16x16x32_bf16 v[90:93], v[154:157], v[212:215], v[90:93]
	v_mfma_f32_16x16x32_bf16 v[78:81], v[142:145], v[220:223], v[78:81]
	v_mfma_f32_16x16x32_bf16 v[74:77], v[154:157], v[220:223], v[74:77]
	v_mfma_f32_16x16x32_bf16 v[126:129], v[150:153], v[200:203], v[126:129]
	v_mfma_f32_16x16x32_bf16 v[122:125], v[158:161], v[200:203], v[122:125]
	v_mfma_f32_16x16x32_bf16 v[110:113], v[150:153], v[208:211], v[110:113]
	v_mfma_f32_16x16x32_bf16 v[106:109], v[158:161], v[208:211], v[106:109]
	v_mfma_f32_16x16x32_bf16 v[94:97], v[150:153], v[216:219], v[94:97]
	v_mfma_f32_16x16x32_bf16 v[90:93], v[158:161], v[216:219], v[90:93]
	v_mfma_f32_16x16x32_bf16 v[78:81], v[150:153], v[224:227], v[78:81]
	v_mfma_f32_16x16x32_bf16 v[74:77], v[158:161], v[224:227], v[74:77]
	v_mfma_f32_16x16x32_bf16 v[118:121], v[170:173], v[196:199], v[118:121]
	v_mfma_f32_16x16x32_bf16 v[114:117], v[178:181], v[196:199], v[114:117]
	v_mfma_f32_16x16x32_bf16 v[102:105], v[170:173], v[204:207], v[102:105]
	v_mfma_f32_16x16x32_bf16 v[98:101], v[178:181], v[204:207], v[98:101]
	v_mfma_f32_16x16x32_bf16 v[86:89], v[170:173], v[212:215], v[86:89]
	v_mfma_f32_16x16x32_bf16 v[82:85], v[178:181], v[212:215], v[82:85]
	v_mfma_f32_16x16x32_bf16 v[70:73], v[170:173], v[220:223], v[70:73]
	v_mfma_f32_16x16x32_bf16 v[66:69], v[178:181], v[220:223], v[66:69]
	v_mfma_f32_16x16x32_bf16 v[118:121], v[174:177], v[200:203], v[118:121]
	v_mfma_f32_16x16x32_bf16 v[114:117], v[182:185], v[200:203], v[114:117]
	v_mfma_f32_16x16x32_bf16 v[102:105], v[174:177], v[208:211], v[102:105]
	v_mfma_f32_16x16x32_bf16 v[98:101], v[182:185], v[208:211], v[98:101]
	v_mfma_f32_16x16x32_bf16 v[86:89], v[174:177], v[216:219], v[86:89]
	v_mfma_f32_16x16x32_bf16 v[82:85], v[182:185], v[216:219], v[82:85]
	v_mfma_f32_16x16x32_bf16 v[70:73], v[174:177], v[224:227], v[70:73]
	v_mfma_f32_16x16x32_bf16 v[66:69], v[182:185], v[224:227], v[66:69]
	s_barrier
; #define PG8_STAGE(bufoff, gbase, voff) do { _Pragma("unroll") for (int _i = 0; _i < 2; ++_i) \
;         __builtin_amdgcn_global_load_lds((const unsigned*)((const char*)(gbase) + (voff)[_i]), (PG8_LAS unsigned*)(lds + (bufoff) + ldsw + _i * 8192), 16, 0, 0); } while (0)
; #define PG8_LDA(dst, b, h) do { _Pragma("unroll") for (int m = 0; m < 4; ++m) _Pragma("unroll") for (int k = 0; k < 2; ++k) dst[m][k] = *(const PG8_LAS bf16x8*)(lds + PG8_SA(b, h) + aoff + m * 2048 + k * 1024); } while (0)
; #define PG8_MMA(ai, bj, At, Bt) do { __builtin_amdgcn_s_setprio(1); _Pragma("unroll") for (int m = 0; m < 4; ++m) _Pragma("unroll") for (int n = 0; n < 2; ++n) _Pragma("unroll") for (int k = 0; k < 2; ++k) \
;         acc[ai][bj][m][n] = __builtin_amdgcn_mfma_f32_16x16x32_bf16(Bt[n][k], At[m][k], acc[ai][bj][m][n], 0, 0, 0); __builtin_amdgcn_s_setprio(0); } while (0)
; #define PG8_WAIT_V(n) asm volatile("s_waitcnt vmcnt(" #n ")" ::: "memory")
; #define PG8_WAIT_L(n) asm volatile("s_waitcnt lgkmcnt(" #n ")" ::: "memory")
; #define PG8_BAR __builtin_amdgcn_s_barrier()
; #define PG8_SCHED __builtin_amdgcn_sched_barrier(0)
; template <class Epi, class Sched, bool ALIGN_EPI = false, bool SP2 = false>
; __device__ __forceinline__ void gemm_phase(PG8_LAS unsigned char* lds, const Gemm g, const Sched& S, const Epi& E) {
;     ...
;             PG8_LDA(At, 1, 1); PG8_STAGE(PG8_SB(1, 0), b3, voffB); PG8_STAGE(PG8_SB(1, 1), b3 + hstep, voffB); PG8_STAGE(PG8_SA(1, 0), a3, voffA);
;             PG8_WAIT_V(8); PG8_WAIT_L(0); PG8_BAR; PG8_MMA(1, 0, At, B0); PG8_MMA(1, 1, At, B1); PG8_BAR; PG8_SCHED;
;     ...
;         if constexpr (ALIGN_EPI) { if (wr == 0) PG8_BAR; }
	s_add_i32 s38, s61, s51
	v_lshl_add_u64 v[228:229], v[228:229], 0, s[34:35]
	s_mov_b32 m0, s38
	ds_read_b128 v[196:199], v148 offset:49152
	ds_read_b128 v[200:203], v148 offset:50176
	ds_read_b128 v[204:207], v148 offset:51200
	ds_read_b128 v[208:211], v148 offset:52224
	ds_read_b128 v[212:215], v148 offset:53248
	ds_read_b128 v[216:219], v148 offset:54272
	ds_read_b128 v[220:223], v148 offset:55296
	ds_read_b128 v[224:227], v148 offset:56320
	global_load_lds_dwordx4 v[228:229], off
	v_lshl_add_u64 v[228:229], v[230:231], 0, s[34:35]
	s_add_i32 m0, s38, 0x2000
	s_add_i32 s38, vcc_hi, s51
	global_load_lds_dwordx4 v[228:229], off
	v_lshl_add_u64 v[228:229], v[232:233], 0, s[34:35]
	s_mov_b32 m0, s38
	s_nop 0
	global_load_lds_dwordx4 v[228:229], off
	v_lshl_add_u64 v[228:229], v[234:235], 0, s[34:35]
	s_add_i32 m0, s38, 0x2000
	s_nop 0
	global_load_lds_dwordx4 v[228:229], off
	v_lshl_add_u64 v[228:229], v[236:237], 0, s[34:35]
	s_mov_b32 m0, s90
	s_nop 0
	global_load_lds_dwordx4 v[228:229], off
	v_lshl_add_u64 v[228:229], v[238:239], 0, s[34:35]
	s_mov_b32 m0, s91
	s_nop 0
	global_load_lds_dwordx4 v[228:229], off
	.p2align	6
	s_waitcnt vmcnt(8)
	s_waitcnt lgkmcnt(0)
	s_barrier
	v_mfma_f32_16x16x32_bf16 v[62:65], v[142:145], v[196:199], v[62:65]
	v_mfma_f32_16x16x32_bf16 v[58:61], v[154:157], v[196:199], v[58:61]
	v_mfma_f32_16x16x32_bf16 v[46:49], v[142:145], v[204:207], v[46:49]
	v_mfma_f32_16x16x32_bf16 v[42:45], v[154:157], v[204:207], v[42:45]
	v_mfma_f32_16x16x32_bf16 v[28:31], v[142:145], v[212:215], v[28:31]
	v_mfma_f32_16x16x32_bf16 v[24:27], v[154:157], v[212:215], v[24:27]
	v_mfma_f32_16x16x32_bf16 v[12:15], v[142:145], v[220:223], v[12:15]
	v_mfma_f32_16x16x32_bf16 v[8:11], v[154:157], v[220:223], v[8:11]
	v_mfma_f32_16x16x32_bf16 v[62:65], v[150:153], v[200:203], v[62:65]
	v_mfma_f32_16x16x32_bf16 v[58:61], v[158:161], v[200:203], v[58:61]
	v_mfma_f32_16x16x32_bf16 v[46:49], v[150:153], v[208:211], v[46:49]
	v_mfma_f32_16x16x32_bf16 v[42:45], v[158:161], v[208:211], v[42:45]
	v_mfma_f32_16x16x32_bf16 v[28:31], v[150:153], v[216:219], v[28:31]
	v_mfma_f32_16x16x32_bf16 v[24:27], v[158:161], v[216:219], v[24:27]
	v_mfma_f32_16x16x32_bf16 v[12:15], v[150:153], v[224:227], v[12:15]
	v_mfma_f32_16x16x32_bf16 v[8:11], v[158:161], v[224:227], v[8:11]
	v_mfma_f32_16x16x32_bf16 v[54:57], v[170:173], v[196:199], v[54:57]
	v_mfma_f32_16x16x32_bf16 v[50:53], v[178:181], v[196:199], v[50:53]
	v_mfma_f32_16x16x32_bf16 v[38:41], v[170:173], v[204:207], v[38:41]
	v_mfma_f32_16x16x32_bf16 v[34:37], v[178:181], v[204:207], v[34:37]
	v_mfma_f32_16x16x32_bf16 v[20:23], v[170:173], v[212:215], v[20:23]
	v_mfma_f32_16x16x32_bf16 v[16:19], v[178:181], v[212:215], v[16:19]
	v_mfma_f32_16x16x32_bf16 v[4:7], v[170:173], v[220:223], v[4:7]
	v_mfma_f32_16x16x32_bf16 v[0:3], v[178:181], v[220:223], v[0:3]
	v_mfma_f32_16x16x32_bf16 v[54:57], v[174:177], v[200:203], v[54:57]
	v_mfma_f32_16x16x32_bf16 v[50:53], v[182:185], v[200:203], v[50:53]
	v_mfma_f32_16x16x32_bf16 v[38:41], v[174:177], v[208:211], v[38:41]
	v_mfma_f32_16x16x32_bf16 v[34:37], v[182:185], v[208:211], v[34:37]
	v_mfma_f32_16x16x32_bf16 v[20:23], v[174:177], v[216:219], v[20:23]
	v_mfma_f32_16x16x32_bf16 v[16:19], v[182:185], v[216:219], v[16:19]
	v_mfma_f32_16x16x32_bf16 v[4:7], v[174:177], v[224:227], v[4:7]
	v_mfma_f32_16x16x32_bf16 v[0:3], v[182:185], v[224:227], v[0:3]
	s_barrier
	s_add_u32 s48, s48, 0x100
	s_addc_u32 s49, s49, 0
	s_add_u32 s44, s44, 0x100
	s_addc_u32 s45, s45, 0
	s_cmp_ge_u32 vcc_lo, s85
	s_mov_b32 s46, vcc_lo
	s_cbranch_scc0 .LBB0_411
	s_and_b64 vcc, exec, s[42:43]
	s_cbranch_vccz .LBB0_414
	s_barrier

; #define PG8_STAGE(bufoff, gbase, voff) do { _Pragma("unroll") for (int _i = 0; _i < 2; ++_i) \
;         __builtin_amdgcn_global_load_lds((const unsigned*)((const char*)(gbase) + (voff)[_i]), (PG8_LAS unsigned*)(lds + (bufoff) + ldsw + _i * 8192), 16, 0, 0); } while (0)
; #define PG8_LDA(dst, b, h) do { _Pragma("unroll") for (int m = 0; m < 4; ++m) _Pragma("unroll") for (int k = 0; k < 2; ++k) dst[m][k] = *(const PG8_LAS bf16x8*)(lds + PG8_SA(b, h) + aoff + m * 2048 + k * 1024); } while (0)
; #define PG8_LDB(dst, b, h) do { _Pragma("unroll") for (int n = 0; n < 2; ++n) _Pragma("unroll") for (int k = 0; k < 2; ++k) dst[n][k] = *(const PG8_LAS bf16x8*)(lds + PG8_SB(b, h) + boff + n * 2048 + k * 1024); } while (0)
; #define PG8_MMA(ai, bj, At, Bt) do { __builtin_amdgcn_s_setprio(1); _Pragma("unroll") for (int m = 0; m < 4; ++m) _Pragma("unroll") for (int n = 0; n < 2; ++n) _Pragma("unroll") for (int k = 0; k < 2; ++k) \
;         acc[ai][bj][m][n] = __builtin_amdgcn_mfma_f32_16x16x32_bf16(Bt[n][k], At[m][k], acc[ai][bj][m][n], 0, 0, 0); __builtin_amdgcn_s_setprio(0); } while (0)
; #define PG8_WAIT_V(n) asm volatile("s_waitcnt vmcnt(" #n ")" ::: "memory")
; #define PG8_WAIT_L(n) asm volatile("s_waitcnt lgkmcnt(" #n ")" ::: "memory")
; #define PG8_BAR __builtin_amdgcn_s_barrier()
; #define PG8_SCHED __builtin_amdgcn_sched_barrier(0)
; template <class Epi, class Sched, bool ALIGN_EPI = false, bool SP2 = false>
; __device__ __forceinline__ void gemm_phase(PG8_LAS unsigned char* lds, const Gemm g, const Sched& S, const Epi& E) {
;     ...
;             const bool last = (t == nt - 2);
;             const char* a1 = cA + (size_t)(t + 1) * kstep;
;             const char* a2 = last ? nA : cA + (size_t)(t + 2) * kstep; const char* b2 = last ? nB : cB + (size_t)(t + 2) * kstep;
;             const char* a3 = a2 + kstep; const char* b3 = b2 + kstep;
;             if (last && has_next) S.a_ready(nxt);
;             if constexpr (SP2) {
;             PG8_LDB(B0, 0, 0); PG8_LDB(B1, 0, 1); PG8_SCHED; PG8_LDA(At, 0, 0); PG8_STAGE(PG8_SA(1, 1), a1 + hstep, voffA);
;             PG8_WAIT_V(8); PG8_WAIT_L(0); PG8_BAR; PG8_MMA(0, 0, At, B0); PG8_MMA(0, 1, At, B1); PG8_BAR; PG8_SCHED;
;             PG8_LDA(At, 0, 1); PG8_STAGE(PG8_SB(0, 0), b2, voffB); PG8_STAGE(PG8_SB(0, 1), b2 + hstep, voffB); PG8_STAGE(PG8_SA(0, 0), a2, voffA);
.LBB0_444:
	s_add_u32 s38, s48, 0xfffc0080
	s_addc_u32 s39, s49, -1
	s_add_i32 s61, 0, 0x10000
	s_cmp_eq_u32 vcc_hi, 12
	s_cselect_b32 s83, s43, s39
	s_cselect_b32 s82, s45, s38
	v_add_u32_e32 v151, s61, v145
	s_cselect_b32 s51, s41, vcc_lo
	s_cselect_b32 s50, s96, s97
	s_add_i32 s72, 0, 0x14000
	ds_read_b128 v[170:173], v151
	ds_read_b128 v[174:177], v151 offset:1024
	ds_read_b128 v[178:181], v151 offset:2048
	ds_read_b128 v[182:185], v151 offset:3072
	v_add_u32_e32 v151, s72, v145
	ds_read_b128 v[196:199], v151
	ds_read_b128 v[200:203], v151 offset:1024
	ds_read_b128 v[204:207], v151 offset:2048
	ds_read_b128 v[208:211], v151 offset:3072
	v_lshl_add_u64 v[160:161], s[48:49], 0, v[142:143]
	s_add_i32 m0, s47, 0xc000
	ds_read_b128 v[212:215], v149
	ds_read_b128 v[216:219], v149 offset:1024
	ds_read_b128 v[220:223], v149 offset:2048
	ds_read_b128 v[224:227], v149 offset:3072
	ds_read_b128 v[228:231], v149 offset:4096
	ds_read_b128 v[232:235], v149 offset:5120
	ds_read_b128 v[236:239], v149 offset:6144
	ds_read_b128 v[240:243], v149 offset:7168
	global_load_lds_dwordx4 v[160:161], off
	v_lshl_add_u64 v[160:161], s[48:49], 0, v[140:141]
	s_add_i32 m0, s47, 0xe000
	s_nop 0
	global_load_lds_dwordx4 v[160:161], off
	.p2align	6
	s_waitcnt vmcnt(8)
	s_waitcnt lgkmcnt(0)
	s_barrier
	v_mfma_f32_16x16x32_bf16 v[126:129], v[170:173], v[212:215], v[126:129]
	v_mfma_f32_16x16x32_bf16 v[122:125], v[178:181], v[212:215], v[122:125]
	v_mfma_f32_16x16x32_bf16 v[110:113], v[170:173], v[220:223], v[110:113]
	v_mfma_f32_16x16x32_bf16 v[106:109], v[178:181], v[220:223], v[106:109]
	v_mfma_f32_16x16x32_bf16 v[94:97], v[170:173], v[228:231], v[94:97]
	v_mfma_f32_16x16x32_bf16 v[90:93], v[178:181], v[228:231], v[90:93]
	v_mfma_f32_16x16x32_bf16 v[78:81], v[170:173], v[236:239], v[78:81]
	v_mfma_f32_16x16x32_bf16 v[74:77], v[178:181], v[236:239], v[74:77]
	v_mfma_f32_16x16x32_bf16 v[126:129], v[174:177], v[216:219], v[126:129]
	v_mfma_f32_16x16x32_bf16 v[122:125], v[182:185], v[216:219], v[122:125]
	v_mfma_f32_16x16x32_bf16 v[110:113], v[174:177], v[224:227], v[110:113]
	v_mfma_f32_16x16x32_bf16 v[106:109], v[182:185], v[224:227], v[106:109]
	v_mfma_f32_16x16x32_bf16 v[94:97], v[174:177], v[232:235], v[94:97]
	v_mfma_f32_16x16x32_bf16 v[90:93], v[182:185], v[232:235], v[90:93]
	v_mfma_f32_16x16x32_bf16 v[78:81], v[174:177], v[240:243], v[78:81]
	v_mfma_f32_16x16x32_bf16 v[74:77], v[182:185], v[240:243], v[74:77]
	v_mfma_f32_16x16x32_bf16 v[118:121], v[196:199], v[212:215], v[118:121]
	v_mfma_f32_16x16x32_bf16 v[114:117], v[204:207], v[212:215], v[114:117]
	v_mfma_f32_16x16x32_bf16 v[102:105], v[196:199], v[220:223], v[102:105]
	v_mfma_f32_16x16x32_bf16 v[98:101], v[204:207], v[220:223], v[98:101]
	v_mfma_f32_16x16x32_bf16 v[86:89], v[196:199], v[228:231], v[86:89]
	v_mfma_f32_16x16x32_bf16 v[82:85], v[204:207], v[228:231], v[82:85]
	v_mfma_f32_16x16x32_bf16 v[70:73], v[196:199], v[236:239], v[70:73]
	v_mfma_f32_16x16x32_bf16 v[66:69], v[204:207], v[236:239], v[66:69]
	v_mfma_f32_16x16x32_bf16 v[118:121], v[200:203], v[216:219], v[118:121]
	v_mfma_f32_16x16x32_bf16 v[114:117], v[208:211], v[216:219], v[114:117]
	v_mfma_f32_16x16x32_bf16 v[102:105], v[200:203], v[224:227], v[102:105]
	v_mfma_f32_16x16x32_bf16 v[98:101], v[208:211], v[224:227], v[98:101]
	v_mfma_f32_16x16x32_bf16 v[86:89], v[200:203], v[232:235], v[86:89]
	v_mfma_f32_16x16x32_bf16 v[82:85], v[208:211], v[232:235], v[82:85]
	v_mfma_f32_16x16x32_bf16 v[70:73], v[200:203], v[240:243], v[70:73]
	v_mfma_f32_16x16x32_bf16 v[66:69], v[208:211], v[240:243], v[66:69]
	s_barrier
	s_add_i32 s38, s61, s89
	v_lshl_add_u64 v[160:161], s[50:51], 0, v[134:135]
	s_mov_b32 m0, s38
	ds_read_b128 v[212:215], v149 offset:16384
	ds_read_b128 v[216:219], v149 offset:17408
	ds_read_b128 v[220:223], v149 offset:18432
	ds_read_b128 v[224:227], v149 offset:19456
	ds_read_b128 v[228:231], v149 offset:20480
	ds_read_b128 v[232:235], v149 offset:21504
	ds_read_b128 v[236:239], v149 offset:22528
	ds_read_b128 v[240:243], v149 offset:23552
	global_load_lds_dwordx4 v[160:161], off
	s_add_i32 m0, s38, 0x2000
	s_add_u32 s38, s50, 0x40000
	v_lshl_add_u64 v[244:245], s[50:51], 0, v[130:131]
	s_addc_u32 s39, s51, 0
	s_add_i32 s61, s72, s89
	global_load_lds_dwordx4 v[244:245], off
	v_lshl_add_u64 v[246:247], s[38:39], 0, v[134:135]
	s_mov_b32 m0, s61
	v_lshl_add_u64 v[248:249], s[82:83], 0, v[132:133]
	global_load_lds_dwordx4 v[246:247], off
	v_lshl_add_u64 v[246:247], s[38:39], 0, v[130:131]
	s_add_i32 m0, s61, 0x2000
	s_nop 0
	global_load_lds_dwordx4 v[246:247], off
	v_lshl_add_u64 v[246:247], s[82:83], 0, v[136:137]
	s_mov_b32 m0, s47
	s_nop 0
	global_load_lds_dwordx4 v[246:247], off
	s_mov_b32 m0, s90
	s_nop 0
	global_load_lds_dwordx4 v[248:249], off
	.p2align	6
	s_waitcnt vmcnt(8)
	s_waitcnt lgkmcnt(0)
	s_barrier
; #define PG8_STAGE(bufoff, gbase, voff) do { _Pragma("unroll") for (int _i = 0; _i < 2; ++_i) \
;         __builtin_amdgcn_global_load_lds((const unsigned*)((const char*)(gbase) + (voff)[_i]), (PG8_LAS unsigned*)(lds + (bufoff) + ldsw + _i * 8192), 16, 0, 0); } while (0)
; #define PG8_LDA(dst, b, h) do { _Pragma("unroll") for (int m = 0; m < 4; ++m) _Pragma("unroll") for (int k = 0; k < 2; ++k) dst[m][k] = *(const PG8_LAS bf16x8*)(lds + PG8_SA(b, h) + aoff + m * 2048 + k * 1024); } while (0)
; #define PG8_LDB(dst, b, h) do { _Pragma("unroll") for (int n = 0; n < 2; ++n) _Pragma("unroll") for (int k = 0; k < 2; ++k) dst[n][k] = *(const PG8_LAS bf16x8*)(lds + PG8_SB(b, h) + boff + n * 2048 + k * 1024); } while (0)
; #define PG8_MMA(ai, bj, At, Bt) do { __builtin_amdgcn_s_setprio(1); _Pragma("unroll") for (int m = 0; m < 4; ++m) _Pragma("unroll") for (int n = 0; n < 2; ++n) _Pragma("unroll") for (int k = 0; k < 2; ++k) \
;         acc[ai][bj][m][n] = __builtin_amdgcn_mfma_f32_16x16x32_bf16(Bt[n][k], At[m][k], acc[ai][bj][m][n], 0, 0, 0); __builtin_amdgcn_s_setprio(0); } while (0)
; #define PG8_WAIT_V(n) asm volatile("s_waitcnt vmcnt(" #n ")" ::: "memory")
; #define PG8_WAIT_L(n) asm volatile("s_waitcnt lgkmcnt(" #n ")" ::: "memory")
; #define PG8_BAR __builtin_amdgcn_s_barrier()
; #define PG8_SCHED __builtin_amdgcn_sched_barrier(0)
; template <class Epi, class Sched, bool ALIGN_EPI = false, bool SP2 = false>
; __device__ __forceinline__ void gemm_phase(PG8_LAS unsigned char* lds, const Gemm g, const Sched& S, const Epi& E) {
;     ...
;             PG8_WAIT_V(8); PG8_WAIT_L(0); PG8_BAR; PG8_MMA(1, 0, At, B0); PG8_MMA(1, 1, At, B1); PG8_BAR; PG8_SCHED;
;             PG8_LDB(B0, 1, 0); PG8_LDB(B1, 1, 1); PG8_SCHED; PG8_LDA(At, 1, 0); PG8_STAGE(PG8_SA(0, 1), a2 + hstep, voffA);
;             PG8_WAIT_V(8); PG8_WAIT_L(0); PG8_BAR; PG8_MMA(0, 0, At, B0); PG8_MMA(0, 1, At, B1); PG8_BAR; PG8_SCHED;
	v_mfma_f32_16x16x32_bf16 v[62:65], v[170:173], v[212:215], v[62:65]
	v_mfma_f32_16x16x32_bf16 v[58:61], v[178:181], v[212:215], v[58:61]
	v_mfma_f32_16x16x32_bf16 v[46:49], v[170:173], v[220:223], v[46:49]
	v_mfma_f32_16x16x32_bf16 v[42:45], v[178:181], v[220:223], v[42:45]
	v_mfma_f32_16x16x32_bf16 v[28:31], v[170:173], v[228:231], v[28:31]
	v_mfma_f32_16x16x32_bf16 v[24:27], v[178:181], v[228:231], v[24:27]
	v_mfma_f32_16x16x32_bf16 v[12:15], v[170:173], v[236:239], v[12:15]
	v_mfma_f32_16x16x32_bf16 v[8:11], v[178:181], v[236:239], v[8:11]
	v_mfma_f32_16x16x32_bf16 v[62:65], v[174:177], v[216:219], v[62:65]
	v_mfma_f32_16x16x32_bf16 v[58:61], v[182:185], v[216:219], v[58:61]
	v_mfma_f32_16x16x32_bf16 v[46:49], v[174:177], v[224:227], v[46:49]
	v_mfma_f32_16x16x32_bf16 v[42:45], v[182:185], v[224:227], v[42:45]
	v_mfma_f32_16x16x32_bf16 v[28:31], v[174:177], v[232:235], v[28:31]
	v_mfma_f32_16x16x32_bf16 v[24:27], v[182:185], v[232:235], v[24:27]
	v_mfma_f32_16x16x32_bf16 v[12:15], v[174:177], v[240:243], v[12:15]
	v_mfma_f32_16x16x32_bf16 v[8:11], v[182:185], v[240:243], v[8:11]
	v_mfma_f32_16x16x32_bf16 v[54:57], v[196:199], v[212:215], v[54:57]
	v_mfma_f32_16x16x32_bf16 v[50:53], v[204:207], v[212:215], v[50:53]
	v_mfma_f32_16x16x32_bf16 v[38:41], v[196:199], v[220:223], v[38:41]
	v_mfma_f32_16x16x32_bf16 v[34:37], v[204:207], v[220:223], v[34:37]
	v_mfma_f32_16x16x32_bf16 v[20:23], v[196:199], v[228:231], v[20:23]
	v_mfma_f32_16x16x32_bf16 v[16:19], v[204:207], v[228:231], v[16:19]
	v_mfma_f32_16x16x32_bf16 v[4:7], v[196:199], v[236:239], v[4:7]
	v_mfma_f32_16x16x32_bf16 v[0:3], v[204:207], v[236:239], v[0:3]
	v_mfma_f32_16x16x32_bf16 v[54:57], v[200:203], v[216:219], v[54:57]
	v_mfma_f32_16x16x32_bf16 v[50:53], v[208:211], v[216:219], v[50:53]
	v_mfma_f32_16x16x32_bf16 v[38:41], v[200:203], v[224:227], v[38:41]
	v_mfma_f32_16x16x32_bf16 v[34:37], v[208:211], v[224:227], v[34:37]
	v_mfma_f32_16x16x32_bf16 v[20:23], v[200:203], v[232:235], v[20:23]
	v_mfma_f32_16x16x32_bf16 v[16:19], v[208:211], v[232:235], v[16:19]
	v_mfma_f32_16x16x32_bf16 v[4:7], v[200:203], v[240:243], v[4:7]
	v_mfma_f32_16x16x32_bf16 v[0:3], v[208:211], v[240:243], v[0:3]
	s_barrier
	s_add_i32 s61, 0, 0x18000
	v_add_u32_e32 v151, s61, v145
	s_add_i32 s72, 0, 0x1c000
	ds_read_b128 v[170:173], v151
	ds_read_b128 v[174:177], v151 offset:1024
	ds_read_b128 v[178:181], v151 offset:2048
	ds_read_b128 v[182:185], v151 offset:3072
	v_add_u32_e32 v151, s72, v145
	ds_read_b128 v[196:199], v151
	ds_read_b128 v[200:203], v151 offset:1024
	ds_read_b128 v[204:207], v151 offset:2048
	ds_read_b128 v[208:211], v151 offset:3072
	s_add_u32 s38, s82, 0x40000
	s_addc_u32 s39, s83, 0
	s_mov_b32 m0, s91
	v_lshl_add_u64 v[250:251], s[38:39], 0, v[136:137]
	ds_read_b128 v[212:215], v149 offset:32768
	ds_read_b128 v[216:219], v149 offset:33792
	ds_read_b128 v[220:223], v149 offset:34816
	ds_read_b128 v[224:227], v149 offset:35840
	ds_read_b128 v[228:231], v149 offset:36864
	ds_read_b128 v[232:235], v149 offset:37888
	ds_read_b128 v[236:239], v149 offset:38912
	ds_read_b128 v[240:243], v149 offset:39936
	global_load_lds_dwordx4 v[250:251], off
	v_lshl_add_u64 v[250:251], s[38:39], 0, v[132:133]
	s_mov_b32 m0, s92
	s_nop 0
	global_load_lds_dwordx4 v[250:251], off
	.p2align	6
	s_waitcnt vmcnt(8)
	s_waitcnt lgkmcnt(0)
	s_barrier
	v_mfma_f32_16x16x32_bf16 v[126:129], v[170:173], v[212:215], v[126:129]
	v_mfma_f32_16x16x32_bf16 v[122:125], v[178:181], v[212:215], v[122:125]
	v_mfma_f32_16x16x32_bf16 v[110:113], v[170:173], v[220:223], v[110:113]
	v_mfma_f32_16x16x32_bf16 v[106:109], v[178:181], v[220:223], v[106:109]
	v_mfma_f32_16x16x32_bf16 v[94:97], v[170:173], v[228:231], v[94:97]
	v_mfma_f32_16x16x32_bf16 v[90:93], v[178:181], v[228:231], v[90:93]
	v_mfma_f32_16x16x32_bf16 v[78:81], v[170:173], v[236:239], v[78:81]
	v_mfma_f32_16x16x32_bf16 v[74:77], v[178:181], v[236:239], v[74:77]
	v_mfma_f32_16x16x32_bf16 v[126:129], v[174:177], v[216:219], v[126:129]
	v_mfma_f32_16x16x32_bf16 v[122:125], v[182:185], v[216:219], v[122:125]
	v_mfma_f32_16x16x32_bf16 v[110:113], v[174:177], v[224:227], v[110:113]
	v_mfma_f32_16x16x32_bf16 v[106:109], v[182:185], v[224:227], v[106:109]
	v_mfma_f32_16x16x32_bf16 v[94:97], v[174:177], v[232:235], v[94:97]
	v_mfma_f32_16x16x32_bf16 v[90:93], v[182:185], v[232:235], v[90:93]
	v_mfma_f32_16x16x32_bf16 v[78:81], v[174:177], v[240:243], v[78:81]
	v_mfma_f32_16x16x32_bf16 v[74:77], v[182:185], v[240:243], v[74:77]
	v_mfma_f32_16x16x32_bf16 v[118:121], v[196:199], v[212:215], v[118:121]
	v_mfma_f32_16x16x32_bf16 v[114:117], v[204:207], v[212:215], v[114:117]
	v_mfma_f32_16x16x32_bf16 v[102:105], v[196:199], v[220:223], v[102:105]
	v_mfma_f32_16x16x32_bf16 v[98:101], v[204:207], v[220:223], v[98:101]
	v_mfma_f32_16x16x32_bf16 v[86:89], v[196:199], v[228:231], v[86:89]
	v_mfma_f32_16x16x32_bf16 v[82:85], v[204:207], v[228:231], v[82:85]
	v_mfma_f32_16x16x32_bf16 v[70:73], v[196:199], v[236:239], v[70:73]
	v_mfma_f32_16x16x32_bf16 v[66:69], v[204:207], v[236:239], v[66:69]
	v_mfma_f32_16x16x32_bf16 v[118:121], v[200:203], v[216:219], v[118:121]
	v_mfma_f32_16x16x32_bf16 v[114:117], v[208:211], v[216:219], v[114:117]
	v_mfma_f32_16x16x32_bf16 v[102:105], v[200:203], v[224:227], v[102:105]
	v_mfma_f32_16x16x32_bf16 v[98:101], v[208:211], v[224:227], v[98:101]
	v_mfma_f32_16x16x32_bf16 v[86:89], v[200:203], v[232:235], v[86:89]
	v_mfma_f32_16x16x32_bf16 v[82:85], v[208:211], v[232:235], v[82:85]
	v_mfma_f32_16x16x32_bf16 v[70:73], v[200:203], v[240:243], v[70:73]
	v_mfma_f32_16x16x32_bf16 v[66:69], v[208:211], v[240:243], v[66:69]
	s_barrier
; #define PG8_STAGE(bufoff, gbase, voff) do { _Pragma("unroll") for (int _i = 0; _i < 2; ++_i) \
;         __builtin_amdgcn_global_load_lds((const unsigned*)((const char*)(gbase) + (voff)[_i]), (PG8_LAS unsigned*)(lds + (bufoff) + ldsw + _i * 8192), 16, 0, 0); } while (0)
; #define PG8_LDA(dst, b, h) do { _Pragma("unroll") for (int m = 0; m < 4; ++m) _Pragma("unroll") for (int k = 0; k < 2; ++k) dst[m][k] = *(const PG8_LAS bf16x8*)(lds + PG8_SA(b, h) + aoff + m * 2048 + k * 1024); } while (0)
; #define PG8_MMA(ai, bj, At, Bt) do { __builtin_amdgcn_s_setprio(1); _Pragma("unroll") for (int m = 0; m < 4; ++m) _Pragma("unroll") for (int n = 0; n < 2; ++n) _Pragma("unroll") for (int k = 0; k < 2; ++k) \
;         acc[ai][bj][m][n] = __builtin_amdgcn_mfma_f32_16x16x32_bf16(Bt[n][k], At[m][k], acc[ai][bj][m][n], 0, 0, 0); __builtin_amdgcn_s_setprio(0); } while (0)
; #define PG8_WAIT_V(n) asm volatile("s_waitcnt vmcnt(" #n ")" ::: "memory")
; #define PG8_WAIT_L(n) asm volatile("s_waitcnt lgkmcnt(" #n ")" ::: "memory")
; #define PG8_BAR __builtin_amdgcn_s_barrier()
; #define PG8_SCHED __builtin_amdgcn_sched_barrier(0)
; template <class Epi, class Sched, bool ALIGN_EPI = false, bool SP2 = false>
; __device__ __forceinline__ void gemm_phase(PG8_LAS unsigned char* lds, const Gemm g, const Sched& S, const Epi& E) {
;     ...
;             PG8_LDA(At, 1, 1); PG8_STAGE(PG8_SB(1, 0), b3, voffB); PG8_STAGE(PG8_SB(1, 1), b3 + hstep, voffB); PG8_STAGE(PG8_SA(1, 0), a3, voffA);
;             PG8_WAIT_V(8); PG8_WAIT_L(0); PG8_BAR; PG8_MMA(1, 0, At, B0); PG8_MMA(1, 1, At, B1); PG8_BAR; PG8_SCHED;
;     ...
;         if constexpr (ALIGN_EPI) { if (wr == 0) PG8_BAR; }
	s_add_i32 s38, s61, s89
	v_lshl_add_u64 v[160:161], v[160:161], 0, s[34:35]
	s_mov_b32 m0, s38
	ds_read_b128 v[212:215], v149 offset:49152
	ds_read_b128 v[216:219], v149 offset:50176
	ds_read_b128 v[220:223], v149 offset:51200
	ds_read_b128 v[224:227], v149 offset:52224
	ds_read_b128 v[228:231], v149 offset:53248
	ds_read_b128 v[232:235], v149 offset:54272
	ds_read_b128 v[236:239], v149 offset:55296
	ds_read_b128 v[240:243], v149 offset:56320
	global_load_lds_dwordx4 v[160:161], off
	s_add_i32 m0, s38, 0x2000
	s_add_u32 s38, s50, 0x40080
	v_lshl_add_u64 v[160:161], v[244:245], 0, s[34:35]
	s_addc_u32 s39, s51, 0
	s_add_i32 s50, s72, s89
	global_load_lds_dwordx4 v[160:161], off
	v_lshl_add_u64 v[160:161], s[38:39], 0, v[134:135]
	s_mov_b32 m0, s50
	s_nop 0
	global_load_lds_dwordx4 v[160:161], off
	v_lshl_add_u64 v[160:161], s[38:39], 0, v[130:131]
	s_add_i32 m0, s50, 0x2000
	s_nop 0
	global_load_lds_dwordx4 v[160:161], off
	v_lshl_add_u64 v[160:161], v[246:247], 0, s[34:35]
	s_mov_b32 m0, s93
	s_nop 0
	global_load_lds_dwordx4 v[160:161], off
	v_lshl_add_u64 v[160:161], v[248:249], 0, s[34:35]
	s_mov_b32 m0, s94
	s_nop 0
	global_load_lds_dwordx4 v[160:161], off
	.p2align	6
	s_waitcnt vmcnt(8)
	s_waitcnt lgkmcnt(0)
	s_barrier
	v_mfma_f32_16x16x32_bf16 v[62:65], v[170:173], v[212:215], v[62:65]
	v_mfma_f32_16x16x32_bf16 v[58:61], v[178:181], v[212:215], v[58:61]
	v_mfma_f32_16x16x32_bf16 v[46:49], v[170:173], v[220:223], v[46:49]
	v_mfma_f32_16x16x32_bf16 v[42:45], v[178:181], v[220:223], v[42:45]
	v_mfma_f32_16x16x32_bf16 v[28:31], v[170:173], v[228:231], v[28:31]
	v_mfma_f32_16x16x32_bf16 v[24:27], v[178:181], v[228:231], v[24:27]
	v_mfma_f32_16x16x32_bf16 v[12:15], v[170:173], v[236:239], v[12:15]
	v_mfma_f32_16x16x32_bf16 v[8:11], v[178:181], v[236:239], v[8:11]
	v_mfma_f32_16x16x32_bf16 v[62:65], v[174:177], v[216:219], v[62:65]
	v_mfma_f32_16x16x32_bf16 v[58:61], v[182:185], v[216:219], v[58:61]
	v_mfma_f32_16x16x32_bf16 v[46:49], v[174:177], v[224:227], v[46:49]
	v_mfma_f32_16x16x32_bf16 v[42:45], v[182:185], v[224:227], v[42:45]
	v_mfma_f32_16x16x32_bf16 v[28:31], v[174:177], v[232:235], v[28:31]
	v_mfma_f32_16x16x32_bf16 v[24:27], v[182:185], v[232:235], v[24:27]
	v_mfma_f32_16x16x32_bf16 v[12:15], v[174:177], v[240:243], v[12:15]
	v_mfma_f32_16x16x32_bf16 v[8:11], v[182:185], v[240:243], v[8:11]
	v_mfma_f32_16x16x32_bf16 v[54:57], v[196:199], v[212:215], v[54:57]
	v_mfma_f32_16x16x32_bf16 v[50:53], v[204:207], v[212:215], v[50:53]
	v_mfma_f32_16x16x32_bf16 v[38:41], v[196:199], v[220:223], v[38:41]
	v_mfma_f32_16x16x32_bf16 v[34:37], v[204:207], v[220:223], v[34:37]
	v_mfma_f32_16x16x32_bf16 v[20:23], v[196:199], v[228:231], v[20:23]
	v_mfma_f32_16x16x32_bf16 v[16:19], v[204:207], v[228:231], v[16:19]
	v_mfma_f32_16x16x32_bf16 v[4:7], v[196:199], v[236:239], v[4:7]
	v_mfma_f32_16x16x32_bf16 v[0:3], v[204:207], v[236:239], v[0:3]
	v_mfma_f32_16x16x32_bf16 v[54:57], v[200:203], v[216:219], v[54:57]
	v_mfma_f32_16x16x32_bf16 v[50:53], v[208:211], v[216:219], v[50:53]
	v_mfma_f32_16x16x32_bf16 v[38:41], v[200:203], v[224:227], v[38:41]
	v_mfma_f32_16x16x32_bf16 v[34:37], v[208:211], v[224:227], v[34:37]
	v_mfma_f32_16x16x32_bf16 v[20:23], v[200:203], v[232:235], v[20:23]
	v_mfma_f32_16x16x32_bf16 v[16:19], v[208:211], v[232:235], v[16:19]
	v_mfma_f32_16x16x32_bf16 v[4:7], v[200:203], v[240:243], v[4:7]
	v_mfma_f32_16x16x32_bf16 v[0:3], v[208:211], v[240:243], v[0:3]
	s_barrier
	s_add_i32 vcc_hi, vcc_hi, 2
	s_add_u32 s97, s97, 0x100
	s_addc_u32 vcc_lo, vcc_lo, 0
	s_add_u32 s48, s48, 0x100
	s_addc_u32 s49, s49, 0
	s_cmp_gt_u32 vcc_hi, 13
	s_cbranch_scc0 .LBB0_444
	s_and_b64 vcc, exec, s[4:5]
	s_cbranch_vccz .LBB0_447
	s_barrier

; #define PG8_STAGE(bufoff, gbase, voff) do { _Pragma("unroll") for (int _i = 0; _i < 2; ++_i) \
;         __builtin_amdgcn_global_load_lds((const unsigned*)((const char*)(gbase) + (voff)[_i]), (PG8_LAS unsigned*)(lds + (bufoff) + ldsw + _i * 8192), 16, 0, 0); } while (0)
; #define PG8_LDA(dst, b, h) do { _Pragma("unroll") for (int m = 0; m < 4; ++m) _Pragma("unroll") for (int k = 0; k < 2; ++k) dst[m][k] = *(const PG8_LAS bf16x8*)(lds + PG8_SA(b, h) + aoff + m * 2048 + k * 1024); } while (0)
; #define PG8_LDB(dst, b, h) do { _Pragma("unroll") for (int n = 0; n < 2; ++n) _Pragma("unroll") for (int k = 0; k < 2; ++k) dst[n][k] = *(const PG8_LAS bf16x8*)(lds + PG8_SB(b, h) + boff + n * 2048 + k * 1024); } while (0)
; #define PG8_MMA(ai, bj, At, Bt) do { __builtin_amdgcn_s_setprio(1); _Pragma("unroll") for (int m = 0; m < 4; ++m) _Pragma("unroll") for (int n = 0; n < 2; ++n) _Pragma("unroll") for (int k = 0; k < 2; ++k) \
;         acc[ai][bj][m][n] = __builtin_amdgcn_mfma_f32_16x16x32_bf16(Bt[n][k], At[m][k], acc[ai][bj][m][n], 0, 0, 0); __builtin_amdgcn_s_setprio(0); } while (0)
; #define PG8_WAIT_V(n) asm volatile("s_waitcnt vmcnt(" #n ")" ::: "memory")
; #define PG8_WAIT_L(n) asm volatile("s_waitcnt lgkmcnt(" #n ")" ::: "memory")
; #define PG8_BAR __builtin_amdgcn_s_barrier()
; #define PG8_SCHED __builtin_amdgcn_sched_barrier(0)
; template <class Epi, class Sched, bool ALIGN_EPI = false, bool SP2 = false>
; __device__ __forceinline__ void gemm_phase(PG8_LAS unsigned char* lds, const Gemm g, const Sched& S, const Epi& E) {
;     ...
;             const bool last = (t == nt - 2);
;             const char* a1 = cA + (size_t)(t + 1) * kstep;
;             const char* a2 = last ? nA : cA + (size_t)(t + 2) * kstep; const char* b2 = last ? nB : cB + (size_t)(t + 2) * kstep;
;             const char* a3 = a2 + kstep; const char* b3 = b2 + kstep;
;             if (last && has_next) S.a_ready(nxt);
;             if constexpr (SP2) {
;             PG8_LDB(B0, 0, 0); PG8_LDB(B1, 0, 1); PG8_SCHED; PG8_LDA(At, 0, 0); PG8_STAGE(PG8_SA(1, 1), a1 + hstep, voffA);
;             PG8_WAIT_V(8); PG8_WAIT_L(0); PG8_BAR; PG8_MMA(0, 0, At, B0); PG8_MMA(0, 1, At, B1); PG8_BAR; PG8_SCHED;
;             PG8_LDA(At, 0, 1); PG8_STAGE(PG8_SB(0, 0), b2, voffB); PG8_STAGE(PG8_SB(0, 1), b2 + hstep, voffB); PG8_STAGE(PG8_SA(0, 0), a2, voffA);
.LBB0_546:
	s_add_i32 s48, s46, 2
	s_add_u32 s49, s44, 0x80
	s_addc_u32 s47, s45, 0
	s_add_i32 s61, 0, 0x10000
	s_cmp_eq_u32 s87, s46
	s_cselect_b32 s47, s43, s47
	s_cselect_b32 s46, s42, s49
	v_add_u32_e32 v149, s61, v146
	s_cselect_b32 s93, s77, s9
	s_cselect_b32 s92, s76, s0
	s_add_i32 s49, 0, 0x14000
	ds_read_b128 v[142:145], v149
	ds_read_b128 v[150:153], v149 offset:1024
	ds_read_b128 v[154:157], v149 offset:2048
	ds_read_b128 v[158:161], v149 offset:3072
	v_add_u32_e32 v149, s49, v146
	ds_read_b128 v[170:173], v149
	ds_read_b128 v[174:177], v149 offset:1024
	ds_read_b128 v[178:181], v149 offset:2048
	ds_read_b128 v[182:185], v149 offset:3072
	v_lshl_add_u64 v[228:229], s[44:45], 0, v[140:141]
	s_add_i32 m0, s78, 0xc000
	ds_read_b128 v[196:199], v148
	ds_read_b128 v[200:203], v148 offset:1024
	ds_read_b128 v[204:207], v148 offset:2048
	ds_read_b128 v[208:211], v148 offset:3072
	ds_read_b128 v[212:215], v148 offset:4096
	ds_read_b128 v[216:219], v148 offset:5120
	ds_read_b128 v[220:223], v148 offset:6144
	ds_read_b128 v[224:227], v148 offset:7168
	global_load_lds_dwordx4 v[228:229], off
	v_lshl_add_u64 v[228:229], s[44:45], 0, v[138:139]
	s_add_i32 m0, s78, 0xe000
	s_nop 0
	global_load_lds_dwordx4 v[228:229], off
	.p2align	6
	s_waitcnt vmcnt(8)
	s_waitcnt lgkmcnt(0)
	s_barrier
	v_mfma_f32_16x16x32_bf16 v[126:129], v[142:145], v[196:199], v[126:129]
	v_mfma_f32_16x16x32_bf16 v[122:125], v[154:157], v[196:199], v[122:125]
	v_mfma_f32_16x16x32_bf16 v[110:113], v[142:145], v[204:207], v[110:113]
	v_mfma_f32_16x16x32_bf16 v[106:109], v[154:157], v[204:207], v[106:109]
	v_mfma_f32_16x16x32_bf16 v[94:97], v[142:145], v[212:215], v[94:97]
	v_mfma_f32_16x16x32_bf16 v[90:93], v[154:157], v[212:215], v[90:93]
	v_mfma_f32_16x16x32_bf16 v[78:81], v[142:145], v[220:223], v[78:81]
	v_mfma_f32_16x16x32_bf16 v[74:77], v[154:157], v[220:223], v[74:77]
	v_mfma_f32_16x16x32_bf16 v[126:129], v[150:153], v[200:203], v[126:129]
	v_mfma_f32_16x16x32_bf16 v[122:125], v[158:161], v[200:203], v[122:125]
	v_mfma_f32_16x16x32_bf16 v[110:113], v[150:153], v[208:211], v[110:113]
	v_mfma_f32_16x16x32_bf16 v[106:109], v[158:161], v[208:211], v[106:109]
	v_mfma_f32_16x16x32_bf16 v[94:97], v[150:153], v[216:219], v[94:97]
	v_mfma_f32_16x16x32_bf16 v[90:93], v[158:161], v[216:219], v[90:93]
	v_mfma_f32_16x16x32_bf16 v[78:81], v[150:153], v[224:227], v[78:81]
	v_mfma_f32_16x16x32_bf16 v[74:77], v[158:161], v[224:227], v[74:77]
	v_mfma_f32_16x16x32_bf16 v[118:121], v[170:173], v[196:199], v[118:121]
	v_mfma_f32_16x16x32_bf16 v[114:117], v[178:181], v[196:199], v[114:117]
	v_mfma_f32_16x16x32_bf16 v[102:105], v[170:173], v[204:207], v[102:105]
	v_mfma_f32_16x16x32_bf16 v[98:101], v[178:181], v[204:207], v[98:101]
	v_mfma_f32_16x16x32_bf16 v[86:89], v[170:173], v[212:215], v[86:89]
	v_mfma_f32_16x16x32_bf16 v[82:85], v[178:181], v[212:215], v[82:85]
	v_mfma_f32_16x16x32_bf16 v[70:73], v[170:173], v[220:223], v[70:73]
	v_mfma_f32_16x16x32_bf16 v[66:69], v[178:181], v[220:223], v[66:69]
	v_mfma_f32_16x16x32_bf16 v[118:121], v[174:177], v[200:203], v[118:121]
	v_mfma_f32_16x16x32_bf16 v[114:117], v[182:185], v[200:203], v[114:117]
	v_mfma_f32_16x16x32_bf16 v[102:105], v[174:177], v[208:211], v[102:105]
	v_mfma_f32_16x16x32_bf16 v[98:101], v[182:185], v[208:211], v[98:101]
	v_mfma_f32_16x16x32_bf16 v[86:89], v[174:177], v[216:219], v[86:89]
	v_mfma_f32_16x16x32_bf16 v[82:85], v[182:185], v[216:219], v[82:85]
	v_mfma_f32_16x16x32_bf16 v[70:73], v[174:177], v[224:227], v[70:73]
	v_mfma_f32_16x16x32_bf16 v[66:69], v[182:185], v[224:227], v[66:69]
	s_barrier
	s_add_i32 s61, s61, s51
	v_lshl_add_u64 v[228:229], s[92:93], 0, v[132:133]
	s_mov_b32 m0, s61
	ds_read_b128 v[196:199], v148 offset:16384
	ds_read_b128 v[200:203], v148 offset:17408
	ds_read_b128 v[204:207], v148 offset:18432
	ds_read_b128 v[208:211], v148 offset:19456
	ds_read_b128 v[212:215], v148 offset:20480
	ds_read_b128 v[216:219], v148 offset:21504
	ds_read_b128 v[220:223], v148 offset:22528
	ds_read_b128 v[224:227], v148 offset:23552
	global_load_lds_dwordx4 v[228:229], off
	s_add_i32 m0, s61, 0x2000
	v_lshl_add_u64 v[230:231], s[92:93], 0, v[136:137]
	s_add_u32 s92, s92, s8
	s_addc_u32 s93, s93, 0
	s_add_i32 s49, s49, s51
	global_load_lds_dwordx4 v[230:231], off
	v_lshl_add_u64 v[232:233], s[92:93], 0, v[132:133]
	s_mov_b32 m0, s49
	v_lshl_add_u64 v[234:235], s[92:93], 0, v[136:137]
	global_load_lds_dwordx4 v[232:233], off
	s_add_i32 m0, s49, 0x2000
	v_lshl_add_u64 v[236:237], s[46:47], 0, v[130:131]
	global_load_lds_dwordx4 v[234:235], off
	s_mov_b32 m0, s78
	v_lshl_add_u64 v[238:239], s[46:47], 0, v[134:135]
	global_load_lds_dwordx4 v[236:237], off
	s_mov_b32 m0, s79
	s_nop 0
	global_load_lds_dwordx4 v[238:239], off
	.p2align	6
	s_waitcnt vmcnt(8)
	s_waitcnt lgkmcnt(0)
	s_barrier
; #define PG8_STAGE(bufoff, gbase, voff) do { _Pragma("unroll") for (int _i = 0; _i < 2; ++_i) \
;         __builtin_amdgcn_global_load_lds((const unsigned*)((const char*)(gbase) + (voff)[_i]), (PG8_LAS unsigned*)(lds + (bufoff) + ldsw + _i * 8192), 16, 0, 0); } while (0)
; #define PG8_LDA(dst, b, h) do { _Pragma("unroll") for (int m = 0; m < 4; ++m) _Pragma("unroll") for (int k = 0; k < 2; ++k) dst[m][k] = *(const PG8_LAS bf16x8*)(lds + PG8_SA(b, h) + aoff + m * 2048 + k * 1024); } while (0)
; #define PG8_LDB(dst, b, h) do { _Pragma("unroll") for (int n = 0; n < 2; ++n) _Pragma("unroll") for (int k = 0; k < 2; ++k) dst[n][k] = *(const PG8_LAS bf16x8*)(lds + PG8_SB(b, h) + boff + n * 2048 + k * 1024); } while (0)
; #define PG8_MMA(ai, bj, At, Bt) do { __builtin_amdgcn_s_setprio(1); _Pragma("unroll") for (int m = 0; m < 4; ++m) _Pragma("unroll") for (int n = 0; n < 2; ++n) _Pragma("unroll") for (int k = 0; k < 2; ++k) \
;         acc[ai][bj][m][n] = __builtin_amdgcn_mfma_f32_16x16x32_bf16(Bt[n][k], At[m][k], acc[ai][bj][m][n], 0, 0, 0); __builtin_amdgcn_s_setprio(0); } while (0)
; #define PG8_WAIT_V(n) asm volatile("s_waitcnt vmcnt(" #n ")" ::: "memory")
; #define PG8_WAIT_L(n) asm volatile("s_waitcnt lgkmcnt(" #n ")" ::: "memory")
; #define PG8_BAR __builtin_amdgcn_s_barrier()
; #define PG8_SCHED __builtin_amdgcn_sched_barrier(0)
; template <class Epi, class Sched, bool ALIGN_EPI = false, bool SP2 = false>
; __device__ __forceinline__ void gemm_phase(PG8_LAS unsigned char* lds, const Gemm g, const Sched& S, const Epi& E) {
;     ...
;             PG8_WAIT_V(8); PG8_WAIT_L(0); PG8_BAR; PG8_MMA(1, 0, At, B0); PG8_MMA(1, 1, At, B1); PG8_BAR; PG8_SCHED;
;             PG8_LDB(B0, 1, 0); PG8_LDB(B1, 1, 1); PG8_SCHED; PG8_LDA(At, 1, 0); PG8_STAGE(PG8_SA(0, 1), a2 + hstep, voffA);
;             PG8_WAIT_V(8); PG8_WAIT_L(0); PG8_BAR; PG8_MMA(0, 0, At, B0); PG8_MMA(0, 1, At, B1); PG8_BAR; PG8_SCHED;
	v_mfma_f32_16x16x32_bf16 v[62:65], v[142:145], v[196:199], v[62:65]
	v_mfma_f32_16x16x32_bf16 v[58:61], v[154:157], v[196:199], v[58:61]
	v_mfma_f32_16x16x32_bf16 v[46:49], v[142:145], v[204:207], v[46:49]
	v_mfma_f32_16x16x32_bf16 v[42:45], v[154:157], v[204:207], v[42:45]
	v_mfma_f32_16x16x32_bf16 v[28:31], v[142:145], v[212:215], v[28:31]
	v_mfma_f32_16x16x32_bf16 v[24:27], v[154:157], v[212:215], v[24:27]
	v_mfma_f32_16x16x32_bf16 v[12:15], v[142:145], v[220:223], v[12:15]
	v_mfma_f32_16x16x32_bf16 v[8:11], v[154:157], v[220:223], v[8:11]
	v_mfma_f32_16x16x32_bf16 v[62:65], v[150:153], v[200:203], v[62:65]
	v_mfma_f32_16x16x32_bf16 v[58:61], v[158:161], v[200:203], v[58:61]
	v_mfma_f32_16x16x32_bf16 v[46:49], v[150:153], v[208:211], v[46:49]
	v_mfma_f32_16x16x32_bf16 v[42:45], v[158:161], v[208:211], v[42:45]
	v_mfma_f32_16x16x32_bf16 v[28:31], v[150:153], v[216:219], v[28:31]
	v_mfma_f32_16x16x32_bf16 v[24:27], v[158:161], v[216:219], v[24:27]
	v_mfma_f32_16x16x32_bf16 v[12:15], v[150:153], v[224:227], v[12:15]
	v_mfma_f32_16x16x32_bf16 v[8:11], v[158:161], v[224:227], v[8:11]
	v_mfma_f32_16x16x32_bf16 v[54:57], v[170:173], v[196:199], v[54:57]
	v_mfma_f32_16x16x32_bf16 v[50:53], v[178:181], v[196:199], v[50:53]
	v_mfma_f32_16x16x32_bf16 v[38:41], v[170:173], v[204:207], v[38:41]
	v_mfma_f32_16x16x32_bf16 v[34:37], v[178:181], v[204:207], v[34:37]
	v_mfma_f32_16x16x32_bf16 v[20:23], v[170:173], v[212:215], v[20:23]
	v_mfma_f32_16x16x32_bf16 v[16:19], v[178:181], v[212:215], v[16:19]
	v_mfma_f32_16x16x32_bf16 v[4:7], v[170:173], v[220:223], v[4:7]
	v_mfma_f32_16x16x32_bf16 v[0:3], v[178:181], v[220:223], v[0:3]
	v_mfma_f32_16x16x32_bf16 v[54:57], v[174:177], v[200:203], v[54:57]
	v_mfma_f32_16x16x32_bf16 v[50:53], v[182:185], v[200:203], v[50:53]
	v_mfma_f32_16x16x32_bf16 v[38:41], v[174:177], v[208:211], v[38:41]
	v_mfma_f32_16x16x32_bf16 v[34:37], v[182:185], v[208:211], v[34:37]
	v_mfma_f32_16x16x32_bf16 v[20:23], v[174:177], v[216:219], v[20:23]
	v_mfma_f32_16x16x32_bf16 v[16:19], v[182:185], v[216:219], v[16:19]
	v_mfma_f32_16x16x32_bf16 v[4:7], v[174:177], v[224:227], v[4:7]
	v_mfma_f32_16x16x32_bf16 v[0:3], v[182:185], v[224:227], v[0:3]
	s_barrier
	s_add_i32 s49, 0, 0x18000
	v_add_u32_e32 v149, s49, v146
	s_add_i32 s61, 0, 0x1c000
	ds_read_b128 v[142:145], v149
	ds_read_b128 v[150:153], v149 offset:1024
	ds_read_b128 v[154:157], v149 offset:2048
	ds_read_b128 v[158:161], v149 offset:3072
	v_add_u32_e32 v149, s61, v146
	ds_read_b128 v[170:173], v149
	ds_read_b128 v[174:177], v149 offset:1024
	ds_read_b128 v[178:181], v149 offset:2048
	ds_read_b128 v[182:185], v149 offset:3072
	s_add_u32 s46, s46, s8
	s_addc_u32 s47, s47, 0
	s_mov_b32 m0, s80
	v_lshl_add_u64 v[240:241], s[46:47], 0, v[130:131]
	ds_read_b128 v[196:199], v148 offset:32768
	ds_read_b128 v[200:203], v148 offset:33792
	ds_read_b128 v[204:207], v148 offset:34816
	ds_read_b128 v[208:211], v148 offset:35840
	ds_read_b128 v[212:215], v148 offset:36864
	ds_read_b128 v[216:219], v148 offset:37888
	ds_read_b128 v[220:223], v148 offset:38912
	ds_read_b128 v[224:227], v148 offset:39936
	global_load_lds_dwordx4 v[240:241], off
	v_lshl_add_u64 v[240:241], s[46:47], 0, v[134:135]
	s_mov_b32 m0, s81
	s_nop 0
	global_load_lds_dwordx4 v[240:241], off
	.p2align	6
	s_waitcnt vmcnt(8)
	s_waitcnt lgkmcnt(0)
	s_barrier
	v_mfma_f32_16x16x32_bf16 v[126:129], v[142:145], v[196:199], v[126:129]
	v_mfma_f32_16x16x32_bf16 v[122:125], v[154:157], v[196:199], v[122:125]
	v_mfma_f32_16x16x32_bf16 v[110:113], v[142:145], v[204:207], v[110:113]
	v_mfma_f32_16x16x32_bf16 v[106:109], v[154:157], v[204:207], v[106:109]
	v_mfma_f32_16x16x32_bf16 v[94:97], v[142:145], v[212:215], v[94:97]
	v_mfma_f32_16x16x32_bf16 v[90:93], v[154:157], v[212:215], v[90:93]
	v_mfma_f32_16x16x32_bf16 v[78:81], v[142:145], v[220:223], v[78:81]
	v_mfma_f32_16x16x32_bf16 v[74:77], v[154:157], v[220:223], v[74:77]
	v_mfma_f32_16x16x32_bf16 v[126:129], v[150:153], v[200:203], v[126:129]
	v_mfma_f32_16x16x32_bf16 v[122:125], v[158:161], v[200:203], v[122:125]
	v_mfma_f32_16x16x32_bf16 v[110:113], v[150:153], v[208:211], v[110:113]
	v_mfma_f32_16x16x32_bf16 v[106:109], v[158:161], v[208:211], v[106:109]
	v_mfma_f32_16x16x32_bf16 v[94:97], v[150:153], v[216:219], v[94:97]
	v_mfma_f32_16x16x32_bf16 v[90:93], v[158:161], v[216:219], v[90:93]
	v_mfma_f32_16x16x32_bf16 v[78:81], v[150:153], v[224:227], v[78:81]
	v_mfma_f32_16x16x32_bf16 v[74:77], v[158:161], v[224:227], v[74:77]
	v_mfma_f32_16x16x32_bf16 v[118:121], v[170:173], v[196:199], v[118:121]
	v_mfma_f32_16x16x32_bf16 v[114:117], v[178:181], v[196:199], v[114:117]
	v_mfma_f32_16x16x32_bf16 v[102:105], v[170:173], v[204:207], v[102:105]
	v_mfma_f32_16x16x32_bf16 v[98:101], v[178:181], v[204:207], v[98:101]
	v_mfma_f32_16x16x32_bf16 v[86:89], v[170:173], v[212:215], v[86:89]
	v_mfma_f32_16x16x32_bf16 v[82:85], v[178:181], v[212:215], v[82:85]
	v_mfma_f32_16x16x32_bf16 v[70:73], v[170:173], v[220:223], v[70:73]
	v_mfma_f32_16x16x32_bf16 v[66:69], v[178:181], v[220:223], v[66:69]
	v_mfma_f32_16x16x32_bf16 v[118:121], v[174:177], v[200:203], v[118:121]
	v_mfma_f32_16x16x32_bf16 v[114:117], v[182:185], v[200:203], v[114:117]
	v_mfma_f32_16x16x32_bf16 v[102:105], v[174:177], v[208:211], v[102:105]
	v_mfma_f32_16x16x32_bf16 v[98:101], v[182:185], v[208:211], v[98:101]
	v_mfma_f32_16x16x32_bf16 v[86:89], v[174:177], v[216:219], v[86:89]
	v_mfma_f32_16x16x32_bf16 v[82:85], v[182:185], v[216:219], v[82:85]
	v_mfma_f32_16x16x32_bf16 v[70:73], v[174:177], v[224:227], v[70:73]
	v_mfma_f32_16x16x32_bf16 v[66:69], v[182:185], v[224:227], v[66:69]
	s_barrier
; #define PG8_STAGE(bufoff, gbase, voff) do { _Pragma("unroll") for (int _i = 0; _i < 2; ++_i) \
;         __builtin_amdgcn_global_load_lds((const unsigned*)((const char*)(gbase) + (voff)[_i]), (PG8_LAS unsigned*)(lds + (bufoff) + ldsw + _i * 8192), 16, 0, 0); } while (0)
; #define PG8_LDA(dst, b, h) do { _Pragma("unroll") for (int m = 0; m < 4; ++m) _Pragma("unroll") for (int k = 0; k < 2; ++k) dst[m][k] = *(const PG8_LAS bf16x8*)(lds + PG8_SA(b, h) + aoff + m * 2048 + k * 1024); } while (0)
; #define PG8_MMA(ai, bj, At, Bt) do { __builtin_amdgcn_s_setprio(1); _Pragma("unroll") for (int m = 0; m < 4; ++m) _Pragma("unroll") for (int n = 0; n < 2; ++n) _Pragma("unroll") for (int k = 0; k < 2; ++k) \
;         acc[ai][bj][m][n] = __builtin_amdgcn_mfma_f32_16x16x32_bf16(Bt[n][k], At[m][k], acc[ai][bj][m][n], 0, 0, 0); __builtin_amdgcn_s_setprio(0); } while (0)
; #define PG8_WAIT_V(n) asm volatile("s_waitcnt vmcnt(" #n ")" ::: "memory")
; #define PG8_WAIT_L(n) asm volatile("s_waitcnt lgkmcnt(" #n ")" ::: "memory")
; #define PG8_BAR __builtin_amdgcn_s_barrier()
; #define PG8_SCHED __builtin_amdgcn_sched_barrier(0)
; template <class Epi, class Sched, bool ALIGN_EPI = false, bool SP2 = false>
; __device__ __forceinline__ void gemm_phase(PG8_LAS unsigned char* lds, const Gemm g, const Sched& S, const Epi& E) {
;     ...
;             PG8_LDA(At, 1, 1); PG8_STAGE(PG8_SB(1, 0), b3, voffB); PG8_STAGE(PG8_SB(1, 1), b3 + hstep, voffB); PG8_STAGE(PG8_SA(1, 0), a3, voffA);
;             PG8_WAIT_V(8); PG8_WAIT_L(0); PG8_BAR; PG8_MMA(1, 0, At, B0); PG8_MMA(1, 1, At, B1); PG8_BAR; PG8_SCHED;
;     ...
;         if constexpr (ALIGN_EPI) { if (wr == 0) PG8_BAR; }
	s_add_i32 s46, s49, s51
	v_lshl_add_u64 v[228:229], v[228:229], 0, s[34:35]
	s_mov_b32 m0, s46
	ds_read_b128 v[196:199], v148 offset:49152
	ds_read_b128 v[200:203], v148 offset:50176
	ds_read_b128 v[204:207], v148 offset:51200
	ds_read_b128 v[208:211], v148 offset:52224
	ds_read_b128 v[212:215], v148 offset:53248
	ds_read_b128 v[216:219], v148 offset:54272
	ds_read_b128 v[220:223], v148 offset:55296
	ds_read_b128 v[224:227], v148 offset:56320
	global_load_lds_dwordx4 v[228:229], off
	v_lshl_add_u64 v[228:229], v[230:231], 0, s[34:35]
	s_add_i32 m0, s46, 0x2000
	s_add_i32 s46, s61, s51
	global_load_lds_dwordx4 v[228:229], off
	v_lshl_add_u64 v[228:229], v[232:233], 0, s[34:35]
	s_mov_b32 m0, s46
	s_nop 0
	global_load_lds_dwordx4 v[228:229], off
	v_lshl_add_u64 v[228:229], v[234:235], 0, s[34:35]
	s_add_i32 m0, s46, 0x2000
	s_nop 0
	global_load_lds_dwordx4 v[228:229], off
	v_lshl_add_u64 v[228:229], v[236:237], 0, s[34:35]
	s_mov_b32 m0, s83
	s_nop 0
	global_load_lds_dwordx4 v[228:229], off
	v_lshl_add_u64 v[228:229], v[238:239], 0, s[34:35]
	s_mov_b32 m0, s84
	s_nop 0
	global_load_lds_dwordx4 v[228:229], off
	.p2align	6
	s_waitcnt vmcnt(8)
	s_waitcnt lgkmcnt(0)
	s_barrier
	v_mfma_f32_16x16x32_bf16 v[62:65], v[142:145], v[196:199], v[62:65]
	v_mfma_f32_16x16x32_bf16 v[58:61], v[154:157], v[196:199], v[58:61]
	v_mfma_f32_16x16x32_bf16 v[46:49], v[142:145], v[204:207], v[46:49]
	v_mfma_f32_16x16x32_bf16 v[42:45], v[154:157], v[204:207], v[42:45]
	v_mfma_f32_16x16x32_bf16 v[28:31], v[142:145], v[212:215], v[28:31]
	v_mfma_f32_16x16x32_bf16 v[24:27], v[154:157], v[212:215], v[24:27]
	v_mfma_f32_16x16x32_bf16 v[12:15], v[142:145], v[220:223], v[12:15]
	v_mfma_f32_16x16x32_bf16 v[8:11], v[154:157], v[220:223], v[8:11]
	v_mfma_f32_16x16x32_bf16 v[62:65], v[150:153], v[200:203], v[62:65]
	v_mfma_f32_16x16x32_bf16 v[58:61], v[158:161], v[200:203], v[58:61]
	v_mfma_f32_16x16x32_bf16 v[46:49], v[150:153], v[208:211], v[46:49]
	v_mfma_f32_16x16x32_bf16 v[42:45], v[158:161], v[208:211], v[42:45]
	v_mfma_f32_16x16x32_bf16 v[28:31], v[150:153], v[216:219], v[28:31]
	v_mfma_f32_16x16x32_bf16 v[24:27], v[158:161], v[216:219], v[24:27]
	v_mfma_f32_16x16x32_bf16 v[12:15], v[150:153], v[224:227], v[12:15]
	v_mfma_f32_16x16x32_bf16 v[8:11], v[158:161], v[224:227], v[8:11]
	v_mfma_f32_16x16x32_bf16 v[54:57], v[170:173], v[196:199], v[54:57]
	v_mfma_f32_16x16x32_bf16 v[50:53], v[178:181], v[196:199], v[50:53]
	v_mfma_f32_16x16x32_bf16 v[38:41], v[170:173], v[204:207], v[38:41]
	v_mfma_f32_16x16x32_bf16 v[34:37], v[178:181], v[204:207], v[34:37]
	v_mfma_f32_16x16x32_bf16 v[20:23], v[170:173], v[212:215], v[20:23]
	v_mfma_f32_16x16x32_bf16 v[16:19], v[178:181], v[212:215], v[16:19]
	v_mfma_f32_16x16x32_bf16 v[4:7], v[170:173], v[220:223], v[4:7]
	v_mfma_f32_16x16x32_bf16 v[0:3], v[178:181], v[220:223], v[0:3]
	v_mfma_f32_16x16x32_bf16 v[54:57], v[174:177], v[200:203], v[54:57]
	v_mfma_f32_16x16x32_bf16 v[50:53], v[182:185], v[200:203], v[50:53]
	v_mfma_f32_16x16x32_bf16 v[38:41], v[174:177], v[208:211], v[38:41]
	v_mfma_f32_16x16x32_bf16 v[34:37], v[182:185], v[208:211], v[34:37]
	v_mfma_f32_16x16x32_bf16 v[20:23], v[174:177], v[216:219], v[20:23]
	v_mfma_f32_16x16x32_bf16 v[16:19], v[182:185], v[216:219], v[16:19]
	v_mfma_f32_16x16x32_bf16 v[4:7], v[174:177], v[224:227], v[4:7]
	v_mfma_f32_16x16x32_bf16 v[0:3], v[182:185], v[224:227], v[0:3]
	s_barrier
	s_add_u32 s0, s0, 0x100
	s_addc_u32 s9, s9, 0
	s_add_u32 s44, s44, 0x100
	s_addc_u32 s45, s45, 0
	s_cmp_ge_u32 s48, s85
	s_mov_b32 s46, s48
	s_cbranch_scc0 .LBB0_546
	s_and_b64 vcc, exec, s[40:41]
	s_cbranch_vccz .LBB0_549
	s_barrier

; #define PG8_STAGE(bufoff, gbase, voff) do { _Pragma("unroll") for (int _i = 0; _i < 2; ++_i) \
;         __builtin_amdgcn_global_load_lds((const unsigned*)((const char*)(gbase) + (voff)[_i]), (PG8_LAS unsigned*)(lds + (bufoff) + ldsw + _i * 8192), 16, 0, 0); } while (0)
; #define PG8_LDA(dst, b, h) do { _Pragma("unroll") for (int m = 0; m < 4; ++m) _Pragma("unroll") for (int k = 0; k < 2; ++k) dst[m][k] = *(const PG8_LAS bf16x8*)(lds + PG8_SA(b, h) + aoff + m * 2048 + k * 1024); } while (0)
; #define PG8_LDB(dst, b, h) do { _Pragma("unroll") for (int n = 0; n < 2; ++n) _Pragma("unroll") for (int k = 0; k < 2; ++k) dst[n][k] = *(const PG8_LAS bf16x8*)(lds + PG8_SB(b, h) + boff + n * 2048 + k * 1024); } while (0)
; #define PG8_MMA(ai, bj, At, Bt) do { __builtin_amdgcn_s_setprio(1); _Pragma("unroll") for (int m = 0; m < 4; ++m) _Pragma("unroll") for (int n = 0; n < 2; ++n) _Pragma("unroll") for (int k = 0; k < 2; ++k) \
;         acc[ai][bj][m][n] = __builtin_amdgcn_mfma_f32_16x16x32_bf16(Bt[n][k], At[m][k], acc[ai][bj][m][n], 0, 0, 0); __builtin_amdgcn_s_setprio(0); } while (0)
; #define PG8_WAIT_V(n) asm volatile("s_waitcnt vmcnt(" #n ")" ::: "memory")
; #define PG8_WAIT_L(n) asm volatile("s_waitcnt lgkmcnt(" #n ")" ::: "memory")
; #define PG8_BAR __builtin_amdgcn_s_barrier()
; #define PG8_SCHED __builtin_amdgcn_sched_barrier(0)
; template <class Epi, class Sched, bool ALIGN_EPI = false, bool SP2 = false>
; __device__ __forceinline__ void gemm_phase(PG8_LAS unsigned char* lds, const Gemm g, const Sched& S, const Epi& E) {
;     ...
;             const bool last = (t == nt - 2);
;             const char* a1 = cA + (size_t)(t + 1) * kstep;
;             const char* a2 = last ? nA : cA + (size_t)(t + 2) * kstep; const char* b2 = last ? nB : cB + (size_t)(t + 2) * kstep;
;             const char* a3 = a2 + kstep; const char* b3 = b2 + kstep;
;             if (last && has_next) S.a_ready(nxt);
;             if constexpr (SP2) {
;             PG8_LDB(B0, 0, 0); PG8_LDB(B1, 0, 1); PG8_SCHED; PG8_LDA(At, 0, 0); PG8_STAGE(PG8_SA(1, 1), a1 + hstep, voffA);
;             PG8_WAIT_V(8); PG8_WAIT_L(0); PG8_BAR; PG8_MMA(0, 0, At, B0); PG8_MMA(0, 1, At, B1); PG8_BAR; PG8_SCHED;
;             PG8_LDA(At, 0, 1); PG8_STAGE(PG8_SB(0, 0), b2, voffB); PG8_STAGE(PG8_SB(0, 1), b2 + hstep, voffB); PG8_STAGE(PG8_SA(0, 0), a2, voffA);
.LBB0_580:
	s_add_u32 s48, s46, 0xfffc0080
	s_addc_u32 s49, s47, -1
	s_add_i32 s82, 0, 0x10000
	s_cmp_eq_u32 s81, 12
	s_cselect_b32 s51, s9, s49
	s_cselect_b32 s50, s66, s48
	v_add_u32_e32 v151, s82, v145
	s_cselect_b32 s49, s7, s80
	s_cselect_b32 s48, s67, s79
	s_add_i32 s84, 0, 0x14000
	ds_read_b128 v[170:173], v151
	ds_read_b128 v[174:177], v151 offset:1024
	ds_read_b128 v[178:181], v151 offset:2048
	ds_read_b128 v[182:185], v151 offset:3072
	v_add_u32_e32 v151, s84, v145
	ds_read_b128 v[196:199], v151
	ds_read_b128 v[200:203], v151 offset:1024
	ds_read_b128 v[204:207], v151 offset:2048
	ds_read_b128 v[208:211], v151 offset:3072
	v_lshl_add_u64 v[160:161], s[46:47], 0, v[142:143]
	s_add_i32 m0, s71, 0xc000
	ds_read_b128 v[212:215], v149
	ds_read_b128 v[216:219], v149 offset:1024
	ds_read_b128 v[220:223], v149 offset:2048
	ds_read_b128 v[224:227], v149 offset:3072
	ds_read_b128 v[228:231], v149 offset:4096
	ds_read_b128 v[232:235], v149 offset:5120
	ds_read_b128 v[236:239], v149 offset:6144
	ds_read_b128 v[240:243], v149 offset:7168
	global_load_lds_dwordx4 v[160:161], off
	v_lshl_add_u64 v[160:161], s[46:47], 0, v[140:141]
	s_add_i32 m0, s71, 0xe000
	s_nop 0
	global_load_lds_dwordx4 v[160:161], off
	.p2align	6
	s_waitcnt vmcnt(8)
	s_waitcnt lgkmcnt(0)
	s_barrier
	v_mfma_f32_16x16x32_bf16 v[126:129], v[170:173], v[212:215], v[126:129]
	v_mfma_f32_16x16x32_bf16 v[122:125], v[178:181], v[212:215], v[122:125]
	v_mfma_f32_16x16x32_bf16 v[110:113], v[170:173], v[220:223], v[110:113]
	v_mfma_f32_16x16x32_bf16 v[106:109], v[178:181], v[220:223], v[106:109]
	v_mfma_f32_16x16x32_bf16 v[94:97], v[170:173], v[228:231], v[94:97]
	v_mfma_f32_16x16x32_bf16 v[90:93], v[178:181], v[228:231], v[90:93]
	v_mfma_f32_16x16x32_bf16 v[78:81], v[170:173], v[236:239], v[78:81]
	v_mfma_f32_16x16x32_bf16 v[74:77], v[178:181], v[236:239], v[74:77]
	v_mfma_f32_16x16x32_bf16 v[126:129], v[174:177], v[216:219], v[126:129]
	v_mfma_f32_16x16x32_bf16 v[122:125], v[182:185], v[216:219], v[122:125]
	v_mfma_f32_16x16x32_bf16 v[110:113], v[174:177], v[224:227], v[110:113]
	v_mfma_f32_16x16x32_bf16 v[106:109], v[182:185], v[224:227], v[106:109]
	v_mfma_f32_16x16x32_bf16 v[94:97], v[174:177], v[232:235], v[94:97]
	v_mfma_f32_16x16x32_bf16 v[90:93], v[182:185], v[232:235], v[90:93]
	v_mfma_f32_16x16x32_bf16 v[78:81], v[174:177], v[240:243], v[78:81]
	v_mfma_f32_16x16x32_bf16 v[74:77], v[182:185], v[240:243], v[74:77]
	v_mfma_f32_16x16x32_bf16 v[118:121], v[196:199], v[212:215], v[118:121]
	v_mfma_f32_16x16x32_bf16 v[114:117], v[204:207], v[212:215], v[114:117]
	v_mfma_f32_16x16x32_bf16 v[102:105], v[196:199], v[220:223], v[102:105]
	v_mfma_f32_16x16x32_bf16 v[98:101], v[204:207], v[220:223], v[98:101]
	v_mfma_f32_16x16x32_bf16 v[86:89], v[196:199], v[228:231], v[86:89]
	v_mfma_f32_16x16x32_bf16 v[82:85], v[204:207], v[228:231], v[82:85]
	v_mfma_f32_16x16x32_bf16 v[70:73], v[196:199], v[236:239], v[70:73]
	v_mfma_f32_16x16x32_bf16 v[66:69], v[204:207], v[236:239], v[66:69]
	v_mfma_f32_16x16x32_bf16 v[118:121], v[200:203], v[216:219], v[118:121]
	v_mfma_f32_16x16x32_bf16 v[114:117], v[208:211], v[216:219], v[114:117]
	v_mfma_f32_16x16x32_bf16 v[102:105], v[200:203], v[224:227], v[102:105]
	v_mfma_f32_16x16x32_bf16 v[98:101], v[208:211], v[224:227], v[98:101]
	v_mfma_f32_16x16x32_bf16 v[86:89], v[200:203], v[232:235], v[86:89]
	v_mfma_f32_16x16x32_bf16 v[82:85], v[208:211], v[232:235], v[82:85]
	v_mfma_f32_16x16x32_bf16 v[70:73], v[200:203], v[240:243], v[70:73]
	v_mfma_f32_16x16x32_bf16 v[66:69], v[208:211], v[240:243], v[66:69]
	s_barrier
	s_add_i32 s82, s82, s69
	v_lshl_add_u64 v[160:161], s[48:49], 0, v[134:135]
	s_mov_b32 m0, s82
	ds_read_b128 v[212:215], v149 offset:16384
	ds_read_b128 v[216:219], v149 offset:17408
	ds_read_b128 v[220:223], v149 offset:18432
	ds_read_b128 v[224:227], v149 offset:19456
	ds_read_b128 v[228:231], v149 offset:20480
	ds_read_b128 v[232:235], v149 offset:21504
	ds_read_b128 v[236:239], v149 offset:22528
	ds_read_b128 v[240:243], v149 offset:23552
	global_load_lds_dwordx4 v[160:161], off
	s_add_i32 m0, s82, 0x2000
	s_add_u32 s82, s48, 0x40000
	v_lshl_add_u64 v[244:245], s[48:49], 0, v[130:131]
	s_addc_u32 s83, s49, 0
	s_add_i32 s84, s84, s69
	global_load_lds_dwordx4 v[244:245], off
	v_lshl_add_u64 v[246:247], s[82:83], 0, v[134:135]
	s_mov_b32 m0, s84
	v_lshl_add_u64 v[248:249], s[50:51], 0, v[132:133]
	global_load_lds_dwordx4 v[246:247], off
	v_lshl_add_u64 v[246:247], s[82:83], 0, v[130:131]
	s_add_i32 m0, s84, 0x2000
	s_nop 0
	global_load_lds_dwordx4 v[246:247], off
	v_lshl_add_u64 v[246:247], s[50:51], 0, v[136:137]
	s_mov_b32 m0, s71
	s_nop 0
	global_load_lds_dwordx4 v[246:247], off
	s_mov_b32 m0, s72
	s_nop 0
	global_load_lds_dwordx4 v[248:249], off
	.p2align	6
	s_waitcnt vmcnt(8)
	s_waitcnt lgkmcnt(0)
	s_barrier
; #define PG8_STAGE(bufoff, gbase, voff) do { _Pragma("unroll") for (int _i = 0; _i < 2; ++_i) \
;         __builtin_amdgcn_global_load_lds((const unsigned*)((const char*)(gbase) + (voff)[_i]), (PG8_LAS unsigned*)(lds + (bufoff) + ldsw + _i * 8192), 16, 0, 0); } while (0)
; #define PG8_LDA(dst, b, h) do { _Pragma("unroll") for (int m = 0; m < 4; ++m) _Pragma("unroll") for (int k = 0; k < 2; ++k) dst[m][k] = *(const PG8_LAS bf16x8*)(lds + PG8_SA(b, h) + aoff + m * 2048 + k * 1024); } while (0)
; #define PG8_LDB(dst, b, h) do { _Pragma("unroll") for (int n = 0; n < 2; ++n) _Pragma("unroll") for (int k = 0; k < 2; ++k) dst[n][k] = *(const PG8_LAS bf16x8*)(lds + PG8_SB(b, h) + boff + n * 2048 + k * 1024); } while (0)
; #define PG8_MMA(ai, bj, At, Bt) do { __builtin_amdgcn_s_setprio(1); _Pragma("unroll") for (int m = 0; m < 4; ++m) _Pragma("unroll") for (int n = 0; n < 2; ++n) _Pragma("unroll") for (int k = 0; k < 2; ++k) \
;         acc[ai][bj][m][n] = __builtin_amdgcn_mfma_f32_16x16x32_bf16(Bt[n][k], At[m][k], acc[ai][bj][m][n], 0, 0, 0); __builtin_amdgcn_s_setprio(0); } while (0)
; #define PG8_WAIT_V(n) asm volatile("s_waitcnt vmcnt(" #n ")" ::: "memory")
; #define PG8_WAIT_L(n) asm volatile("s_waitcnt lgkmcnt(" #n ")" ::: "memory")
; #define PG8_BAR __builtin_amdgcn_s_barrier()
; #define PG8_SCHED __builtin_amdgcn_sched_barrier(0)
; template <class Epi, class Sched, bool ALIGN_EPI = false, bool SP2 = false>
; __device__ __forceinline__ void gemm_phase(PG8_LAS unsigned char* lds, const Gemm g, const Sched& S, const Epi& E) {
;     ...
;             PG8_WAIT_V(8); PG8_WAIT_L(0); PG8_BAR; PG8_MMA(1, 0, At, B0); PG8_MMA(1, 1, At, B1); PG8_BAR; PG8_SCHED;
;             PG8_LDB(B0, 1, 0); PG8_LDB(B1, 1, 1); PG8_SCHED; PG8_LDA(At, 1, 0); PG8_STAGE(PG8_SA(0, 1), a2 + hstep, voffA);
;             PG8_WAIT_V(8); PG8_WAIT_L(0); PG8_BAR; PG8_MMA(0, 0, At, B0); PG8_MMA(0, 1, At, B1); PG8_BAR; PG8_SCHED;
	v_mfma_f32_16x16x32_bf16 v[62:65], v[170:173], v[212:215], v[62:65]
	v_mfma_f32_16x16x32_bf16 v[58:61], v[178:181], v[212:215], v[58:61]
	v_mfma_f32_16x16x32_bf16 v[46:49], v[170:173], v[220:223], v[46:49]
	v_mfma_f32_16x16x32_bf16 v[42:45], v[178:181], v[220:223], v[42:45]
	v_mfma_f32_16x16x32_bf16 v[28:31], v[170:173], v[228:231], v[28:31]
	v_mfma_f32_16x16x32_bf16 v[24:27], v[178:181], v[228:231], v[24:27]
	v_mfma_f32_16x16x32_bf16 v[12:15], v[170:173], v[236:239], v[12:15]
	v_mfma_f32_16x16x32_bf16 v[8:11], v[178:181], v[236:239], v[8:11]
	v_mfma_f32_16x16x32_bf16 v[62:65], v[174:177], v[216:219], v[62:65]
	v_mfma_f32_16x16x32_bf16 v[58:61], v[182:185], v[216:219], v[58:61]
	v_mfma_f32_16x16x32_bf16 v[46:49], v[174:177], v[224:227], v[46:49]
	v_mfma_f32_16x16x32_bf16 v[42:45], v[182:185], v[224:227], v[42:45]
	v_mfma_f32_16x16x32_bf16 v[28:31], v[174:177], v[232:235], v[28:31]
	v_mfma_f32_16x16x32_bf16 v[24:27], v[182:185], v[232:235], v[24:27]
	v_mfma_f32_16x16x32_bf16 v[12:15], v[174:177], v[240:243], v[12:15]
	v_mfma_f32_16x16x32_bf16 v[8:11], v[182:185], v[240:243], v[8:11]
	v_mfma_f32_16x16x32_bf16 v[54:57], v[196:199], v[212:215], v[54:57]
	v_mfma_f32_16x16x32_bf16 v[50:53], v[204:207], v[212:215], v[50:53]
	v_mfma_f32_16x16x32_bf16 v[38:41], v[196:199], v[220:223], v[38:41]
	v_mfma_f32_16x16x32_bf16 v[34:37], v[204:207], v[220:223], v[34:37]
	v_mfma_f32_16x16x32_bf16 v[20:23], v[196:199], v[228:231], v[20:23]
	v_mfma_f32_16x16x32_bf16 v[16:19], v[204:207], v[228:231], v[16:19]
	v_mfma_f32_16x16x32_bf16 v[4:7], v[196:199], v[236:239], v[4:7]
	v_mfma_f32_16x16x32_bf16 v[0:3], v[204:207], v[236:239], v[0:3]
	v_mfma_f32_16x16x32_bf16 v[54:57], v[200:203], v[216:219], v[54:57]
	v_mfma_f32_16x16x32_bf16 v[50:53], v[208:211], v[216:219], v[50:53]
	v_mfma_f32_16x16x32_bf16 v[38:41], v[200:203], v[224:227], v[38:41]
	v_mfma_f32_16x16x32_bf16 v[34:37], v[208:211], v[224:227], v[34:37]
	v_mfma_f32_16x16x32_bf16 v[20:23], v[200:203], v[232:235], v[20:23]
	v_mfma_f32_16x16x32_bf16 v[16:19], v[208:211], v[232:235], v[16:19]
	v_mfma_f32_16x16x32_bf16 v[4:7], v[200:203], v[240:243], v[4:7]
	v_mfma_f32_16x16x32_bf16 v[0:3], v[208:211], v[240:243], v[0:3]
	s_barrier
	s_add_i32 s82, 0, 0x18000
	v_add_u32_e32 v151, s82, v145
	s_add_i32 s83, 0, 0x1c000
	ds_read_b128 v[170:173], v151
	ds_read_b128 v[174:177], v151 offset:1024
	ds_read_b128 v[178:181], v151 offset:2048
	ds_read_b128 v[182:185], v151 offset:3072
	v_add_u32_e32 v151, s83, v145
	ds_read_b128 v[196:199], v151
	ds_read_b128 v[200:203], v151 offset:1024
	ds_read_b128 v[204:207], v151 offset:2048
	ds_read_b128 v[208:211], v151 offset:3072
	s_add_u32 s50, s50, 0x40000
	s_addc_u32 s51, s51, 0
	s_mov_b32 m0, s73
	v_lshl_add_u64 v[250:251], s[50:51], 0, v[136:137]
	ds_read_b128 v[212:215], v149 offset:32768
	ds_read_b128 v[216:219], v149 offset:33792
	ds_read_b128 v[220:223], v149 offset:34816
	ds_read_b128 v[224:227], v149 offset:35840
	ds_read_b128 v[228:231], v149 offset:36864
	ds_read_b128 v[232:235], v149 offset:37888
	ds_read_b128 v[236:239], v149 offset:38912
	ds_read_b128 v[240:243], v149 offset:39936
	global_load_lds_dwordx4 v[250:251], off
	v_lshl_add_u64 v[250:251], s[50:51], 0, v[132:133]
	s_mov_b32 m0, s76
	s_nop 0
	global_load_lds_dwordx4 v[250:251], off
	.p2align	6
	s_waitcnt vmcnt(8)
	s_waitcnt lgkmcnt(0)
	s_barrier
	v_mfma_f32_16x16x32_bf16 v[126:129], v[170:173], v[212:215], v[126:129]
	v_mfma_f32_16x16x32_bf16 v[122:125], v[178:181], v[212:215], v[122:125]
	v_mfma_f32_16x16x32_bf16 v[110:113], v[170:173], v[220:223], v[110:113]
	v_mfma_f32_16x16x32_bf16 v[106:109], v[178:181], v[220:223], v[106:109]
	v_mfma_f32_16x16x32_bf16 v[94:97], v[170:173], v[228:231], v[94:97]
	v_mfma_f32_16x16x32_bf16 v[90:93], v[178:181], v[228:231], v[90:93]
	v_mfma_f32_16x16x32_bf16 v[78:81], v[170:173], v[236:239], v[78:81]
	v_mfma_f32_16x16x32_bf16 v[74:77], v[178:181], v[236:239], v[74:77]
	v_mfma_f32_16x16x32_bf16 v[126:129], v[174:177], v[216:219], v[126:129]
	v_mfma_f32_16x16x32_bf16 v[122:125], v[182:185], v[216:219], v[122:125]
	v_mfma_f32_16x16x32_bf16 v[110:113], v[174:177], v[224:227], v[110:113]
	v_mfma_f32_16x16x32_bf16 v[106:109], v[182:185], v[224:227], v[106:109]
	v_mfma_f32_16x16x32_bf16 v[94:97], v[174:177], v[232:235], v[94:97]
	v_mfma_f32_16x16x32_bf16 v[90:93], v[182:185], v[232:235], v[90:93]
	v_mfma_f32_16x16x32_bf16 v[78:81], v[174:177], v[240:243], v[78:81]
	v_mfma_f32_16x16x32_bf16 v[74:77], v[182:185], v[240:243], v[74:77]
	v_mfma_f32_16x16x32_bf16 v[118:121], v[196:199], v[212:215], v[118:121]
	v_mfma_f32_16x16x32_bf16 v[114:117], v[204:207], v[212:215], v[114:117]
	v_mfma_f32_16x16x32_bf16 v[102:105], v[196:199], v[220:223], v[102:105]
	v_mfma_f32_16x16x32_bf16 v[98:101], v[204:207], v[220:223], v[98:101]
	v_mfma_f32_16x16x32_bf16 v[86:89], v[196:199], v[228:231], v[86:89]
	v_mfma_f32_16x16x32_bf16 v[82:85], v[204:207], v[228:231], v[82:85]
	v_mfma_f32_16x16x32_bf16 v[70:73], v[196:199], v[236:239], v[70:73]
	v_mfma_f32_16x16x32_bf16 v[66:69], v[204:207], v[236:239], v[66:69]
	v_mfma_f32_16x16x32_bf16 v[118:121], v[200:203], v[216:219], v[118:121]
	v_mfma_f32_16x16x32_bf16 v[114:117], v[208:211], v[216:219], v[114:117]
	v_mfma_f32_16x16x32_bf16 v[102:105], v[200:203], v[224:227], v[102:105]
	v_mfma_f32_16x16x32_bf16 v[98:101], v[208:211], v[224:227], v[98:101]
	v_mfma_f32_16x16x32_bf16 v[86:89], v[200:203], v[232:235], v[86:89]
	v_mfma_f32_16x16x32_bf16 v[82:85], v[208:211], v[232:235], v[82:85]
	v_mfma_f32_16x16x32_bf16 v[70:73], v[200:203], v[240:243], v[70:73]
	v_mfma_f32_16x16x32_bf16 v[66:69], v[208:211], v[240:243], v[66:69]
	s_barrier
; #define PG8_STAGE(bufoff, gbase, voff) do { _Pragma("unroll") for (int _i = 0; _i < 2; ++_i) \
;         __builtin_amdgcn_global_load_lds((const unsigned*)((const char*)(gbase) + (voff)[_i]), (PG8_LAS unsigned*)(lds + (bufoff) + ldsw + _i * 8192), 16, 0, 0); } while (0)
; #define PG8_LDA(dst, b, h) do { _Pragma("unroll") for (int m = 0; m < 4; ++m) _Pragma("unroll") for (int k = 0; k < 2; ++k) dst[m][k] = *(const PG8_LAS bf16x8*)(lds + PG8_SA(b, h) + aoff + m * 2048 + k * 1024); } while (0)
; #define PG8_MMA(ai, bj, At, Bt) do { __builtin_amdgcn_s_setprio(1); _Pragma("unroll") for (int m = 0; m < 4; ++m) _Pragma("unroll") for (int n = 0; n < 2; ++n) _Pragma("unroll") for (int k = 0; k < 2; ++k) \
;         acc[ai][bj][m][n] = __builtin_amdgcn_mfma_f32_16x16x32_bf16(Bt[n][k], At[m][k], acc[ai][bj][m][n], 0, 0, 0); __builtin_amdgcn_s_setprio(0); } while (0)
; #define PG8_WAIT_V(n) asm volatile("s_waitcnt vmcnt(" #n ")" ::: "memory")
; #define PG8_WAIT_L(n) asm volatile("s_waitcnt lgkmcnt(" #n ")" ::: "memory")
; #define PG8_BAR __builtin_amdgcn_s_barrier()
; #define PG8_SCHED __builtin_amdgcn_sched_barrier(0)
; template <class Epi, class Sched, bool ALIGN_EPI = false, bool SP2 = false>
; __device__ __forceinline__ void gemm_phase(PG8_LAS unsigned char* lds, const Gemm g, const Sched& S, const Epi& E) {
;     ...
;             PG8_LDA(At, 1, 1); PG8_STAGE(PG8_SB(1, 0), b3, voffB); PG8_STAGE(PG8_SB(1, 1), b3 + hstep, voffB); PG8_STAGE(PG8_SA(1, 0), a3, voffA);
;             PG8_WAIT_V(8); PG8_WAIT_L(0); PG8_BAR; PG8_MMA(1, 0, At, B0); PG8_MMA(1, 1, At, B1); PG8_BAR; PG8_SCHED;
;     ...
;         if constexpr (ALIGN_EPI) { if (wr == 0) PG8_BAR; }
	s_add_i32 s50, s82, s69
	v_lshl_add_u64 v[160:161], v[160:161], 0, s[34:35]
	s_mov_b32 m0, s50
	ds_read_b128 v[212:215], v149 offset:49152
	ds_read_b128 v[216:219], v149 offset:50176
	ds_read_b128 v[220:223], v149 offset:51200
	ds_read_b128 v[224:227], v149 offset:52224
	ds_read_b128 v[228:231], v149 offset:53248
	ds_read_b128 v[232:235], v149 offset:54272
	ds_read_b128 v[236:239], v149 offset:55296
	ds_read_b128 v[240:243], v149 offset:56320
	global_load_lds_dwordx4 v[160:161], off
	s_add_i32 m0, s50, 0x2000
	s_add_u32 s48, s48, 0x40080
	v_lshl_add_u64 v[160:161], v[244:245], 0, s[34:35]
	s_addc_u32 s49, s49, 0
	s_add_i32 s50, s83, s69
	global_load_lds_dwordx4 v[160:161], off
	v_lshl_add_u64 v[160:161], s[48:49], 0, v[134:135]
	s_mov_b32 m0, s50
	s_nop 0
	global_load_lds_dwordx4 v[160:161], off
	v_lshl_add_u64 v[160:161], s[48:49], 0, v[130:131]
	s_add_i32 m0, s50, 0x2000
	s_nop 0
	global_load_lds_dwordx4 v[160:161], off
	v_lshl_add_u64 v[160:161], v[246:247], 0, s[34:35]
	s_mov_b32 m0, s77
	s_nop 0
	global_load_lds_dwordx4 v[160:161], off
	v_lshl_add_u64 v[160:161], v[248:249], 0, s[34:35]
	s_mov_b32 m0, s78
	s_nop 0
	global_load_lds_dwordx4 v[160:161], off
	.p2align	6
	s_waitcnt vmcnt(8)
	s_waitcnt lgkmcnt(0)
	s_barrier
	v_mfma_f32_16x16x32_bf16 v[62:65], v[170:173], v[212:215], v[62:65]
	v_mfma_f32_16x16x32_bf16 v[58:61], v[178:181], v[212:215], v[58:61]
	v_mfma_f32_16x16x32_bf16 v[46:49], v[170:173], v[220:223], v[46:49]
	v_mfma_f32_16x16x32_bf16 v[42:45], v[178:181], v[220:223], v[42:45]
	v_mfma_f32_16x16x32_bf16 v[28:31], v[170:173], v[228:231], v[28:31]
	v_mfma_f32_16x16x32_bf16 v[24:27], v[178:181], v[228:231], v[24:27]
	v_mfma_f32_16x16x32_bf16 v[12:15], v[170:173], v[236:239], v[12:15]
	v_mfma_f32_16x16x32_bf16 v[8:11], v[178:181], v[236:239], v[8:11]
	v_mfma_f32_16x16x32_bf16 v[62:65], v[174:177], v[216:219], v[62:65]
	v_mfma_f32_16x16x32_bf16 v[58:61], v[182:185], v[216:219], v[58:61]
	v_mfma_f32_16x16x32_bf16 v[46:49], v[174:177], v[224:227], v[46:49]
	v_mfma_f32_16x16x32_bf16 v[42:45], v[182:185], v[224:227], v[42:45]
	v_mfma_f32_16x16x32_bf16 v[28:31], v[174:177], v[232:235], v[28:31]
	v_mfma_f32_16x16x32_bf16 v[24:27], v[182:185], v[232:235], v[24:27]
	v_mfma_f32_16x16x32_bf16 v[12:15], v[174:177], v[240:243], v[12:15]
	v_mfma_f32_16x16x32_bf16 v[8:11], v[182:185], v[240:243], v[8:11]
	v_mfma_f32_16x16x32_bf16 v[54:57], v[196:199], v[212:215], v[54:57]
	v_mfma_f32_16x16x32_bf16 v[50:53], v[204:207], v[212:215], v[50:53]
	v_mfma_f32_16x16x32_bf16 v[38:41], v[196:199], v[220:223], v[38:41]
	v_mfma_f32_16x16x32_bf16 v[34:37], v[204:207], v[220:223], v[34:37]
	v_mfma_f32_16x16x32_bf16 v[20:23], v[196:199], v[228:231], v[20:23]
	v_mfma_f32_16x16x32_bf16 v[16:19], v[204:207], v[228:231], v[16:19]
	v_mfma_f32_16x16x32_bf16 v[4:7], v[196:199], v[236:239], v[4:7]
	v_mfma_f32_16x16x32_bf16 v[0:3], v[204:207], v[236:239], v[0:3]
	v_mfma_f32_16x16x32_bf16 v[54:57], v[200:203], v[216:219], v[54:57]
	v_mfma_f32_16x16x32_bf16 v[50:53], v[208:211], v[216:219], v[50:53]
	v_mfma_f32_16x16x32_bf16 v[38:41], v[200:203], v[224:227], v[38:41]
	v_mfma_f32_16x16x32_bf16 v[34:37], v[208:211], v[224:227], v[34:37]
	v_mfma_f32_16x16x32_bf16 v[20:23], v[200:203], v[232:235], v[20:23]
	v_mfma_f32_16x16x32_bf16 v[16:19], v[208:211], v[232:235], v[16:19]
	v_mfma_f32_16x16x32_bf16 v[4:7], v[200:203], v[240:243], v[4:7]
	v_mfma_f32_16x16x32_bf16 v[0:3], v[208:211], v[240:243], v[0:3]
	s_barrier
	s_add_i32 s81, s81, 2
	s_add_u32 s79, s79, 0x100
	s_addc_u32 s80, s80, 0
	s_add_u32 s46, s46, 0x100
	s_addc_u32 s47, s47, 0
	s_cmp_gt_u32 s81, 13
	s_cbranch_scc0 .LBB0_580
	s_and_b64 vcc, exec, s[4:5]
	s_cbranch_vccz .LBB0_583
	s_barrier
